# merge-GEMM epilogues: touch loads for the later gate-row batches issued with the first batch (L2 warm-up), no change to the computation
# baseline (speedup 1.0000x reference)
; #define MG_LOAD(B, S) do { _Pragma("unroll") for (int mm = 0; mm < 2; ++mm) _Pragma("unroll") for (int bj = 0; bj < 2; ++bj) { \
;             const size_t o = (size_t)(((B) >> 1) * HALF + (((B) & 1) * 2 + mm) * 16) * IN_DIM + bj * HALF; \
;             gn[S][mm][bj] = *(const u32x4*)(zn + o); gd[S][mm][bj] = *(const u32x4*)(zd + o); } } while (0)
;     __device__ __forceinline__ void operator()(f32x4 (&acc)[2][2][4][2], const Unit& u, int wr, int wc, int fr, int fq) const {
;         const bool indep = u.ks >= 0;
;         if (u.seg == 2 && !indep) return;
;         const int row0 = u.pm * BM + wr * 64 + fr, col0 = u.pn * BM + wc * 32 + 8 * fq;
;         const bool plain = indep || u.seg == 3;
;         const int sn = plain ? (u.seg < 2 ? u.seg : 2) : u.seg, sd = plain ? sn : u.seg + 1;
;         const float dmask = plain ? 0.f : 1.f;
;         const bf16_t* zn = Z + (size_t)row0 * IN_DIM + OFF_GATE + sn * DM + col0;
;         const bf16_t* zd = Z + (size_t)row0 * IN_DIM + OFF_GATE + sd * DM + col0;
;     ...
;         u32x4 gn[2][2][2], gd[2][2][2];
;     ...
;         MG_LOAD(0, 0); MG_LOAD(1, 1); __builtin_amdgcn_sched_barrier(0);
.LBB0_544:
	s_cmp_gt_i32 s44, -1
	s_cselect_b64 s[46:47], -1, 0
	s_cmp_lt_i32 s44, 0
	s_cselect_b64 s[48:49], -1, 0
	s_cmp_eq_u32 s26, 2
	s_cselect_b64 s[44:45], -1, 0
	s_and_b64 s[44:45], s[48:49], s[44:45]
	s_and_b64 vcc, exec, s[44:45]
	s_cbranch_vccnz .LBB0_551
	s_cmp_eq_u32 s26, 3
	v_lshl_or_b32 v206, s50, 8, v221
	s_cselect_b64 s[50:51], -1, 0
	s_min_i32 s23, s26, 2
	s_or_b64 s[44:45], s[46:47], s[50:51]
	v_lshl_add_u32 v208, s52, 8, v219
	s_and_b64 s[52:53], s[44:45], exec
	s_cselect_b32 s25, s23, s26
	s_add_i32 s27, s26, 1
	v_mov_b64_e32 v[128:129], s[6:7]
	v_cndmask_b32_e64 v210, 1.0, 0, s[44:45]
	s_and_b64 s[44:45], s[44:45], exec
	v_mad_i64_i32 v[128:129], s[44:45], v208, s74, v[128:129]
	s_cselect_b32 s23, s23, s27
	s_lshl_b32 s44, s25, 11
	v_lshl_add_u64 v[128:129], v[128:129], 0, s[18:19]
	s_ashr_i32 s45, s44, 31
	v_lshl_add_u64 v[130:131], s[44:45], 1, v[128:129]
	v_ashrrev_i32_e32 v207, 31, v206
	s_lshl_b32 s44, s23, 11
	v_lshlrev_b64 v[132:133], 1, v[206:207]
	s_ashr_i32 s45, s44, 31
	v_lshl_add_u64 v[214:215], v[130:131], 0, v[132:133]
	v_lshl_add_u64 v[128:129], s[44:45], 1, v[128:129]
	v_lshl_add_u64 v[212:213], v[128:129], 0, v[132:133]
	v_add_co_u32_e32 v128, vcc, s75, v214
	v_mov_b32_e32 v240, 0x380000
	v_mov_b32_e32 v241, 0
	v_lshl_add_u64 v[242:243], v[214:215], 0, v[240:241]
	global_load_dword v244, v[242:243], off
	global_load_dwordx4 v[176:179], v[214:215], off
	v_lshl_add_u64 v[242:243], v[214:215], 0, v[240:241]
	global_load_dword v244, v[242:243], off offset:256
	global_load_dwordx4 v[164:167], v[214:215], off offset:256
	v_lshl_add_u64 v[242:243], v[212:213], 0, v[240:241]
	global_load_dword v244, v[242:243], off
	global_load_dwordx4 v[180:183], v[212:213], off
	v_lshl_add_u64 v[242:243], v[212:213], 0, v[240:241]
	global_load_dword v244, v[242:243], off offset:256
	global_load_dwordx4 v[160:163], v[212:213], off offset:256
	v_addc_co_u32_e32 v129, vcc, 0, v215, vcc
	v_add_co_u32_e32 v130, vcc, s75, v212
	v_ashrrev_i32_e32 v209, 31, v208
	s_nop 0
	v_addc_co_u32_e32 v131, vcc, 0, v213, vcc
	v_lshl_add_u64 v[242:243], v[128:129], 0, v[240:241]
	global_load_dword v244, v[242:243], off
	global_load_dwordx4 v[156:159], v[128:129], off
	v_lshl_add_u64 v[242:243], v[128:129], 0, v[240:241]
	global_load_dword v244, v[242:243], off offset:256
	global_load_dwordx4 v[140:143], v[128:129], off offset:256
	v_lshl_add_u64 v[242:243], v[130:131], 0, v[240:241]
	global_load_dword v244, v[242:243], off
	global_load_dwordx4 v[148:151], v[130:131], off
	v_lshl_add_u64 v[242:243], v[130:131], 0, v[240:241]
	global_load_dword v244, v[242:243], off offset:256
	global_load_dwordx4 v[136:139], v[130:131], off offset:256
	v_add_co_u32_e32 v128, vcc, s76, v214
	s_nop 1
	v_addc_co_u32_e32 v129, vcc, 0, v215, vcc
	v_add_co_u32_e32 v130, vcc, s76, v212
	s_nop 1
	v_addc_co_u32_e32 v131, vcc, 0, v213, vcc
	v_lshl_add_u64 v[242:243], v[128:129], 0, v[240:241]
	global_load_dword v244, v[242:243], off
	global_load_dwordx4 v[188:191], v[128:129], off
	v_lshl_add_u64 v[242:243], v[128:129], 0, v[240:241]
	global_load_dword v244, v[242:243], off offset:256
	global_load_dwordx4 v[172:175], v[128:129], off offset:256
	v_lshl_add_u64 v[242:243], v[130:131], 0, v[240:241]
	global_load_dword v244, v[242:243], off
	global_load_dwordx4 v[184:187], v[130:131], off
	v_lshl_add_u64 v[242:243], v[130:131], 0, v[240:241]
	global_load_dword v244, v[242:243], off offset:256
	global_load_dwordx4 v[168:171], v[130:131], off offset:256
	v_add_co_u32_e32 v128, vcc, s77, v214
	s_nop 1
	v_addc_co_u32_e32 v129, vcc, 0, v215, vcc
	v_add_co_u32_e32 v130, vcc, s77, v212
	s_nop 1
	v_addc_co_u32_e32 v131, vcc, 0, v213, vcc
	v_lshl_add_u64 v[242:243], v[128:129], 0, v[240:241]
	global_load_dword v244, v[242:243], off
	global_load_dwordx4 v[152:155], v[128:129], off
	v_lshl_add_u64 v[242:243], v[128:129], 0, v[240:241]
	global_load_dword v244, v[242:243], off offset:256
	global_load_dwordx4 v[132:135], v[128:129], off offset:256
	v_lshl_add_u64 v[242:243], v[130:131], 0, v[240:241]
	global_load_dword v244, v[242:243], off
	global_load_dwordx4 v[144:147], v[130:131], off
	s_nop 0
	v_lshl_add_u64 v[242:243], v[130:131], 0, v[240:241]
	global_load_dword v244, v[242:243], off offset:256
	global_load_dwordx4 v[128:131], v[130:131], off offset:256
	s_waitcnt vmcnt(0)
; #define MG_LOAD(B, S) do { _Pragma("unroll") for (int mm = 0; mm < 2; ++mm) _Pragma("unroll") for (int bj = 0; bj < 2; ++bj) { \
;             const size_t o = (size_t)(((B) >> 1) * HALF + (((B) & 1) * 2 + mm) * 16) * IN_DIM + bj * HALF; \
;             gn[S][mm][bj] = *(const u32x4*)(zn + o); gd[S][mm][bj] = *(const u32x4*)(zd + o); } } while (0)
;     __device__ __forceinline__ void operator()(f32x4 (&acc)[2][2][4][2], const Unit& u, int wr, int wc, int fr, int fq) const {
;     ...
;         u32x4 gn[2][2][2], gd[2][2][2];
;     ...
;         MG_LOAD(0, 0); MG_LOAD(1, 1); __builtin_amdgcn_sched_barrier(0);
;         MG_APPLY(0, 0); __builtin_amdgcn_sched_barrier(0);
	v_lshlrev_b32_e32 v223, 16, v176
	v_and_b32_e32 v176, 0xffff0000, v176
	v_mul_f32_e32 v176, 0xbfb8aa3b, v176
	v_exp_f32_e32 v176, v176
	v_mul_f32_e32 v223, 0xbfb8aa3b, v223
	v_exp_f32_e32 v223, v223
	v_lshlrev_b32_e32 v224, 16, v180
	v_add_f32_e32 v176, 1.0, v176
	v_and_b32_e32 v180, 0xffff0000, v180
	v_rcp_f32_e32 v227, v176
	v_lshlrev_b32_e32 v176, 16, v177
	v_and_b32_e32 v177, 0xffff0000, v177
	v_add_f32_e32 v223, 1.0, v223
	v_mul_f32_e32 v180, 0xbfb8aa3b, v180
	v_mul_f32_e32 v176, 0xbfb8aa3b, v176
	v_mul_f32_e32 v177, 0xbfb8aa3b, v177
	v_exp_f32_e32 v225, v180
	v_rcp_f32_e32 v226, v223
	v_exp_f32_e32 v180, v176
	v_exp_f32_e32 v223, v177
	v_lshlrev_b32_e32 v176, 16, v181
	v_and_b32_e32 v177, 0xffff0000, v181
	v_mul_f32_e32 v176, 0xbfb8aa3b, v176
	v_mul_f32_e32 v177, 0xbfb8aa3b, v177
	v_exp_f32_e32 v176, v176
	v_add_f32_e32 v180, 1.0, v180
	v_exp_f32_e32 v177, v177
	v_add_f32_e32 v181, 1.0, v223
	v_rcp_f32_e32 v180, v180
	v_rcp_f32_e32 v181, v181
	v_pk_fma_f32 v[176:177], v[210:211], v[176:177], 1.0 op_sel_hi:[0,1,0]
	v_mul_f32_e32 v224, 0xbfb8aa3b, v224
	v_exp_f32_e32 v224, v224
	v_pk_mul_f32 v[176:177], v[180:181], v[176:177]
	v_pk_fma_f32 v[224:225], v[210:211], v[224:225], 1.0 op_sel_hi:[0,1,0]
	v_pk_mul_f32 v[126:127], v[126:127], v[176:177]
	v_lshlrev_b32_e32 v176, 16, v178
	v_and_b32_e32 v178, 0xffff0000, v178
	v_mul_f32_e32 v178, 0xbfb8aa3b, v178
	v_exp_f32_e32 v178, v178
	v_mul_f32_e32 v176, 0xbfb8aa3b, v176
	v_exp_f32_e32 v177, v176
	v_lshlrev_b32_e32 v176, 16, v182
	v_add_f32_e32 v178, 1.0, v178
	v_rcp_f32_e32 v181, v178
	v_lshlrev_b32_e32 v178, 16, v179
	v_and_b32_e32 v179, 0xffff0000, v179
	v_mul_f32_e32 v178, 0xbfb8aa3b, v178
	v_mul_f32_e32 v179, 0xbfb8aa3b, v179
	v_add_f32_e32 v180, 1.0, v177
	v_and_b32_e32 v177, 0xffff0000, v182
	v_exp_f32_e32 v182, v178
	v_exp_f32_e32 v223, v179
	v_mul_f32_e32 v176, 0xbfb8aa3b, v176
	v_mul_f32_e32 v177, 0xbfb8aa3b, v177
	v_exp_f32_e32 v176, v176
	v_exp_f32_e32 v177, v177
	v_lshlrev_b32_e32 v178, 16, v183
	v_and_b32_e32 v179, 0xffff0000, v183
	v_rcp_f32_e32 v180, v180
	v_mul_f32_e32 v178, 0xbfb8aa3b, v178
	v_mul_f32_e32 v179, 0xbfb8aa3b, v179
	v_exp_f32_e32 v178, v178
	v_add_f32_e32 v182, 1.0, v182
	v_exp_f32_e32 v179, v179
	v_add_f32_e32 v183, 1.0, v223
	v_rcp_f32_e32 v182, v182
	v_rcp_f32_e32 v183, v183
	v_pk_fma_f32 v[176:177], v[210:211], v[176:177], 1.0 op_sel_hi:[0,1,0]
	v_pk_mul_f32 v[176:177], v[180:181], v[176:177]
	v_pk_mul_f32 v[224:225], v[226:227], v[224:225]
	v_pk_mul_f32 v[120:121], v[120:121], v[176:177]
	v_pk_fma_f32 v[176:177], v[210:211], v[178:179], 1.0 op_sel_hi:[0,1,0]
	v_pk_mul_f32 v[176:177], v[182:183], v[176:177]
	v_pk_mul_f32 v[124:125], v[124:125], v[224:225]
	v_pk_mul_f32 v[122:123], v[122:123], v[176:177]
	v_lshlrev_b32_e32 v176, 16, v164
	v_and_b32_e32 v164, 0xffff0000, v164
	v_mul_f32_e32 v176, 0xbfb8aa3b, v176
	v_mul_f32_e32 v164, 0xbfb8aa3b, v164
	v_exp_f32_e32 v177, v176
	v_exp_f32_e32 v164, v164
	v_lshlrev_b32_e32 v176, 16, v160
	v_and_b32_e32 v160, 0xffff0000, v160
	v_mul_f32_e32 v160, 0xbfb8aa3b, v160
	v_add_f32_e32 v178, 1.0, v177
	v_exp_f32_e32 v177, v160
	v_add_f32_e32 v160, 1.0, v164
	v_rcp_f32_e32 v179, v160
	v_lshlrev_b32_e32 v160, 16, v165
	v_and_b32_e32 v165, 0xffff0000, v165
	v_mul_f32_e32 v160, 0xbfb8aa3b, v160
	v_mul_f32_e32 v165, 0xbfb8aa3b, v165
	v_exp_f32_e32 v164, v160
	v_exp_f32_e32 v165, v165
	v_lshlrev_b32_e32 v160, 16, v161
	v_and_b32_e32 v161, 0xffff0000, v161
	v_mul_f32_e32 v160, 0xbfb8aa3b, v160
	v_mul_f32_e32 v161, 0xbfb8aa3b, v161
	v_exp_f32_e32 v160, v160
	v_add_f32_e32 v164, 1.0, v164
	v_exp_f32_e32 v161, v161
	v_add_f32_e32 v165, 1.0, v165
	v_rcp_f32_e32 v164, v164
	v_rcp_f32_e32 v165, v165
	v_pk_fma_f32 v[160:161], v[210:211], v[160:161], 1.0 op_sel_hi:[0,1,0]
	v_mul_f32_e32 v176, 0xbfb8aa3b, v176
	v_exp_f32_e32 v176, v176
	v_pk_mul_f32 v[160:161], v[164:165], v[160:161]
	v_rcp_f32_e32 v178, v178
	v_pk_mul_f32 v[94:95], v[94:95], v[160:161]
	v_lshlrev_b32_e32 v160, 16, v166
	v_mul_f32_e32 v160, 0xbfb8aa3b, v160
	v_exp_f32_e32 v161, v160
	v_lshlrev_b32_e32 v160, 16, v162
	v_mul_f32_e32 v160, 0xbfb8aa3b, v160
	v_exp_f32_e32 v160, v160
	v_add_f32_e32 v164, 1.0, v161
	v_and_b32_e32 v161, 0xffff0000, v162
	v_and_b32_e32 v162, 0xffff0000, v166
	v_mul_f32_e32 v162, 0xbfb8aa3b, v162
	v_exp_f32_e32 v162, v162
	v_mul_f32_e32 v161, 0xbfb8aa3b, v161
	v_exp_f32_e32 v161, v161
	v_rcp_f32_e32 v164, v164
	v_add_f32_e32 v162, 1.0, v162
	v_rcp_f32_e32 v165, v162
	v_lshlrev_b32_e32 v162, 16, v167
	v_and_b32_e32 v167, 0xffff0000, v167
	v_mul_f32_e32 v162, 0xbfb8aa3b, v162
	v_mul_f32_e32 v167, 0xbfb8aa3b, v167
	v_exp_f32_e32 v166, v162
	v_exp_f32_e32 v167, v167
	v_lshlrev_b32_e32 v162, 16, v163
	v_and_b32_e32 v163, 0xffff0000, v163
	v_mul_f32_e32 v162, 0xbfb8aa3b, v162
	v_mul_f32_e32 v163, 0xbfb8aa3b, v163
	v_exp_f32_e32 v162, v162
	v_add_f32_e32 v166, 1.0, v166
	v_exp_f32_e32 v163, v163
	v_add_f32_e32 v167, 1.0, v167
	v_rcp_f32_e32 v166, v166
	v_rcp_f32_e32 v167, v167
	v_pk_fma_f32 v[160:161], v[210:211], v[160:161], 1.0 op_sel_hi:[0,1,0]
	v_pk_mul_f32 v[160:161], v[164:165], v[160:161]
	v_pk_fma_f32 v[176:177], v[210:211], v[176:177], 1.0 op_sel_hi:[0,1,0]
	v_pk_mul_f32 v[88:89], v[88:89], v[160:161]
	v_pk_fma_f32 v[160:161], v[210:211], v[162:163], 1.0 op_sel_hi:[0,1,0]
	v_pk_mul_f32 v[160:161], v[166:167], v[160:161]
	v_pk_mul_f32 v[176:177], v[178:179], v[176:177]
	v_pk_mul_f32 v[90:91], v[90:91], v[160:161]
	v_lshlrev_b32_e32 v160, 16, v156
	v_and_b32_e32 v156, 0xffff0000, v156
	v_mul_f32_e32 v160, 0xbfb8aa3b, v160
	v_mul_f32_e32 v156, 0xbfb8aa3b, v156
	v_exp_f32_e32 v161, v160
	v_exp_f32_e32 v156, v156
	v_lshlrev_b32_e32 v160, 16, v148
; #define MG_LOAD(B, S) do { _Pragma("unroll") for (int mm = 0; mm < 2; ++mm) _Pragma("unroll") for (int bj = 0; bj < 2; ++bj) { \
;             const size_t o = (size_t)(((B) >> 1) * HALF + (((B) & 1) * 2 + mm) * 16) * IN_DIM + bj * HALF; \
;             gn[S][mm][bj] = *(const u32x4*)(zn + o); gd[S][mm][bj] = *(const u32x4*)(zd + o); } } while (0)
;     __device__ __forceinline__ void operator()(f32x4 (&acc)[2][2][4][2], const Unit& u, int wr, int wc, int fr, int fq) const {
;     ...
;         MG_LOAD(0, 0); MG_LOAD(1, 1); __builtin_amdgcn_sched_barrier(0);
;         MG_APPLY(0, 0); __builtin_amdgcn_sched_barrier(0);
;         MG_LOAD(2, 0); __builtin_amdgcn_sched_barrier(0);
	v_and_b32_e32 v148, 0xffff0000, v148
	v_mul_f32_e32 v148, 0xbfb8aa3b, v148
	v_add_f32_e32 v162, 1.0, v161
	v_exp_f32_e32 v161, v148
	v_add_f32_e32 v148, 1.0, v156
	v_rcp_f32_e32 v163, v148
	v_lshlrev_b32_e32 v148, 16, v157
	v_and_b32_e32 v157, 0xffff0000, v157
	v_mul_f32_e32 v148, 0xbfb8aa3b, v148
	v_mul_f32_e32 v157, 0xbfb8aa3b, v157
	v_exp_f32_e32 v156, v148
	v_exp_f32_e32 v157, v157
	v_lshlrev_b32_e32 v148, 16, v149
	v_and_b32_e32 v149, 0xffff0000, v149
	v_mul_f32_e32 v148, 0xbfb8aa3b, v148
	v_mul_f32_e32 v149, 0xbfb8aa3b, v149
	v_exp_f32_e32 v148, v148
	v_add_f32_e32 v156, 1.0, v156
	v_exp_f32_e32 v149, v149
	v_add_f32_e32 v157, 1.0, v157
	v_rcp_f32_e32 v156, v156
	v_rcp_f32_e32 v157, v157
	v_pk_fma_f32 v[148:149], v[210:211], v[148:149], 1.0 op_sel_hi:[0,1,0]
	v_mul_f32_e32 v160, 0xbfb8aa3b, v160
	v_exp_f32_e32 v160, v160
	v_pk_mul_f32 v[148:149], v[156:157], v[148:149]
	v_rcp_f32_e32 v162, v162
	v_pk_mul_f32 v[118:119], v[118:119], v[148:149]
	v_lshlrev_b32_e32 v148, 16, v158
	v_mul_f32_e32 v148, 0xbfb8aa3b, v148
	v_exp_f32_e32 v149, v148
	v_lshlrev_b32_e32 v148, 16, v150
	v_mul_f32_e32 v148, 0xbfb8aa3b, v148
	v_exp_f32_e32 v148, v148
	v_add_f32_e32 v156, 1.0, v149
	v_and_b32_e32 v149, 0xffff0000, v150
	v_and_b32_e32 v150, 0xffff0000, v158
	v_mul_f32_e32 v150, 0xbfb8aa3b, v150
	v_exp_f32_e32 v150, v150
	v_mul_f32_e32 v149, 0xbfb8aa3b, v149
	v_exp_f32_e32 v149, v149
	v_rcp_f32_e32 v156, v156
	v_add_f32_e32 v150, 1.0, v150
	v_rcp_f32_e32 v157, v150
	v_lshlrev_b32_e32 v150, 16, v159
	v_and_b32_e32 v159, 0xffff0000, v159
	v_mul_f32_e32 v150, 0xbfb8aa3b, v150
	v_mul_f32_e32 v159, 0xbfb8aa3b, v159
	v_exp_f32_e32 v158, v150
	v_exp_f32_e32 v159, v159
	v_lshlrev_b32_e32 v150, 16, v151
	v_and_b32_e32 v151, 0xffff0000, v151
	v_mul_f32_e32 v150, 0xbfb8aa3b, v150
	v_mul_f32_e32 v151, 0xbfb8aa3b, v151
	v_exp_f32_e32 v150, v150
	v_add_f32_e32 v158, 1.0, v158
	v_exp_f32_e32 v151, v151
	v_add_f32_e32 v159, 1.0, v159
	v_rcp_f32_e32 v158, v158
	v_rcp_f32_e32 v159, v159
	v_pk_fma_f32 v[148:149], v[210:211], v[148:149], 1.0 op_sel_hi:[0,1,0]
	v_pk_mul_f32 v[148:149], v[156:157], v[148:149]
	v_pk_fma_f32 v[160:161], v[210:211], v[160:161], 1.0 op_sel_hi:[0,1,0]
	v_pk_mul_f32 v[112:113], v[112:113], v[148:149]
	v_pk_fma_f32 v[148:149], v[210:211], v[150:151], 1.0 op_sel_hi:[0,1,0]
	v_pk_mul_f32 v[148:149], v[158:159], v[148:149]
	v_pk_mul_f32 v[160:161], v[162:163], v[160:161]
	v_pk_mul_f32 v[114:115], v[114:115], v[148:149]
	v_lshlrev_b32_e32 v148, 16, v140
	v_and_b32_e32 v140, 0xffff0000, v140
	v_mul_f32_e32 v148, 0xbfb8aa3b, v148
	v_mul_f32_e32 v140, 0xbfb8aa3b, v140
	v_exp_f32_e32 v149, v148
	v_exp_f32_e32 v140, v140
	v_lshlrev_b32_e32 v148, 16, v136
	v_and_b32_e32 v136, 0xffff0000, v136
	v_mul_f32_e32 v136, 0xbfb8aa3b, v136
	v_add_f32_e32 v150, 1.0, v149
	v_exp_f32_e32 v149, v136
	v_add_f32_e32 v136, 1.0, v140
	v_rcp_f32_e32 v151, v136
	v_lshlrev_b32_e32 v136, 16, v141
	v_and_b32_e32 v141, 0xffff0000, v141
	v_mul_f32_e32 v136, 0xbfb8aa3b, v136
	v_mul_f32_e32 v141, 0xbfb8aa3b, v141
	v_exp_f32_e32 v140, v136
	v_exp_f32_e32 v141, v141
	v_lshlrev_b32_e32 v136, 16, v137
	v_and_b32_e32 v137, 0xffff0000, v137
	v_mul_f32_e32 v136, 0xbfb8aa3b, v136
	v_mul_f32_e32 v137, 0xbfb8aa3b, v137
	v_exp_f32_e32 v136, v136
	v_add_f32_e32 v140, 1.0, v140
	v_exp_f32_e32 v137, v137
	v_add_f32_e32 v141, 1.0, v141
	v_rcp_f32_e32 v140, v140
	v_rcp_f32_e32 v141, v141
	v_pk_fma_f32 v[136:137], v[210:211], v[136:137], 1.0 op_sel_hi:[0,1,0]
	v_mul_f32_e32 v148, 0xbfb8aa3b, v148
	v_exp_f32_e32 v148, v148
	v_pk_mul_f32 v[136:137], v[140:141], v[136:137]
	v_rcp_f32_e32 v150, v150
	v_pk_mul_f32 v[86:87], v[86:87], v[136:137]
	v_lshlrev_b32_e32 v136, 16, v142
	v_mul_f32_e32 v136, 0xbfb8aa3b, v136
	v_exp_f32_e32 v137, v136
	v_lshlrev_b32_e32 v136, 16, v138
	v_mul_f32_e32 v136, 0xbfb8aa3b, v136
	v_exp_f32_e32 v136, v136
	v_add_f32_e32 v140, 1.0, v137
	v_and_b32_e32 v137, 0xffff0000, v138
	v_and_b32_e32 v138, 0xffff0000, v142
	v_mul_f32_e32 v138, 0xbfb8aa3b, v138
	v_exp_f32_e32 v138, v138
	v_mul_f32_e32 v137, 0xbfb8aa3b, v137
	v_exp_f32_e32 v137, v137
	v_rcp_f32_e32 v140, v140
	v_add_f32_e32 v138, 1.0, v138
	v_rcp_f32_e32 v141, v138
	v_lshlrev_b32_e32 v138, 16, v143
	v_and_b32_e32 v143, 0xffff0000, v143
	v_mul_f32_e32 v138, 0xbfb8aa3b, v138
	v_mul_f32_e32 v143, 0xbfb8aa3b, v143
	v_exp_f32_e32 v142, v138
	v_exp_f32_e32 v143, v143
	v_lshlrev_b32_e32 v138, 16, v139
	v_and_b32_e32 v139, 0xffff0000, v139
	v_mul_f32_e32 v138, 0xbfb8aa3b, v138
	v_mul_f32_e32 v139, 0xbfb8aa3b, v139
	v_exp_f32_e32 v138, v138
	v_add_f32_e32 v142, 1.0, v142
	v_exp_f32_e32 v139, v139
	v_add_f32_e32 v143, 1.0, v143
	v_rcp_f32_e32 v142, v142
	v_rcp_f32_e32 v143, v143
	v_pk_fma_f32 v[136:137], v[210:211], v[136:137], 1.0 op_sel_hi:[0,1,0]
	v_pk_mul_f32 v[136:137], v[140:141], v[136:137]
	v_pk_fma_f32 v[148:149], v[210:211], v[148:149], 1.0 op_sel_hi:[0,1,0]
	v_pk_mul_f32 v[80:81], v[80:81], v[136:137]
	v_pk_fma_f32 v[136:137], v[210:211], v[138:139], 1.0 op_sel_hi:[0,1,0]
	v_pk_mul_f32 v[148:149], v[150:151], v[148:149]
	v_pk_mul_f32 v[136:137], v[142:143], v[136:137]
	v_pk_mul_f32 v[92:93], v[92:93], v[176:177]
	v_pk_mul_f32 v[116:117], v[116:117], v[160:161]
	v_pk_mul_f32 v[84:85], v[84:85], v[148:149]
	v_pk_mul_f32 v[82:83], v[82:83], v[136:137]
	v_add_co_u32_e32 v136, vcc, s78, v214
	s_nop 1
	v_addc_co_u32_e32 v137, vcc, 0, v215, vcc
	v_add_co_u32_e32 v138, vcc, s78, v212
	s_nop 1
	v_addc_co_u32_e32 v139, vcc, 0, v213, vcc
	global_load_dwordx4 v[176:179], v[136:137], off
	global_load_dwordx4 v[164:167], v[136:137], off offset:256
	global_load_dwordx4 v[180:183], v[138:139], off
	global_load_dwordx4 v[160:163], v[138:139], off offset:256
; #define MG_LOAD(B, S) do { _Pragma("unroll") for (int mm = 0; mm < 2; ++mm) _Pragma("unroll") for (int bj = 0; bj < 2; ++bj) { \
;             const size_t o = (size_t)(((B) >> 1) * HALF + (((B) & 1) * 2 + mm) * 16) * IN_DIM + bj * HALF; \
;             gn[S][mm][bj] = *(const u32x4*)(zn + o); gd[S][mm][bj] = *(const u32x4*)(zd + o); } } while (0)
;     __device__ __forceinline__ void operator()(f32x4 (&acc)[2][2][4][2], const Unit& u, int wr, int wc, int fr, int fq) const {
;     ...
;         MG_LOAD(0, 0); MG_LOAD(1, 1); __builtin_amdgcn_sched_barrier(0);
;         MG_APPLY(0, 0); __builtin_amdgcn_sched_barrier(0);
;         MG_LOAD(2, 0); __builtin_amdgcn_sched_barrier(0);
;         MG_APPLY(1, 1); __builtin_amdgcn_sched_barrier(0);
	v_add_co_u32_e32 v136, vcc, s79, v214
	s_nop 1
	v_addc_co_u32_e32 v137, vcc, 0, v215, vcc
	v_add_co_u32_e32 v138, vcc, s79, v212
	s_nop 1
	v_addc_co_u32_e32 v139, vcc, 0, v213, vcc
	global_load_dwordx4 v[148:151], v[136:137], off
	global_load_dwordx4 v[140:143], v[136:137], off offset:256
	global_load_dwordx4 v[156:159], v[138:139], off
	s_nop 0
	global_load_dwordx4 v[136:139], v[138:139], off offset:256
	v_lshlrev_b32_e32 v223, 16, v188
	v_and_b32_e32 v188, 0xffff0000, v188
	v_mul_f32_e32 v188, 0xbfb8aa3b, v188
	v_exp_f32_e32 v188, v188
	v_lshlrev_b32_e32 v224, 16, v184
	v_and_b32_e32 v184, 0xffff0000, v184
	v_mul_f32_e32 v184, 0xbfb8aa3b, v184
	v_exp_f32_e32 v225, v184
	v_add_f32_e32 v184, 1.0, v188
	v_rcp_f32_e32 v227, v184
	v_lshlrev_b32_e32 v184, 16, v189
	v_and_b32_e32 v189, 0xffff0000, v189
	v_mul_f32_e32 v184, 0xbfb8aa3b, v184
	v_mul_f32_e32 v189, 0xbfb8aa3b, v189
	v_exp_f32_e32 v188, v184
	v_exp_f32_e32 v189, v189
	v_lshlrev_b32_e32 v184, 16, v185
	v_and_b32_e32 v185, 0xffff0000, v185
	v_mul_f32_e32 v184, 0xbfb8aa3b, v184
	v_mul_f32_e32 v185, 0xbfb8aa3b, v185
	v_exp_f32_e32 v184, v184
	v_add_f32_e32 v188, 1.0, v188
	v_exp_f32_e32 v185, v185
	v_add_f32_e32 v189, 1.0, v189
	v_rcp_f32_e32 v188, v188
	v_rcp_f32_e32 v189, v189
	v_pk_fma_f32 v[184:185], v[210:211], v[184:185], 1.0 op_sel_hi:[0,1,0]
	v_mul_f32_e32 v223, 0xbfb8aa3b, v223
	v_exp_f32_e32 v223, v223
	v_pk_mul_f32 v[184:185], v[188:189], v[184:185]
	v_mul_f32_e32 v224, 0xbfb8aa3b, v224
	v_pk_mul_f32 v[110:111], v[110:111], v[184:185]
	v_lshlrev_b32_e32 v184, 16, v190
	v_mul_f32_e32 v184, 0xbfb8aa3b, v184
	v_exp_f32_e32 v185, v184
	v_lshlrev_b32_e32 v184, 16, v186
	v_mul_f32_e32 v184, 0xbfb8aa3b, v184
	v_exp_f32_e32 v184, v184
	v_add_f32_e32 v188, 1.0, v185
	v_and_b32_e32 v185, 0xffff0000, v186
	v_and_b32_e32 v186, 0xffff0000, v190
	v_mul_f32_e32 v186, 0xbfb8aa3b, v186
	v_exp_f32_e32 v186, v186
	v_mul_f32_e32 v185, 0xbfb8aa3b, v185
	v_exp_f32_e32 v185, v185
	v_rcp_f32_e32 v188, v188
	v_add_f32_e32 v186, 1.0, v186
	v_rcp_f32_e32 v189, v186
	v_lshlrev_b32_e32 v186, 16, v191
	v_and_b32_e32 v191, 0xffff0000, v191
	v_mul_f32_e32 v186, 0xbfb8aa3b, v186
	v_mul_f32_e32 v191, 0xbfb8aa3b, v191
	v_exp_f32_e32 v190, v186
	v_exp_f32_e32 v191, v191
	v_lshlrev_b32_e32 v186, 16, v187
	v_and_b32_e32 v187, 0xffff0000, v187
	v_mul_f32_e32 v186, 0xbfb8aa3b, v186
	v_mul_f32_e32 v187, 0xbfb8aa3b, v187
	v_exp_f32_e32 v186, v186
	v_add_f32_e32 v190, 1.0, v190
	v_exp_f32_e32 v187, v187
	v_add_f32_e32 v191, 1.0, v191
	v_rcp_f32_e32 v190, v190
	v_rcp_f32_e32 v191, v191
	v_pk_fma_f32 v[184:185], v[210:211], v[184:185], 1.0 op_sel_hi:[0,1,0]
	v_pk_mul_f32 v[184:185], v[188:189], v[184:185]
	v_exp_f32_e32 v224, v224
	v_pk_mul_f32 v[104:105], v[104:105], v[184:185]
	v_pk_fma_f32 v[184:185], v[210:211], v[186:187], 1.0 op_sel_hi:[0,1,0]
	v_pk_mul_f32 v[184:185], v[190:191], v[184:185]
	v_add_f32_e32 v223, 1.0, v223
	v_pk_mul_f32 v[106:107], v[106:107], v[184:185]
	v_lshlrev_b32_e32 v184, 16, v172
	v_and_b32_e32 v172, 0xffff0000, v172
	v_mul_f32_e32 v184, 0xbfb8aa3b, v184
	v_mul_f32_e32 v172, 0xbfb8aa3b, v172
	v_exp_f32_e32 v185, v184
	v_exp_f32_e32 v172, v172
	v_lshlrev_b32_e32 v184, 16, v168
	v_and_b32_e32 v168, 0xffff0000, v168
	v_mul_f32_e32 v168, 0xbfb8aa3b, v168
	v_add_f32_e32 v186, 1.0, v185
	v_exp_f32_e32 v185, v168
	v_add_f32_e32 v168, 1.0, v172
	v_rcp_f32_e32 v187, v168
	v_lshlrev_b32_e32 v168, 16, v173
	v_and_b32_e32 v173, 0xffff0000, v173
	v_mul_f32_e32 v168, 0xbfb8aa3b, v168
	v_mul_f32_e32 v173, 0xbfb8aa3b, v173
	v_exp_f32_e32 v172, v168
	v_exp_f32_e32 v173, v173
	v_lshlrev_b32_e32 v168, 16, v169
	v_and_b32_e32 v169, 0xffff0000, v169
	v_mul_f32_e32 v168, 0xbfb8aa3b, v168
	v_mul_f32_e32 v169, 0xbfb8aa3b, v169
	v_exp_f32_e32 v168, v168
	v_add_f32_e32 v172, 1.0, v172
	v_exp_f32_e32 v169, v169
	v_add_f32_e32 v173, 1.0, v173
	v_rcp_f32_e32 v172, v172
	v_rcp_f32_e32 v173, v173
	v_pk_fma_f32 v[168:169], v[210:211], v[168:169], 1.0 op_sel_hi:[0,1,0]
	v_mul_f32_e32 v184, 0xbfb8aa3b, v184
	v_exp_f32_e32 v184, v184
	v_pk_mul_f32 v[168:169], v[172:173], v[168:169]
	v_rcp_f32_e32 v226, v223
	v_pk_mul_f32 v[78:79], v[78:79], v[168:169]
	v_lshlrev_b32_e32 v168, 16, v174
	v_mul_f32_e32 v168, 0xbfb8aa3b, v168
	v_exp_f32_e32 v169, v168
	v_lshlrev_b32_e32 v168, 16, v170
	v_mul_f32_e32 v168, 0xbfb8aa3b, v168
	v_exp_f32_e32 v168, v168
	v_add_f32_e32 v172, 1.0, v169
	v_and_b32_e32 v169, 0xffff0000, v170
	v_and_b32_e32 v170, 0xffff0000, v174
	v_mul_f32_e32 v170, 0xbfb8aa3b, v170
	v_exp_f32_e32 v170, v170
	v_mul_f32_e32 v169, 0xbfb8aa3b, v169
	v_exp_f32_e32 v169, v169
	v_rcp_f32_e32 v172, v172
	v_add_f32_e32 v170, 1.0, v170
	v_rcp_f32_e32 v173, v170
	v_lshlrev_b32_e32 v170, 16, v175
	v_and_b32_e32 v175, 0xffff0000, v175
	v_mul_f32_e32 v170, 0xbfb8aa3b, v170
	v_mul_f32_e32 v175, 0xbfb8aa3b, v175
	v_exp_f32_e32 v174, v170
	v_exp_f32_e32 v175, v175
	v_lshlrev_b32_e32 v170, 16, v171
	v_and_b32_e32 v171, 0xffff0000, v171
	v_mul_f32_e32 v170, 0xbfb8aa3b, v170
	v_mul_f32_e32 v171, 0xbfb8aa3b, v171
	v_exp_f32_e32 v170, v170
	v_add_f32_e32 v174, 1.0, v174
	v_exp_f32_e32 v171, v171
	v_add_f32_e32 v175, 1.0, v175
	v_rcp_f32_e32 v174, v174
	v_rcp_f32_e32 v175, v175
	v_pk_fma_f32 v[168:169], v[210:211], v[168:169], 1.0 op_sel_hi:[0,1,0]
	v_pk_mul_f32 v[168:169], v[172:173], v[168:169]
	v_rcp_f32_e32 v186, v186
	v_pk_mul_f32 v[72:73], v[72:73], v[168:169]
	v_pk_fma_f32 v[168:169], v[210:211], v[170:171], 1.0 op_sel_hi:[0,1,0]
	v_pk_mul_f32 v[168:169], v[174:175], v[168:169]
	v_pk_fma_f32 v[224:225], v[210:211], v[224:225], 1.0 op_sel_hi:[0,1,0]
	v_pk_mul_f32 v[74:75], v[74:75], v[168:169]
	v_lshlrev_b32_e32 v168, 16, v152
; #define MG_LOAD(B, S) do { _Pragma("unroll") for (int mm = 0; mm < 2; ++mm) _Pragma("unroll") for (int bj = 0; bj < 2; ++bj) { \
;             const size_t o = (size_t)(((B) >> 1) * HALF + (((B) & 1) * 2 + mm) * 16) * IN_DIM + bj * HALF; \
;             gn[S][mm][bj] = *(const u32x4*)(zn + o); gd[S][mm][bj] = *(const u32x4*)(zd + o); } } while (0)
;     __device__ __forceinline__ void operator()(f32x4 (&acc)[2][2][4][2], const Unit& u, int wr, int wc, int fr, int fq) const {
;     ...
;         MG_LOAD(0, 0); MG_LOAD(1, 1); __builtin_amdgcn_sched_barrier(0);
;         MG_APPLY(0, 0); __builtin_amdgcn_sched_barrier(0);
;         MG_LOAD(2, 0); __builtin_amdgcn_sched_barrier(0);
;         MG_APPLY(1, 1); __builtin_amdgcn_sched_barrier(0);
;         MG_LOAD(3, 1); __builtin_amdgcn_sched_barrier(0);
	v_and_b32_e32 v152, 0xffff0000, v152
	v_mul_f32_e32 v168, 0xbfb8aa3b, v168
	v_mul_f32_e32 v152, 0xbfb8aa3b, v152
	v_exp_f32_e32 v169, v168
	v_exp_f32_e32 v152, v152
	v_lshlrev_b32_e32 v168, 16, v144
	v_and_b32_e32 v144, 0xffff0000, v144
	v_mul_f32_e32 v144, 0xbfb8aa3b, v144
	v_add_f32_e32 v170, 1.0, v169
	v_exp_f32_e32 v169, v144
	v_add_f32_e32 v144, 1.0, v152
	v_rcp_f32_e32 v171, v144
	v_lshlrev_b32_e32 v144, 16, v153
	v_and_b32_e32 v153, 0xffff0000, v153
	v_mul_f32_e32 v144, 0xbfb8aa3b, v144
	v_mul_f32_e32 v153, 0xbfb8aa3b, v153
	v_exp_f32_e32 v152, v144
	v_exp_f32_e32 v153, v153
	v_lshlrev_b32_e32 v144, 16, v145
	v_and_b32_e32 v145, 0xffff0000, v145
	v_mul_f32_e32 v144, 0xbfb8aa3b, v144
	v_mul_f32_e32 v145, 0xbfb8aa3b, v145
	v_exp_f32_e32 v144, v144
	v_add_f32_e32 v152, 1.0, v152
	v_exp_f32_e32 v145, v145
	v_add_f32_e32 v153, 1.0, v153
	v_rcp_f32_e32 v152, v152
	v_rcp_f32_e32 v153, v153
	v_pk_fma_f32 v[144:145], v[210:211], v[144:145], 1.0 op_sel_hi:[0,1,0]
	v_mul_f32_e32 v168, 0xbfb8aa3b, v168
	v_exp_f32_e32 v168, v168
	v_pk_mul_f32 v[144:145], v[152:153], v[144:145]
	v_rcp_f32_e32 v170, v170
	v_pk_mul_f32 v[102:103], v[102:103], v[144:145]
	v_lshlrev_b32_e32 v144, 16, v154
	v_mul_f32_e32 v144, 0xbfb8aa3b, v144
	v_exp_f32_e32 v145, v144
	v_lshlrev_b32_e32 v144, 16, v146
	v_mul_f32_e32 v144, 0xbfb8aa3b, v144
	v_exp_f32_e32 v144, v144
	v_add_f32_e32 v152, 1.0, v145
	v_and_b32_e32 v145, 0xffff0000, v146
	v_and_b32_e32 v146, 0xffff0000, v154
	v_mul_f32_e32 v146, 0xbfb8aa3b, v146
	v_exp_f32_e32 v146, v146
	v_mul_f32_e32 v145, 0xbfb8aa3b, v145
	v_exp_f32_e32 v145, v145
	v_rcp_f32_e32 v152, v152
	v_add_f32_e32 v146, 1.0, v146
	v_rcp_f32_e32 v153, v146
	v_lshlrev_b32_e32 v146, 16, v155
	v_and_b32_e32 v155, 0xffff0000, v155
	v_mul_f32_e32 v146, 0xbfb8aa3b, v146
	v_mul_f32_e32 v155, 0xbfb8aa3b, v155
	v_exp_f32_e32 v154, v146
	v_exp_f32_e32 v155, v155
	v_lshlrev_b32_e32 v146, 16, v147
	v_and_b32_e32 v147, 0xffff0000, v147
	v_mul_f32_e32 v146, 0xbfb8aa3b, v146
	v_mul_f32_e32 v147, 0xbfb8aa3b, v147
	v_exp_f32_e32 v146, v146
	v_add_f32_e32 v154, 1.0, v154
	v_exp_f32_e32 v147, v147
	v_add_f32_e32 v155, 1.0, v155
	v_rcp_f32_e32 v154, v154
	v_rcp_f32_e32 v155, v155
	v_pk_fma_f32 v[144:145], v[210:211], v[144:145], 1.0 op_sel_hi:[0,1,0]
	v_pk_mul_f32 v[144:145], v[152:153], v[144:145]
	v_pk_fma_f32 v[184:185], v[210:211], v[184:185], 1.0 op_sel_hi:[0,1,0]
	v_pk_mul_f32 v[96:97], v[96:97], v[144:145]
	v_pk_fma_f32 v[144:145], v[210:211], v[146:147], 1.0 op_sel_hi:[0,1,0]
	v_pk_mul_f32 v[144:145], v[154:155], v[144:145]
	v_pk_fma_f32 v[168:169], v[210:211], v[168:169], 1.0 op_sel_hi:[0,1,0]
	v_pk_mul_f32 v[98:99], v[98:99], v[144:145]
	v_lshlrev_b32_e32 v144, 16, v132
	v_and_b32_e32 v132, 0xffff0000, v132
	v_mul_f32_e32 v144, 0xbfb8aa3b, v144
	v_mul_f32_e32 v132, 0xbfb8aa3b, v132
	v_exp_f32_e32 v145, v144
	v_exp_f32_e32 v132, v132
	v_lshlrev_b32_e32 v144, 16, v128
	v_and_b32_e32 v128, 0xffff0000, v128
	v_mul_f32_e32 v128, 0xbfb8aa3b, v128
	v_add_f32_e32 v146, 1.0, v145
	v_exp_f32_e32 v145, v128
	v_add_f32_e32 v128, 1.0, v132
	v_rcp_f32_e32 v147, v128
	v_lshlrev_b32_e32 v128, 16, v133
	v_and_b32_e32 v133, 0xffff0000, v133
	v_mul_f32_e32 v128, 0xbfb8aa3b, v128
	v_mul_f32_e32 v133, 0xbfb8aa3b, v133
	v_exp_f32_e32 v132, v128
	v_exp_f32_e32 v133, v133
	v_lshlrev_b32_e32 v128, 16, v129
	v_and_b32_e32 v129, 0xffff0000, v129
	v_mul_f32_e32 v128, 0xbfb8aa3b, v128
	v_mul_f32_e32 v129, 0xbfb8aa3b, v129
	v_exp_f32_e32 v128, v128
	v_add_f32_e32 v132, 1.0, v132
	v_exp_f32_e32 v129, v129
	v_add_f32_e32 v133, 1.0, v133
	v_rcp_f32_e32 v132, v132
	v_rcp_f32_e32 v133, v133
	v_pk_fma_f32 v[128:129], v[210:211], v[128:129], 1.0 op_sel_hi:[0,1,0]
	v_mul_f32_e32 v144, 0xbfb8aa3b, v144
	v_exp_f32_e32 v144, v144
	v_pk_mul_f32 v[128:129], v[132:133], v[128:129]
	v_rcp_f32_e32 v146, v146
	v_pk_mul_f32 v[70:71], v[70:71], v[128:129]
	v_lshlrev_b32_e32 v128, 16, v134
	v_mul_f32_e32 v128, 0xbfb8aa3b, v128
	v_exp_f32_e32 v129, v128
	v_lshlrev_b32_e32 v128, 16, v130
	v_mul_f32_e32 v128, 0xbfb8aa3b, v128
	v_exp_f32_e32 v128, v128
	v_add_f32_e32 v132, 1.0, v129
	v_and_b32_e32 v129, 0xffff0000, v130
	v_and_b32_e32 v130, 0xffff0000, v134
	v_mul_f32_e32 v130, 0xbfb8aa3b, v130
	v_exp_f32_e32 v130, v130
	v_mul_f32_e32 v129, 0xbfb8aa3b, v129
	v_exp_f32_e32 v129, v129
	v_rcp_f32_e32 v132, v132
	v_add_f32_e32 v130, 1.0, v130
	v_rcp_f32_e32 v133, v130
	v_lshlrev_b32_e32 v130, 16, v135
	v_and_b32_e32 v135, 0xffff0000, v135
	v_mul_f32_e32 v130, 0xbfb8aa3b, v130
	v_mul_f32_e32 v135, 0xbfb8aa3b, v135
	v_exp_f32_e32 v134, v130
	v_exp_f32_e32 v135, v135
	v_lshlrev_b32_e32 v130, 16, v131
	v_and_b32_e32 v131, 0xffff0000, v131
	v_mul_f32_e32 v130, 0xbfb8aa3b, v130
	v_mul_f32_e32 v131, 0xbfb8aa3b, v131
	v_exp_f32_e32 v130, v130
	v_add_f32_e32 v134, 1.0, v134
	v_exp_f32_e32 v131, v131
	v_add_f32_e32 v135, 1.0, v135
	v_rcp_f32_e32 v134, v134
	v_rcp_f32_e32 v135, v135
	v_pk_fma_f32 v[128:129], v[210:211], v[128:129], 1.0 op_sel_hi:[0,1,0]
	v_pk_mul_f32 v[128:129], v[132:133], v[128:129]
	v_pk_fma_f32 v[144:145], v[210:211], v[144:145], 1.0 op_sel_hi:[0,1,0]
	v_pk_mul_f32 v[64:65], v[64:65], v[128:129]
	v_pk_fma_f32 v[128:129], v[210:211], v[130:131], 1.0 op_sel_hi:[0,1,0]
	v_pk_mul_f32 v[224:225], v[226:227], v[224:225]
	v_pk_mul_f32 v[184:185], v[186:187], v[184:185]
	v_pk_mul_f32 v[168:169], v[170:171], v[168:169]
	v_pk_mul_f32 v[144:145], v[146:147], v[144:145]
	v_pk_mul_f32 v[128:129], v[134:135], v[128:129]
	v_pk_mul_f32 v[108:109], v[108:109], v[224:225]
	v_pk_mul_f32 v[76:77], v[76:77], v[184:185]
	v_pk_mul_f32 v[100:101], v[100:101], v[168:169]
	v_pk_mul_f32 v[68:69], v[68:69], v[144:145]
	v_pk_mul_f32 v[66:67], v[66:67], v[128:129]
	v_add_co_u32_e32 v128, vcc, s80, v214
	s_nop 1
	v_addc_co_u32_e32 v129, vcc, 0, v215, vcc
	v_add_co_u32_e32 v130, vcc, s80, v212
	s_nop 1
	v_addc_co_u32_e32 v131, vcc, 0, v213, vcc
	global_load_dwordx4 v[184:187], v[128:129], off
	global_load_dwordx4 v[172:175], v[128:129], off offset:256
	global_load_dwordx4 v[188:191], v[130:131], off
	global_load_dwordx4 v[168:171], v[130:131], off offset:256
	v_add_co_u32_e32 v128, vcc, s81, v214
	s_nop 1
	v_addc_co_u32_e32 v129, vcc, 0, v215, vcc
	v_add_co_u32_e32 v130, vcc, s81, v212
	s_nop 1
	v_addc_co_u32_e32 v131, vcc, 0, v213, vcc
	global_load_dwordx4 v[144:147], v[128:129], off
	global_load_dwordx4 v[132:135], v[128:129], off offset:256
	global_load_dwordx4 v[152:155], v[130:131], off
	s_nop 0
	global_load_dwordx4 v[128:131], v[130:131], off offset:256
	s_waitcnt vmcnt(15)
; #define MG_LOAD(B, S) do { _Pragma("unroll") for (int mm = 0; mm < 2; ++mm) _Pragma("unroll") for (int bj = 0; bj < 2; ++bj) { \
;             const size_t o = (size_t)(((B) >> 1) * HALF + (((B) & 1) * 2 + mm) * 16) * IN_DIM + bj * HALF; \
;             gn[S][mm][bj] = *(const u32x4*)(zn + o); gd[S][mm][bj] = *(const u32x4*)(zd + o); } } while (0)
;     __device__ __forceinline__ void operator()(f32x4 (&acc)[2][2][4][2], const Unit& u, int wr, int wc, int fr, int fq) const {
;     ...
;         MG_LOAD(0, 0); MG_LOAD(1, 1); __builtin_amdgcn_sched_barrier(0);
;         MG_APPLY(0, 0); __builtin_amdgcn_sched_barrier(0);
;         MG_LOAD(2, 0); __builtin_amdgcn_sched_barrier(0);
;         MG_APPLY(1, 1); __builtin_amdgcn_sched_barrier(0);
;         MG_LOAD(3, 1); __builtin_amdgcn_sched_barrier(0);
;         MG_APPLY(2, 0); __builtin_amdgcn_sched_barrier(0);
	v_lshlrev_b32_e32 v212, 16, v176
	v_and_b32_e32 v176, 0xffff0000, v176
	v_mul_f32_e32 v176, 0xbfb8aa3b, v176
	v_exp_f32_e32 v176, v176
	v_mul_f32_e32 v212, 0xbfb8aa3b, v212
	v_exp_f32_e32 v213, v212
	s_waitcnt vmcnt(13)
	v_lshlrev_b32_e32 v212, 16, v180
	v_add_f32_e32 v176, 1.0, v176
	v_and_b32_e32 v180, 0xffff0000, v180
	v_rcp_f32_e32 v215, v176
	v_lshlrev_b32_e32 v176, 16, v177
	v_and_b32_e32 v177, 0xffff0000, v177
	v_mul_f32_e32 v180, 0xbfb8aa3b, v180
	v_mul_f32_e32 v176, 0xbfb8aa3b, v176
	v_mul_f32_e32 v177, 0xbfb8aa3b, v177
	v_add_f32_e32 v214, 1.0, v213
	v_exp_f32_e32 v213, v180
	v_exp_f32_e32 v180, v176
	v_exp_f32_e32 v223, v177
	v_lshlrev_b32_e32 v176, 16, v181
	v_and_b32_e32 v177, 0xffff0000, v181
	v_mul_f32_e32 v176, 0xbfb8aa3b, v176
	v_mul_f32_e32 v177, 0xbfb8aa3b, v177
	v_exp_f32_e32 v176, v176
	v_add_f32_e32 v180, 1.0, v180
	v_exp_f32_e32 v177, v177
	v_add_f32_e32 v181, 1.0, v223
	v_rcp_f32_e32 v180, v180
	v_rcp_f32_e32 v181, v181
	v_pk_fma_f32 v[176:177], v[210:211], v[176:177], 1.0 op_sel_hi:[0,1,0]
	v_mul_f32_e32 v212, 0xbfb8aa3b, v212
	v_exp_f32_e32 v212, v212
	v_pk_mul_f32 v[176:177], v[180:181], v[176:177]
	v_rcp_f32_e32 v214, v214
	v_pk_mul_f32 v[62:63], v[62:63], v[176:177]
	v_lshlrev_b32_e32 v176, 16, v178
	v_and_b32_e32 v178, 0xffff0000, v178
	v_mul_f32_e32 v178, 0xbfb8aa3b, v178
	v_exp_f32_e32 v178, v178
	v_mul_f32_e32 v176, 0xbfb8aa3b, v176
	v_exp_f32_e32 v177, v176
	v_pk_fma_f32 v[212:213], v[210:211], v[212:213], 1.0 op_sel_hi:[0,1,0]
	v_add_f32_e32 v178, 1.0, v178
	v_rcp_f32_e32 v181, v178
	v_lshlrev_b32_e32 v178, 16, v179
	v_and_b32_e32 v179, 0xffff0000, v179
	v_pk_mul_f32 v[212:213], v[214:215], v[212:213]
	v_mul_f32_e32 v178, 0xbfb8aa3b, v178
	v_mul_f32_e32 v179, 0xbfb8aa3b, v179
	v_pk_mul_f32 v[60:61], v[60:61], v[212:213]
	v_lshlrev_b32_e32 v176, 16, v182
	v_add_f32_e32 v180, 1.0, v177
	v_and_b32_e32 v177, 0xffff0000, v182
	v_exp_f32_e32 v182, v178
	v_exp_f32_e32 v212, v179
	v_mul_f32_e32 v176, 0xbfb8aa3b, v176
	v_mul_f32_e32 v177, 0xbfb8aa3b, v177
	v_exp_f32_e32 v176, v176
	v_exp_f32_e32 v177, v177
	v_lshlrev_b32_e32 v178, 16, v183
	v_and_b32_e32 v179, 0xffff0000, v183
	v_rcp_f32_e32 v180, v180
	v_mul_f32_e32 v178, 0xbfb8aa3b, v178
	v_mul_f32_e32 v179, 0xbfb8aa3b, v179
	v_exp_f32_e32 v178, v178
	v_add_f32_e32 v182, 1.0, v182
	v_exp_f32_e32 v179, v179
	v_add_f32_e32 v183, 1.0, v212
	v_rcp_f32_e32 v182, v182
	v_rcp_f32_e32 v183, v183
	v_pk_fma_f32 v[176:177], v[210:211], v[176:177], 1.0 op_sel_hi:[0,1,0]
	v_pk_mul_f32 v[176:177], v[180:181], v[176:177]
	s_nop 0
	v_pk_mul_f32 v[56:57], v[56:57], v[176:177]
	v_pk_fma_f32 v[176:177], v[210:211], v[178:179], 1.0 op_sel_hi:[0,1,0]
	v_pk_mul_f32 v[176:177], v[182:183], v[176:177]
	s_nop 0
	v_pk_mul_f32 v[58:59], v[58:59], v[176:177]
	v_lshlrev_b32_e32 v176, 16, v164
	v_and_b32_e32 v164, 0xffff0000, v164
	v_mul_f32_e32 v176, 0xbfb8aa3b, v176
	v_mul_f32_e32 v164, 0xbfb8aa3b, v164
	v_exp_f32_e32 v177, v176
	v_exp_f32_e32 v164, v164
	s_waitcnt vmcnt(12)
	v_lshlrev_b32_e32 v176, 16, v160
	v_and_b32_e32 v160, 0xffff0000, v160
	v_mul_f32_e32 v160, 0xbfb8aa3b, v160
	v_add_f32_e32 v178, 1.0, v177
	v_exp_f32_e32 v177, v160
	v_add_f32_e32 v160, 1.0, v164
	v_rcp_f32_e32 v179, v160
	v_lshlrev_b32_e32 v160, 16, v165
	v_and_b32_e32 v165, 0xffff0000, v165
	v_mul_f32_e32 v160, 0xbfb8aa3b, v160
	v_mul_f32_e32 v165, 0xbfb8aa3b, v165
	v_exp_f32_e32 v164, v160
	v_exp_f32_e32 v165, v165
	v_lshlrev_b32_e32 v160, 16, v161
	v_and_b32_e32 v161, 0xffff0000, v161
	v_mul_f32_e32 v160, 0xbfb8aa3b, v160
	v_mul_f32_e32 v161, 0xbfb8aa3b, v161
	v_exp_f32_e32 v160, v160
	v_add_f32_e32 v164, 1.0, v164
	v_exp_f32_e32 v161, v161
	v_add_f32_e32 v165, 1.0, v165
	v_rcp_f32_e32 v164, v164
	v_rcp_f32_e32 v165, v165
	v_pk_fma_f32 v[160:161], v[210:211], v[160:161], 1.0 op_sel_hi:[0,1,0]
	v_mul_f32_e32 v176, 0xbfb8aa3b, v176
	v_exp_f32_e32 v176, v176
	v_pk_mul_f32 v[160:161], v[164:165], v[160:161]
	v_rcp_f32_e32 v178, v178
	v_pk_mul_f32 v[30:31], v[30:31], v[160:161]
	v_lshlrev_b32_e32 v160, 16, v166
	v_mul_f32_e32 v160, 0xbfb8aa3b, v160
	v_exp_f32_e32 v161, v160
	v_lshlrev_b32_e32 v160, 16, v162
	v_mul_f32_e32 v160, 0xbfb8aa3b, v160
	v_exp_f32_e32 v160, v160
	v_add_f32_e32 v164, 1.0, v161
	v_and_b32_e32 v161, 0xffff0000, v162
	v_and_b32_e32 v162, 0xffff0000, v166
	v_mul_f32_e32 v162, 0xbfb8aa3b, v162
	v_exp_f32_e32 v162, v162
	v_mul_f32_e32 v161, 0xbfb8aa3b, v161
	v_exp_f32_e32 v161, v161
	v_rcp_f32_e32 v164, v164
	v_add_f32_e32 v162, 1.0, v162
	v_rcp_f32_e32 v165, v162
	v_lshlrev_b32_e32 v162, 16, v167
	v_and_b32_e32 v167, 0xffff0000, v167
	v_mul_f32_e32 v162, 0xbfb8aa3b, v162
	v_mul_f32_e32 v167, 0xbfb8aa3b, v167
	v_exp_f32_e32 v166, v162
	v_exp_f32_e32 v167, v167
	v_lshlrev_b32_e32 v162, 16, v163
	v_and_b32_e32 v163, 0xffff0000, v163
	v_mul_f32_e32 v162, 0xbfb8aa3b, v162
	v_mul_f32_e32 v163, 0xbfb8aa3b, v163
	v_exp_f32_e32 v162, v162
	v_add_f32_e32 v166, 1.0, v166
	v_exp_f32_e32 v163, v163
	v_add_f32_e32 v167, 1.0, v167
	v_rcp_f32_e32 v166, v166
	v_rcp_f32_e32 v167, v167
	v_pk_fma_f32 v[160:161], v[210:211], v[160:161], 1.0 op_sel_hi:[0,1,0]
	v_pk_mul_f32 v[160:161], v[164:165], v[160:161]
	v_pk_fma_f32 v[176:177], v[210:211], v[176:177], 1.0 op_sel_hi:[0,1,0]
	v_pk_mul_f32 v[24:25], v[24:25], v[160:161]
	v_pk_fma_f32 v[160:161], v[210:211], v[162:163], 1.0 op_sel_hi:[0,1,0]
	v_pk_mul_f32 v[160:161], v[166:167], v[160:161]
	v_pk_mul_f32 v[176:177], v[178:179], v[176:177]
	v_pk_mul_f32 v[26:27], v[26:27], v[160:161]
	s_waitcnt vmcnt(11)
	v_lshlrev_b32_e32 v160, 16, v148
	v_and_b32_e32 v148, 0xffff0000, v148
	v_mul_f32_e32 v148, 0xbfb8aa3b, v148
	v_exp_f32_e32 v148, v148
	v_mul_f32_e32 v160, 0xbfb8aa3b, v160
	v_exp_f32_e32 v161, v160
	s_waitcnt vmcnt(9)
; #define MG_LOAD(B, S) do { _Pragma("unroll") for (int mm = 0; mm < 2; ++mm) _Pragma("unroll") for (int bj = 0; bj < 2; ++bj) { \
;             const size_t o = (size_t)(((B) >> 1) * HALF + (((B) & 1) * 2 + mm) * 16) * IN_DIM + bj * HALF; \
;             gn[S][mm][bj] = *(const u32x4*)(zn + o); gd[S][mm][bj] = *(const u32x4*)(zd + o); } } while (0)
;     __device__ __forceinline__ void operator()(f32x4 (&acc)[2][2][4][2], const Unit& u, int wr, int wc, int fr, int fq) const {
;     ...
;         MG_LOAD(0, 0); MG_LOAD(1, 1); __builtin_amdgcn_sched_barrier(0);
;         MG_APPLY(0, 0); __builtin_amdgcn_sched_barrier(0);
;         MG_LOAD(2, 0); __builtin_amdgcn_sched_barrier(0);
;         MG_APPLY(1, 1); __builtin_amdgcn_sched_barrier(0);
;         MG_LOAD(3, 1); __builtin_amdgcn_sched_barrier(0);
;         MG_APPLY(2, 0); __builtin_amdgcn_sched_barrier(0);
;         MG_APPLY(3, 1); __builtin_amdgcn_sched_barrier(0);
	v_lshlrev_b32_e32 v160, 16, v156
	v_add_f32_e32 v148, 1.0, v148
	v_and_b32_e32 v156, 0xffff0000, v156
	v_rcp_f32_e32 v163, v148
	v_lshlrev_b32_e32 v148, 16, v149
	v_and_b32_e32 v149, 0xffff0000, v149
	v_mul_f32_e32 v156, 0xbfb8aa3b, v156
	v_mul_f32_e32 v148, 0xbfb8aa3b, v148
	v_mul_f32_e32 v149, 0xbfb8aa3b, v149
	v_add_f32_e32 v162, 1.0, v161
	v_exp_f32_e32 v161, v156
	v_exp_f32_e32 v156, v148
	v_exp_f32_e32 v164, v149
	v_lshlrev_b32_e32 v148, 16, v157
	v_and_b32_e32 v149, 0xffff0000, v157
	v_mul_f32_e32 v148, 0xbfb8aa3b, v148
	v_mul_f32_e32 v149, 0xbfb8aa3b, v149
	v_exp_f32_e32 v148, v148
	v_add_f32_e32 v156, 1.0, v156
	v_exp_f32_e32 v149, v149
	v_add_f32_e32 v157, 1.0, v164
	v_rcp_f32_e32 v156, v156
	v_rcp_f32_e32 v157, v157
	v_pk_fma_f32 v[148:149], v[210:211], v[148:149], 1.0 op_sel_hi:[0,1,0]
	v_mul_f32_e32 v160, 0xbfb8aa3b, v160
	v_exp_f32_e32 v160, v160
	v_pk_mul_f32 v[148:149], v[156:157], v[148:149]
	v_rcp_f32_e32 v162, v162
	v_pk_mul_f32 v[54:55], v[54:55], v[148:149]
	v_lshlrev_b32_e32 v148, 16, v150
	v_and_b32_e32 v150, 0xffff0000, v150
	v_mul_f32_e32 v150, 0xbfb8aa3b, v150
	v_exp_f32_e32 v150, v150
	v_mul_f32_e32 v148, 0xbfb8aa3b, v148
	v_exp_f32_e32 v149, v148
	v_pk_fma_f32 v[160:161], v[210:211], v[160:161], 1.0 op_sel_hi:[0,1,0]
	v_add_f32_e32 v150, 1.0, v150
	v_rcp_f32_e32 v157, v150
	v_lshlrev_b32_e32 v150, 16, v151
	v_and_b32_e32 v151, 0xffff0000, v151
	v_pk_mul_f32 v[160:161], v[162:163], v[160:161]
	v_mul_f32_e32 v150, 0xbfb8aa3b, v150
	v_mul_f32_e32 v151, 0xbfb8aa3b, v151
	v_pk_mul_f32 v[52:53], v[52:53], v[160:161]
	v_lshlrev_b32_e32 v148, 16, v158
	v_add_f32_e32 v156, 1.0, v149
	v_and_b32_e32 v149, 0xffff0000, v158
	v_exp_f32_e32 v158, v150
	v_exp_f32_e32 v160, v151
	v_mul_f32_e32 v148, 0xbfb8aa3b, v148
	v_mul_f32_e32 v149, 0xbfb8aa3b, v149
	v_exp_f32_e32 v148, v148
	v_exp_f32_e32 v149, v149
	v_lshlrev_b32_e32 v150, 16, v159
	v_and_b32_e32 v151, 0xffff0000, v159
	v_rcp_f32_e32 v156, v156
	v_mul_f32_e32 v150, 0xbfb8aa3b, v150
	v_mul_f32_e32 v151, 0xbfb8aa3b, v151
	v_exp_f32_e32 v150, v150
	v_add_f32_e32 v158, 1.0, v158
	v_exp_f32_e32 v151, v151
	v_add_f32_e32 v159, 1.0, v160
	v_rcp_f32_e32 v158, v158
	v_rcp_f32_e32 v159, v159
	v_pk_fma_f32 v[148:149], v[210:211], v[148:149], 1.0 op_sel_hi:[0,1,0]
	v_pk_mul_f32 v[148:149], v[156:157], v[148:149]
	v_pk_mul_f32 v[28:29], v[28:29], v[176:177]
	v_pk_mul_f32 v[48:49], v[48:49], v[148:149]
	v_pk_fma_f32 v[148:149], v[210:211], v[150:151], 1.0 op_sel_hi:[0,1,0]
	v_pk_mul_f32 v[148:149], v[158:159], v[148:149]
	s_nop 0
	v_pk_mul_f32 v[50:51], v[50:51], v[148:149]
	v_lshlrev_b32_e32 v148, 16, v140
	v_and_b32_e32 v140, 0xffff0000, v140
	v_mul_f32_e32 v148, 0xbfb8aa3b, v148
	v_mul_f32_e32 v140, 0xbfb8aa3b, v140
	v_exp_f32_e32 v149, v148
	v_exp_f32_e32 v140, v140
	s_waitcnt vmcnt(8)
	v_lshlrev_b32_e32 v148, 16, v136
	v_and_b32_e32 v136, 0xffff0000, v136
	v_mul_f32_e32 v136, 0xbfb8aa3b, v136
	v_add_f32_e32 v150, 1.0, v149
	v_exp_f32_e32 v149, v136
	v_add_f32_e32 v136, 1.0, v140
	v_rcp_f32_e32 v151, v136
	v_lshlrev_b32_e32 v136, 16, v141
	v_and_b32_e32 v141, 0xffff0000, v141
	v_mul_f32_e32 v136, 0xbfb8aa3b, v136
	v_mul_f32_e32 v141, 0xbfb8aa3b, v141
	v_exp_f32_e32 v140, v136
	v_exp_f32_e32 v141, v141
	v_lshlrev_b32_e32 v136, 16, v137
	v_and_b32_e32 v137, 0xffff0000, v137
	v_mul_f32_e32 v136, 0xbfb8aa3b, v136
	v_mul_f32_e32 v137, 0xbfb8aa3b, v137
	v_exp_f32_e32 v136, v136
	v_add_f32_e32 v140, 1.0, v140
	v_exp_f32_e32 v137, v137
	v_add_f32_e32 v141, 1.0, v141
	v_rcp_f32_e32 v140, v140
	v_rcp_f32_e32 v141, v141
	v_pk_fma_f32 v[136:137], v[210:211], v[136:137], 1.0 op_sel_hi:[0,1,0]
	v_mul_f32_e32 v148, 0xbfb8aa3b, v148
	v_exp_f32_e32 v148, v148
	v_pk_mul_f32 v[136:137], v[140:141], v[136:137]
	v_rcp_f32_e32 v150, v150
	v_pk_mul_f32 v[22:23], v[22:23], v[136:137]
	v_lshlrev_b32_e32 v136, 16, v142
	v_mul_f32_e32 v136, 0xbfb8aa3b, v136
	v_exp_f32_e32 v137, v136
	v_lshlrev_b32_e32 v136, 16, v138
	v_mul_f32_e32 v136, 0xbfb8aa3b, v136
	v_exp_f32_e32 v136, v136
	v_add_f32_e32 v140, 1.0, v137
	v_and_b32_e32 v137, 0xffff0000, v138
	v_and_b32_e32 v138, 0xffff0000, v142
	v_mul_f32_e32 v138, 0xbfb8aa3b, v138
	v_exp_f32_e32 v138, v138
	v_mul_f32_e32 v137, 0xbfb8aa3b, v137
	v_exp_f32_e32 v137, v137
	v_rcp_f32_e32 v140, v140
	v_add_f32_e32 v138, 1.0, v138
	v_rcp_f32_e32 v141, v138
	v_lshlrev_b32_e32 v138, 16, v143
	v_and_b32_e32 v143, 0xffff0000, v143
	v_mul_f32_e32 v138, 0xbfb8aa3b, v138
	v_mul_f32_e32 v143, 0xbfb8aa3b, v143
	v_exp_f32_e32 v142, v138
	v_exp_f32_e32 v143, v143
	v_lshlrev_b32_e32 v138, 16, v139
	v_and_b32_e32 v139, 0xffff0000, v139
	v_mul_f32_e32 v138, 0xbfb8aa3b, v138
	v_mul_f32_e32 v139, 0xbfb8aa3b, v139
	v_exp_f32_e32 v138, v138
	v_add_f32_e32 v142, 1.0, v142
	v_exp_f32_e32 v139, v139
	v_add_f32_e32 v143, 1.0, v143
	v_rcp_f32_e32 v142, v142
	v_rcp_f32_e32 v143, v143
	v_pk_fma_f32 v[136:137], v[210:211], v[136:137], 1.0 op_sel_hi:[0,1,0]
	v_pk_mul_f32 v[136:137], v[140:141], v[136:137]
	v_pk_fma_f32 v[148:149], v[210:211], v[148:149], 1.0 op_sel_hi:[0,1,0]
	v_pk_mul_f32 v[16:17], v[16:17], v[136:137]
	v_pk_fma_f32 v[136:137], v[210:211], v[138:139], 1.0 op_sel_hi:[0,1,0]
	v_pk_mul_f32 v[148:149], v[150:151], v[148:149]
	v_pk_mul_f32 v[136:137], v[142:143], v[136:137]
	v_pk_mul_f32 v[20:21], v[20:21], v[148:149]
	v_pk_mul_f32 v[18:19], v[18:19], v[136:137]
	s_waitcnt vmcnt(7)
	v_lshlrev_b32_e32 v140, 16, v185
	v_mul_f32_e32 v140, 0xbfb8aa3b, v140
	v_lshlrev_b32_e32 v136, 16, v184
	v_exp_f32_e32 v141, v140
	v_mul_f32_e32 v136, 0xbfb8aa3b, v136
	v_exp_f32_e32 v137, v136
	v_and_b32_e32 v139, 0xffff0000, v184
	v_mul_f32_e32 v139, 0xbfb8aa3b, v139
	v_exp_f32_e32 v139, v139
	v_add_f32_e32 v141, 1.0, v141
	v_rcp_f32_e32 v142, v141
	v_and_b32_e32 v141, 0xffff0000, v185
	s_waitcnt vmcnt(5)
; #define MG_LOAD(B, S) do { _Pragma("unroll") for (int mm = 0; mm < 2; ++mm) _Pragma("unroll") for (int bj = 0; bj < 2; ++bj) { \
;             const size_t o = (size_t)(((B) >> 1) * HALF + (((B) & 1) * 2 + mm) * 16) * IN_DIM + bj * HALF; \
;             gn[S][mm][bj] = *(const u32x4*)(zn + o); gd[S][mm][bj] = *(const u32x4*)(zd + o); } } while (0)
;     __device__ __forceinline__ void operator()(f32x4 (&acc)[2][2][4][2], const Unit& u, int wr, int wc, int fr, int fq) const {
;     ...
;         MG_LOAD(0, 0); MG_LOAD(1, 1); __builtin_amdgcn_sched_barrier(0);
;         MG_APPLY(0, 0); __builtin_amdgcn_sched_barrier(0);
;         MG_LOAD(2, 0); __builtin_amdgcn_sched_barrier(0);
;         MG_APPLY(1, 1); __builtin_amdgcn_sched_barrier(0);
;         MG_LOAD(3, 1); __builtin_amdgcn_sched_barrier(0);
;         MG_APPLY(2, 0); __builtin_amdgcn_sched_barrier(0);
;         MG_APPLY(3, 1); __builtin_amdgcn_sched_barrier(0);
	v_lshlrev_b32_e32 v136, 16, v188
	v_add_f32_e32 v138, 1.0, v137
	v_and_b32_e32 v137, 0xffff0000, v188
	v_mul_f32_e32 v141, 0xbfb8aa3b, v141
	v_mul_f32_e32 v136, 0xbfb8aa3b, v136
	v_mul_f32_e32 v137, 0xbfb8aa3b, v137
	v_exp_f32_e32 v143, v141
	v_exp_f32_e32 v136, v136
	v_exp_f32_e32 v137, v137
	v_add_f32_e32 v139, 1.0, v139
	v_lshlrev_b32_e32 v140, 16, v189
	v_and_b32_e32 v141, 0xffff0000, v189
	v_rcp_f32_e32 v138, v138
	v_rcp_f32_e32 v139, v139
	v_mul_f32_e32 v140, 0xbfb8aa3b, v140
	v_mul_f32_e32 v141, 0xbfb8aa3b, v141
	v_exp_f32_e32 v140, v140
	v_exp_f32_e32 v141, v141
	v_add_f32_e32 v143, 1.0, v143
	v_pk_fma_f32 v[136:137], v[210:211], v[136:137], 1.0 op_sel_hi:[0,1,0]
	v_rcp_f32_e32 v143, v143
	v_pk_mul_f32 v[136:137], v[138:139], v[136:137]
	v_and_b32_e32 v139, 0xffff0000, v186
	v_pk_mul_f32 v[44:45], v[44:45], v[136:137]
	v_pk_fma_f32 v[136:137], v[210:211], v[140:141], 1.0 op_sel_hi:[0,1,0]
	v_lshlrev_b32_e32 v140, 16, v187
	v_mul_f32_e32 v140, 0xbfb8aa3b, v140
	v_pk_mul_f32 v[136:137], v[142:143], v[136:137]
	v_exp_f32_e32 v141, v140
	v_pk_mul_f32 v[46:47], v[46:47], v[136:137]
	v_lshlrev_b32_e32 v136, 16, v186
	v_mul_f32_e32 v136, 0xbfb8aa3b, v136
	v_exp_f32_e32 v137, v136
	v_mul_f32_e32 v139, 0xbfb8aa3b, v139
	v_add_f32_e32 v141, 1.0, v141
	v_exp_f32_e32 v139, v139
	v_rcp_f32_e32 v142, v141
	v_and_b32_e32 v141, 0xffff0000, v187
	v_mul_f32_e32 v141, 0xbfb8aa3b, v141
	v_lshlrev_b32_e32 v136, 16, v190
	v_add_f32_e32 v138, 1.0, v137
	v_and_b32_e32 v137, 0xffff0000, v190
	v_exp_f32_e32 v143, v141
	v_mul_f32_e32 v136, 0xbfb8aa3b, v136
	v_mul_f32_e32 v137, 0xbfb8aa3b, v137
	v_exp_f32_e32 v136, v136
	v_exp_f32_e32 v137, v137
	v_add_f32_e32 v139, 1.0, v139
	v_lshlrev_b32_e32 v140, 16, v191
	v_and_b32_e32 v141, 0xffff0000, v191
	v_rcp_f32_e32 v138, v138
	v_rcp_f32_e32 v139, v139
	v_mul_f32_e32 v140, 0xbfb8aa3b, v140
	v_mul_f32_e32 v141, 0xbfb8aa3b, v141
	v_exp_f32_e32 v140, v140
	v_exp_f32_e32 v141, v141
	v_add_f32_e32 v143, 1.0, v143
	v_rcp_f32_e32 v143, v143
	v_pk_fma_f32 v[136:137], v[210:211], v[136:137], 1.0 op_sel_hi:[0,1,0]
	v_pk_mul_f32 v[136:137], v[138:139], v[136:137]
	v_and_b32_e32 v139, 0xffff0000, v172
	v_pk_mul_f32 v[40:41], v[40:41], v[136:137]
	v_pk_fma_f32 v[136:137], v[210:211], v[140:141], 1.0 op_sel_hi:[0,1,0]
	v_lshlrev_b32_e32 v140, 16, v173
	v_pk_mul_f32 v[136:137], v[142:143], v[136:137]
	v_mul_f32_e32 v140, 0xbfb8aa3b, v140
	v_pk_mul_f32 v[42:43], v[42:43], v[136:137]
	v_lshlrev_b32_e32 v136, 16, v172
	v_exp_f32_e32 v141, v140
	v_mul_f32_e32 v136, 0xbfb8aa3b, v136
	v_exp_f32_e32 v137, v136
	v_mul_f32_e32 v139, 0xbfb8aa3b, v139
	v_exp_f32_e32 v139, v139
	v_add_f32_e32 v141, 1.0, v141
	v_rcp_f32_e32 v142, v141
	v_and_b32_e32 v141, 0xffff0000, v173
	s_waitcnt vmcnt(4)
	v_lshlrev_b32_e32 v136, 16, v168
	v_add_f32_e32 v138, 1.0, v137
	v_and_b32_e32 v137, 0xffff0000, v168
	v_mul_f32_e32 v141, 0xbfb8aa3b, v141
	v_mul_f32_e32 v136, 0xbfb8aa3b, v136
	v_mul_f32_e32 v137, 0xbfb8aa3b, v137
	v_exp_f32_e32 v143, v141
	v_exp_f32_e32 v136, v136
	v_exp_f32_e32 v137, v137
	v_add_f32_e32 v139, 1.0, v139
	v_lshlrev_b32_e32 v140, 16, v169
	v_and_b32_e32 v141, 0xffff0000, v169
	v_rcp_f32_e32 v138, v138
	v_rcp_f32_e32 v139, v139
	v_mul_f32_e32 v140, 0xbfb8aa3b, v140
	v_mul_f32_e32 v141, 0xbfb8aa3b, v141
	v_exp_f32_e32 v140, v140
	v_exp_f32_e32 v141, v141
	v_add_f32_e32 v143, 1.0, v143
	v_pk_fma_f32 v[136:137], v[210:211], v[136:137], 1.0 op_sel_hi:[0,1,0]
	v_rcp_f32_e32 v143, v143
	v_pk_mul_f32 v[136:137], v[138:139], v[136:137]
	v_and_b32_e32 v139, 0xffff0000, v174
	v_pk_mul_f32 v[12:13], v[12:13], v[136:137]
	v_pk_fma_f32 v[136:137], v[210:211], v[140:141], 1.0 op_sel_hi:[0,1,0]
	v_lshlrev_b32_e32 v140, 16, v175
	v_mul_f32_e32 v140, 0xbfb8aa3b, v140
	v_pk_mul_f32 v[136:137], v[142:143], v[136:137]
	v_exp_f32_e32 v141, v140
	v_pk_mul_f32 v[14:15], v[14:15], v[136:137]
	v_lshlrev_b32_e32 v136, 16, v174
	v_mul_f32_e32 v136, 0xbfb8aa3b, v136
	v_exp_f32_e32 v137, v136
	v_mul_f32_e32 v139, 0xbfb8aa3b, v139
	v_add_f32_e32 v141, 1.0, v141
	v_exp_f32_e32 v139, v139
	v_rcp_f32_e32 v142, v141
	v_and_b32_e32 v141, 0xffff0000, v175
	v_mul_f32_e32 v141, 0xbfb8aa3b, v141
	v_lshlrev_b32_e32 v136, 16, v170
	v_add_f32_e32 v138, 1.0, v137
	v_and_b32_e32 v137, 0xffff0000, v170
	v_exp_f32_e32 v143, v141
	v_mul_f32_e32 v136, 0xbfb8aa3b, v136
	v_mul_f32_e32 v137, 0xbfb8aa3b, v137
	v_exp_f32_e32 v136, v136
	v_exp_f32_e32 v137, v137
	v_add_f32_e32 v139, 1.0, v139
	v_lshlrev_b32_e32 v140, 16, v171
	v_and_b32_e32 v141, 0xffff0000, v171
	v_rcp_f32_e32 v138, v138
	v_rcp_f32_e32 v139, v139
	v_mul_f32_e32 v140, 0xbfb8aa3b, v140
	v_mul_f32_e32 v141, 0xbfb8aa3b, v141
	v_exp_f32_e32 v140, v140
	v_exp_f32_e32 v141, v141
	v_add_f32_e32 v143, 1.0, v143
	v_rcp_f32_e32 v143, v143
	v_pk_fma_f32 v[136:137], v[210:211], v[136:137], 1.0 op_sel_hi:[0,1,0]
	v_pk_mul_f32 v[136:137], v[138:139], v[136:137]
	s_waitcnt vmcnt(3)
	v_and_b32_e32 v139, 0xffff0000, v144
	v_pk_mul_f32 v[8:9], v[8:9], v[136:137]
	v_pk_fma_f32 v[136:137], v[210:211], v[140:141], 1.0 op_sel_hi:[0,1,0]
	v_lshlrev_b32_e32 v140, 16, v145
	v_pk_mul_f32 v[136:137], v[142:143], v[136:137]
	v_mul_f32_e32 v140, 0xbfb8aa3b, v140
	v_pk_mul_f32 v[10:11], v[10:11], v[136:137]
	v_lshlrev_b32_e32 v136, 16, v144
	v_exp_f32_e32 v141, v140
	v_mul_f32_e32 v136, 0xbfb8aa3b, v136
	v_exp_f32_e32 v137, v136
	v_mul_f32_e32 v139, 0xbfb8aa3b, v139
	v_exp_f32_e32 v139, v139
	v_add_f32_e32 v141, 1.0, v141
	v_rcp_f32_e32 v142, v141
	v_and_b32_e32 v141, 0xffff0000, v145
	s_waitcnt vmcnt(1)
; #define MG_LOAD(B, S) do { _Pragma("unroll") for (int mm = 0; mm < 2; ++mm) _Pragma("unroll") for (int bj = 0; bj < 2; ++bj) { \
;             const size_t o = (size_t)(((B) >> 1) * HALF + (((B) & 1) * 2 + mm) * 16) * IN_DIM + bj * HALF; \
;             gn[S][mm][bj] = *(const u32x4*)(zn + o); gd[S][mm][bj] = *(const u32x4*)(zd + o); } } while (0)
;     __device__ __forceinline__ void operator()(f32x4 (&acc)[2][2][4][2], const Unit& u, int wr, int wc, int fr, int fq) const {
;     ...
;         MG_LOAD(0, 0); MG_LOAD(1, 1); __builtin_amdgcn_sched_barrier(0);
;         MG_APPLY(0, 0); __builtin_amdgcn_sched_barrier(0);
;         MG_LOAD(2, 0); __builtin_amdgcn_sched_barrier(0);
;         MG_APPLY(1, 1); __builtin_amdgcn_sched_barrier(0);
;         MG_LOAD(3, 1); __builtin_amdgcn_sched_barrier(0);
;         MG_APPLY(2, 0); __builtin_amdgcn_sched_barrier(0);
;         MG_APPLY(3, 1); __builtin_amdgcn_sched_barrier(0);
	v_lshlrev_b32_e32 v136, 16, v152
	v_add_f32_e32 v138, 1.0, v137
	v_and_b32_e32 v137, 0xffff0000, v152
	v_mul_f32_e32 v141, 0xbfb8aa3b, v141
	v_mul_f32_e32 v136, 0xbfb8aa3b, v136
	v_mul_f32_e32 v137, 0xbfb8aa3b, v137
	v_exp_f32_e32 v143, v141
	v_exp_f32_e32 v136, v136
	v_exp_f32_e32 v137, v137
	v_add_f32_e32 v139, 1.0, v139
	v_lshlrev_b32_e32 v140, 16, v153
	v_and_b32_e32 v141, 0xffff0000, v153
	v_rcp_f32_e32 v138, v138
	v_rcp_f32_e32 v139, v139
	v_mul_f32_e32 v140, 0xbfb8aa3b, v140
	v_mul_f32_e32 v141, 0xbfb8aa3b, v141
	v_exp_f32_e32 v140, v140
	v_exp_f32_e32 v141, v141
	v_add_f32_e32 v143, 1.0, v143
	v_pk_fma_f32 v[136:137], v[210:211], v[136:137], 1.0 op_sel_hi:[0,1,0]
	v_rcp_f32_e32 v143, v143
	v_pk_mul_f32 v[136:137], v[138:139], v[136:137]
	v_and_b32_e32 v139, 0xffff0000, v146
	v_pk_mul_f32 v[36:37], v[36:37], v[136:137]
	v_pk_fma_f32 v[136:137], v[210:211], v[140:141], 1.0 op_sel_hi:[0,1,0]
	v_lshlrev_b32_e32 v140, 16, v147
	v_mul_f32_e32 v140, 0xbfb8aa3b, v140
	v_pk_mul_f32 v[136:137], v[142:143], v[136:137]
	v_exp_f32_e32 v141, v140
	v_pk_mul_f32 v[38:39], v[38:39], v[136:137]
	v_lshlrev_b32_e32 v136, 16, v146
	v_mul_f32_e32 v136, 0xbfb8aa3b, v136
	v_exp_f32_e32 v137, v136
	v_mul_f32_e32 v139, 0xbfb8aa3b, v139
	v_add_f32_e32 v141, 1.0, v141
	v_exp_f32_e32 v139, v139
	v_rcp_f32_e32 v142, v141
	v_and_b32_e32 v141, 0xffff0000, v147
	v_mul_f32_e32 v141, 0xbfb8aa3b, v141
	v_lshlrev_b32_e32 v136, 16, v154
	v_add_f32_e32 v138, 1.0, v137
	v_and_b32_e32 v137, 0xffff0000, v154
	v_exp_f32_e32 v143, v141
	v_mul_f32_e32 v136, 0xbfb8aa3b, v136
	v_mul_f32_e32 v137, 0xbfb8aa3b, v137
	v_exp_f32_e32 v136, v136
	v_exp_f32_e32 v137, v137
	v_add_f32_e32 v139, 1.0, v139
	v_lshlrev_b32_e32 v140, 16, v155
	v_and_b32_e32 v141, 0xffff0000, v155
	v_rcp_f32_e32 v138, v138
	v_rcp_f32_e32 v139, v139
	v_mul_f32_e32 v140, 0xbfb8aa3b, v140
	v_mul_f32_e32 v141, 0xbfb8aa3b, v141
	v_exp_f32_e32 v140, v140
	v_exp_f32_e32 v141, v141
	v_add_f32_e32 v143, 1.0, v143
	v_rcp_f32_e32 v143, v143
	v_pk_fma_f32 v[136:137], v[210:211], v[136:137], 1.0 op_sel_hi:[0,1,0]
	v_pk_mul_f32 v[136:137], v[138:139], v[136:137]
	s_nop 0
	v_pk_mul_f32 v[32:33], v[32:33], v[136:137]
	v_pk_fma_f32 v[136:137], v[210:211], v[140:141], 1.0 op_sel_hi:[0,1,0]
	v_pk_mul_f32 v[136:137], v[142:143], v[136:137]
	s_nop 0
	v_pk_mul_f32 v[34:35], v[34:35], v[136:137]
	v_lshlrev_b32_e32 v136, 16, v132
	v_and_b32_e32 v132, 0xffff0000, v132
	v_mul_f32_e32 v136, 0xbfb8aa3b, v136
	v_mul_f32_e32 v132, 0xbfb8aa3b, v132
	v_exp_f32_e32 v137, v136
	v_exp_f32_e32 v132, v132
	s_waitcnt vmcnt(0)
	v_lshlrev_b32_e32 v136, 16, v128
	v_and_b32_e32 v128, 0xffff0000, v128
	v_mul_f32_e32 v128, 0xbfb8aa3b, v128
	v_add_f32_e32 v138, 1.0, v137
	v_exp_f32_e32 v137, v128
	v_add_f32_e32 v128, 1.0, v132
	v_rcp_f32_e32 v139, v128
	v_lshlrev_b32_e32 v128, 16, v133
	v_and_b32_e32 v133, 0xffff0000, v133
	v_mul_f32_e32 v128, 0xbfb8aa3b, v128
	v_mul_f32_e32 v133, 0xbfb8aa3b, v133
	v_exp_f32_e32 v132, v128
	v_exp_f32_e32 v133, v133
	v_lshlrev_b32_e32 v128, 16, v129
	v_and_b32_e32 v129, 0xffff0000, v129
	v_mul_f32_e32 v128, 0xbfb8aa3b, v128
	v_mul_f32_e32 v129, 0xbfb8aa3b, v129
	v_exp_f32_e32 v128, v128
	v_add_f32_e32 v132, 1.0, v132
	v_exp_f32_e32 v129, v129
	v_add_f32_e32 v133, 1.0, v133
	v_rcp_f32_e32 v132, v132
	v_rcp_f32_e32 v133, v133
	v_pk_fma_f32 v[128:129], v[210:211], v[128:129], 1.0 op_sel_hi:[0,1,0]
	v_mul_f32_e32 v136, 0xbfb8aa3b, v136
	v_exp_f32_e32 v136, v136
	v_pk_mul_f32 v[128:129], v[132:133], v[128:129]
	v_rcp_f32_e32 v138, v138
	v_pk_mul_f32 v[6:7], v[6:7], v[128:129]
	v_lshlrev_b32_e32 v128, 16, v134
	v_mul_f32_e32 v128, 0xbfb8aa3b, v128
	v_exp_f32_e32 v129, v128
	v_lshlrev_b32_e32 v128, 16, v130
	v_mul_f32_e32 v128, 0xbfb8aa3b, v128
	v_exp_f32_e32 v128, v128
	v_add_f32_e32 v132, 1.0, v129
	v_and_b32_e32 v129, 0xffff0000, v130
	v_and_b32_e32 v130, 0xffff0000, v134
	v_mul_f32_e32 v130, 0xbfb8aa3b, v130
	v_exp_f32_e32 v130, v130
	v_mul_f32_e32 v129, 0xbfb8aa3b, v129
	v_exp_f32_e32 v129, v129
	v_rcp_f32_e32 v132, v132
	v_add_f32_e32 v130, 1.0, v130
	v_rcp_f32_e32 v133, v130
	v_lshlrev_b32_e32 v130, 16, v135
	v_and_b32_e32 v135, 0xffff0000, v135
	v_mul_f32_e32 v130, 0xbfb8aa3b, v130
	v_mul_f32_e32 v135, 0xbfb8aa3b, v135
	v_exp_f32_e32 v134, v130
	v_exp_f32_e32 v135, v135
	v_lshlrev_b32_e32 v130, 16, v131
	v_and_b32_e32 v131, 0xffff0000, v131
	v_mul_f32_e32 v130, 0xbfb8aa3b, v130
	v_mul_f32_e32 v131, 0xbfb8aa3b, v131
	v_exp_f32_e32 v130, v130
	v_add_f32_e32 v134, 1.0, v134
	v_exp_f32_e32 v131, v131
	v_add_f32_e32 v135, 1.0, v135
	v_rcp_f32_e32 v134, v134
	v_rcp_f32_e32 v135, v135
	v_pk_fma_f32 v[128:129], v[210:211], v[128:129], 1.0 op_sel_hi:[0,1,0]
	v_pk_mul_f32 v[128:129], v[132:133], v[128:129]
	v_pk_fma_f32 v[136:137], v[210:211], v[136:137], 1.0 op_sel_hi:[0,1,0]
	v_pk_mul_f32 v[0:1], v[0:1], v[128:129]
	v_pk_fma_f32 v[128:129], v[210:211], v[130:131], 1.0 op_sel_hi:[0,1,0]
	v_pk_mul_f32 v[136:137], v[138:139], v[136:137]
	v_pk_mul_f32 v[128:129], v[134:135], v[128:129]
	v_pk_mul_f32 v[4:5], v[4:5], v[136:137]
	v_pk_mul_f32 v[2:3], v[2:3], v[128:129]
	s_mov_b64 s[52:53], -1
	s_and_b64 vcc, exec, s[48:49]
	s_cbranch_vccz .LBB0_549
; __device__ __forceinline__ unsigned cvt_pk_bf16(float lo, float hi) { unsigned r; asm volatile("v_cvt_pk_bf16_f32 %0, %1, %2" : "=v"(r) : "v"(lo), "v"(hi)); return r; }
;     __device__ __forceinline__ void operator()(f32x4 (&acc)[2][2][4][2], const Unit& u, int wr, int wc, int fr, int fq) const {
;     ...
;         } else if (u.seg == 3) {
;             bf16_t* ob = O + (size_t)row0 * DM + col0;
; #pragma unroll
;             for (int ai = 0; ai < 2; ++ai)
; #pragma unroll
;                 for (int m = 0; m < 4; ++m)
; #pragma unroll
;                     for (int bj = 0; bj < 2; ++bj) { const f32x4 v0 = acc[ai][bj][m][0], v1 = acc[ai][bj][m][1];
;                         u32x4 w; w.x = cvt_pk_bf16(v0[0], v0[1]); w.y = cvt_pk_bf16(v0[2], v0[3]); w.z = cvt_pk_bf16(v1[0], v1[1]); w.w = cvt_pk_bf16(v1[2], v1[3]);
;                         *(u32x4*)(ob + (size_t)(ai * HALF + m * 16) * DM + bj * HALF) = w; }
	s_andn2_b64 vcc, exec, s[50:51]
	s_cbranch_vccnz .LBB0_548
	v_lshlrev_b64 v[128:129], 12, v[208:209]
	v_lshl_add_u64 v[128:129], s[10:11], 0, v[128:129]
	v_lshl_add_u64 v[128:129], v[206:207], 1, v[128:129]
	v_cvt_pk_bf16_f32 v130, v124, v125
	v_cvt_pk_bf16_f32 v131, v126, v127
	v_cvt_pk_bf16_f32 v132, v120, v121
	v_cvt_pk_bf16_f32 v133, v122, v123
	global_store_dwordx4 v[128:129], v[130:133], off
	v_add_co_u32_e32 v134, vcc, s66, v128
	s_nop 0
	v_cvt_pk_bf16_f32 v130, v92, v93
	v_cvt_pk_bf16_f32 v131, v94, v95
	v_cvt_pk_bf16_f32 v132, v88, v89
	v_cvt_pk_bf16_f32 v133, v90, v91
	global_store_dwordx4 v[128:129], v[130:133], off offset:256
	v_addc_co_u32_e32 v135, vcc, 0, v129, vcc
	s_nop 0
	v_cvt_pk_bf16_f32 v130, v116, v117
	v_cvt_pk_bf16_f32 v131, v118, v119
	v_cvt_pk_bf16_f32 v132, v112, v113
	v_cvt_pk_bf16_f32 v133, v114, v115
	global_store_dwordx4 v[134:135], v[130:133], off
	s_nop 1
	v_cvt_pk_bf16_f32 v130, v84, v85
	v_cvt_pk_bf16_f32 v131, v86, v87
	v_cvt_pk_bf16_f32 v132, v80, v81
	v_cvt_pk_bf16_f32 v133, v82, v83
	global_store_dwordx4 v[134:135], v[130:133], off offset:256
	v_add_co_u32_e32 v134, vcc, s82, v128
	s_nop 0
	v_cvt_pk_bf16_f32 v130, v108, v109
	v_cvt_pk_bf16_f32 v131, v110, v111
	v_cvt_pk_bf16_f32 v132, v104, v105
	v_cvt_pk_bf16_f32 v133, v106, v107
	s_nop 0
	v_addc_co_u32_e32 v135, vcc, 0, v129, vcc
	global_store_dwordx4 v[134:135], v[130:133], off
	s_nop 1
	v_cvt_pk_bf16_f32 v130, v76, v77
	v_cvt_pk_bf16_f32 v131, v78, v79
	v_cvt_pk_bf16_f32 v132, v72, v73
	v_cvt_pk_bf16_f32 v133, v74, v75
	global_store_dwordx4 v[134:135], v[130:133], off offset:256
	v_add_co_u32_e32 v134, vcc, s83, v128
	s_nop 0
	v_cvt_pk_bf16_f32 v130, v100, v101
	v_cvt_pk_bf16_f32 v131, v102, v103
	v_cvt_pk_bf16_f32 v132, v96, v97
	v_cvt_pk_bf16_f32 v133, v98, v99
	s_nop 0
	v_addc_co_u32_e32 v135, vcc, 0, v129, vcc
	global_store_dwordx4 v[134:135], v[130:133], off
	s_nop 1
	v_cvt_pk_bf16_f32 v130, v68, v69
	v_cvt_pk_bf16_f32 v131, v70, v71
	v_cvt_pk_bf16_f32 v132, v64, v65
	v_cvt_pk_bf16_f32 v133, v66, v67
	global_store_dwordx4 v[134:135], v[130:133], off offset:256
	v_add_co_u32_e32 v134, vcc, s86, v128
	s_nop 0
	v_cvt_pk_bf16_f32 v130, v60, v61
	v_cvt_pk_bf16_f32 v131, v62, v63
	v_cvt_pk_bf16_f32 v132, v56, v57
	v_cvt_pk_bf16_f32 v133, v58, v59
	s_nop 0
	v_addc_co_u32_e32 v135, vcc, 0, v129, vcc
	global_store_dwordx4 v[134:135], v[130:133], off
	s_nop 1
	v_cvt_pk_bf16_f32 v130, v28, v29
	v_cvt_pk_bf16_f32 v131, v30, v31
	v_cvt_pk_bf16_f32 v132, v24, v25
	v_cvt_pk_bf16_f32 v133, v26, v27
	global_store_dwordx4 v[134:135], v[130:133], off offset:256
	v_add_co_u32_e32 v134, vcc, s87, v128
	s_nop 0
	v_cvt_pk_bf16_f32 v130, v52, v53
	v_cvt_pk_bf16_f32 v131, v54, v55
	v_cvt_pk_bf16_f32 v132, v48, v49
	v_cvt_pk_bf16_f32 v133, v50, v51
	s_nop 0
	v_addc_co_u32_e32 v135, vcc, 0, v129, vcc
	global_store_dwordx4 v[134:135], v[130:133], off
	s_nop 1
	v_cvt_pk_bf16_f32 v130, v20, v21
	v_cvt_pk_bf16_f32 v131, v22, v23
	v_cvt_pk_bf16_f32 v132, v16, v17
	v_cvt_pk_bf16_f32 v133, v18, v19
	global_store_dwordx4 v[134:135], v[130:133], off offset:256
	v_add_co_u32_e32 v134, vcc, s88, v128
	s_nop 0
	v_cvt_pk_bf16_f32 v130, v44, v45
	v_cvt_pk_bf16_f32 v131, v46, v47
	v_cvt_pk_bf16_f32 v132, v40, v41
	v_cvt_pk_bf16_f32 v133, v42, v43
	s_nop 0
	v_addc_co_u32_e32 v135, vcc, 0, v129, vcc
	global_store_dwordx4 v[134:135], v[130:133], off
	s_nop 1
	v_cvt_pk_bf16_f32 v130, v12, v13
	v_cvt_pk_bf16_f32 v131, v14, v15
	v_cvt_pk_bf16_f32 v132, v8, v9
	v_cvt_pk_bf16_f32 v133, v10, v11
	global_store_dwordx4 v[134:135], v[130:133], off offset:256
	v_add_co_u32_e32 v134, vcc, s89, v128
	s_nop 0
	v_cvt_pk_bf16_f32 v130, v36, v37
	v_cvt_pk_bf16_f32 v131, v38, v39
	v_cvt_pk_bf16_f32 v132, v32, v33
	v_cvt_pk_bf16_f32 v133, v34, v35
	s_nop 0
	v_addc_co_u32_e32 v135, vcc, 0, v129, vcc
	global_store_dwordx4 v[134:135], v[130:133], off
	v_cvt_pk_bf16_f32 v128, v4, v5
	v_cvt_pk_bf16_f32 v129, v6, v7
	s_nop 1
	v_cvt_pk_bf16_f32 v130, v0, v1
	v_cvt_pk_bf16_f32 v131, v2, v3
	global_store_dwordx4 v[134:135], v[128:131], off offset:256

; #define MG_LOAD(B, S) do { _Pragma("unroll") for (int mm = 0; mm < 2; ++mm) _Pragma("unroll") for (int bj = 0; bj < 2; ++bj) { \
;             const size_t o = (size_t)(((B) >> 1) * HALF + (((B) & 1) * 2 + mm) * 16) * IN_DIM + bj * HALF; \
;             gn[S][mm][bj] = *(const u32x4*)(zn + o); gd[S][mm][bj] = *(const u32x4*)(zd + o); } } while (0)
;     __device__ __forceinline__ void operator()(f32x4 (&acc)[2][2][4][2], const Unit& u, int wr, int wc, int fr, int fq) const {
;         const bool indep = u.ks >= 0;
;         if (u.seg == 2 && !indep) return;
;         const int row0 = u.pm * BM + wr * 64 + fr, col0 = u.pn * BM + wc * 32 + 8 * fq;
;         const bool plain = indep || u.seg == 3;
;         const int sn = plain ? (u.seg < 2 ? u.seg : 2) : u.seg, sd = plain ? sn : u.seg + 1;
;         const float dmask = plain ? 0.f : 1.f;
;         const bf16_t* zn = Z + (size_t)row0 * IN_DIM + OFF_GATE + sn * DM + col0;
;         const bf16_t* zd = Z + (size_t)row0 * IN_DIM + OFF_GATE + sd * DM + col0;
;     ...
;         u32x4 gn[2][2][2], gd[2][2][2];
;     ...
;         MG_LOAD(0, 0); MG_LOAD(1, 1); __builtin_amdgcn_sched_barrier(0);
;         MG_APPLY(0, 0); __builtin_amdgcn_sched_barrier(0);
;         MG_LOAD(2, 0); __builtin_amdgcn_sched_barrier(0);
.LBB0_1615:
	s_cmp_eq_u32 s72, 2
	s_cbranch_scc1 .LBB0_1618
	v_lshl_add_u32 v208, s6, 8, v211
	s_lshl_b32 s6, s72, 11
	s_add_i32 s21, s6, 0x800
	s_cmp_eq_u32 s72, 3
	s_cselect_b64 s[28:29], -1, 0
	v_cndmask_b32_e64 v210, 1.0, 0, s[28:29]
	s_and_b64 s[28:29], s[28:29], exec
	v_mov_b64_e32 v[128:129], s[2:3]
	v_lshl_or_b32 v206, s73, 8, v219
	s_cselect_b32 s6, 0x1000, s6
	v_mad_i64_i32 v[128:129], s[30:31], v208, s56, v[128:129]
	s_cselect_b32 s21, 0x1000, s21
	s_lshl_b32 s6, s6, 1
	v_lshl_add_u64 v[128:129], v[128:129], 0, s[18:19]
	v_ashrrev_i32_e32 v207, 31, v206
	s_lshl_b32 s28, s21, 1
	v_lshl_add_u64 v[130:131], v[128:129], 0, s[6:7]
	v_lshlrev_b64 v[132:133], 1, v[206:207]
	s_mov_b32 s29, s7
	v_lshl_add_u64 v[214:215], v[130:131], 0, v[132:133]
	v_lshl_add_u64 v[128:129], v[128:129], 0, s[28:29]
	v_lshl_add_u64 v[212:213], v[128:129], 0, v[132:133]
	v_add_co_u32_e32 v128, vcc, s57, v214
	v_mov_b32_e32 v240, 0x380000
	v_mov_b32_e32 v241, 0
	v_lshl_add_u64 v[242:243], v[214:215], 0, v[240:241]
	global_load_dword v244, v[242:243], off
	global_load_dwordx4 v[176:179], v[214:215], off
	v_lshl_add_u64 v[242:243], v[214:215], 0, v[240:241]
	global_load_dword v244, v[242:243], off offset:256
	global_load_dwordx4 v[164:167], v[214:215], off offset:256
	v_lshl_add_u64 v[242:243], v[212:213], 0, v[240:241]
	global_load_dword v244, v[242:243], off
	global_load_dwordx4 v[180:183], v[212:213], off
	v_lshl_add_u64 v[242:243], v[212:213], 0, v[240:241]
	global_load_dword v244, v[242:243], off offset:256
	global_load_dwordx4 v[160:163], v[212:213], off offset:256
	v_addc_co_u32_e32 v129, vcc, 0, v215, vcc
	v_add_co_u32_e32 v130, vcc, s57, v212
	s_cmp_lg_u32 s72, 3
	s_nop 0
	v_addc_co_u32_e32 v131, vcc, 0, v213, vcc
	v_lshl_add_u64 v[242:243], v[128:129], 0, v[240:241]
	global_load_dword v244, v[242:243], off
	global_load_dwordx4 v[156:159], v[128:129], off
	v_lshl_add_u64 v[242:243], v[128:129], 0, v[240:241]
	global_load_dword v244, v[242:243], off offset:256
	global_load_dwordx4 v[140:143], v[128:129], off offset:256
	v_lshl_add_u64 v[242:243], v[130:131], 0, v[240:241]
	global_load_dword v244, v[242:243], off
	global_load_dwordx4 v[148:151], v[130:131], off
	v_lshl_add_u64 v[242:243], v[130:131], 0, v[240:241]
	global_load_dword v244, v[242:243], off offset:256
	global_load_dwordx4 v[136:139], v[130:131], off offset:256
	v_add_co_u32_e32 v128, vcc, s58, v214
	s_nop 1
	v_addc_co_u32_e32 v129, vcc, 0, v215, vcc
	v_add_co_u32_e32 v130, vcc, s58, v212
	s_nop 1
	v_addc_co_u32_e32 v131, vcc, 0, v213, vcc
	v_lshl_add_u64 v[242:243], v[128:129], 0, v[240:241]
	global_load_dword v244, v[242:243], off
	global_load_dwordx4 v[188:191], v[128:129], off
	v_lshl_add_u64 v[242:243], v[128:129], 0, v[240:241]
	global_load_dword v244, v[242:243], off offset:256
	global_load_dwordx4 v[172:175], v[128:129], off offset:256
	v_lshl_add_u64 v[242:243], v[130:131], 0, v[240:241]
	global_load_dword v244, v[242:243], off
	global_load_dwordx4 v[184:187], v[130:131], off
	v_lshl_add_u64 v[242:243], v[130:131], 0, v[240:241]
	global_load_dword v244, v[242:243], off offset:256
	global_load_dwordx4 v[168:171], v[130:131], off offset:256
	v_add_co_u32_e32 v128, vcc, s59, v214
	s_nop 1
	v_addc_co_u32_e32 v129, vcc, 0, v215, vcc
	v_add_co_u32_e32 v130, vcc, s59, v212
	s_nop 1
	v_addc_co_u32_e32 v131, vcc, 0, v213, vcc
	v_lshl_add_u64 v[242:243], v[128:129], 0, v[240:241]
	global_load_dword v244, v[242:243], off
	global_load_dwordx4 v[152:155], v[128:129], off
	v_lshl_add_u64 v[242:243], v[128:129], 0, v[240:241]
	global_load_dword v244, v[242:243], off offset:256
	global_load_dwordx4 v[132:135], v[128:129], off offset:256
	v_lshl_add_u64 v[242:243], v[130:131], 0, v[240:241]
	global_load_dword v244, v[242:243], off
	global_load_dwordx4 v[144:147], v[130:131], off
	s_nop 0
	v_lshl_add_u64 v[242:243], v[130:131], 0, v[240:241]
	global_load_dword v244, v[242:243], off offset:256
	global_load_dwordx4 v[128:131], v[130:131], off offset:256
	s_waitcnt vmcnt(0)
	v_lshlrev_b32_e32 v209, 16, v176
	v_and_b32_e32 v176, 0xffff0000, v176
	v_mul_f32_e32 v176, 0xbfb8aa3b, v176
	v_exp_f32_e32 v176, v176
	v_mul_f32_e32 v209, 0xbfb8aa3b, v209
	v_exp_f32_e32 v209, v209
	v_lshlrev_b32_e32 v221, 16, v180
	v_add_f32_e32 v176, 1.0, v176
	v_and_b32_e32 v180, 0xffff0000, v180
	v_rcp_f32_e32 v225, v176
	v_lshlrev_b32_e32 v176, 16, v177
	v_and_b32_e32 v177, 0xffff0000, v177
	v_add_f32_e32 v209, 1.0, v209
	v_mul_f32_e32 v180, 0xbfb8aa3b, v180
	v_mul_f32_e32 v176, 0xbfb8aa3b, v176
	v_mul_f32_e32 v177, 0xbfb8aa3b, v177
	v_exp_f32_e32 v223, v180
	v_rcp_f32_e32 v224, v209
	v_exp_f32_e32 v180, v176
	v_exp_f32_e32 v209, v177
	v_lshlrev_b32_e32 v176, 16, v181
	v_and_b32_e32 v177, 0xffff0000, v181
	v_mul_f32_e32 v176, 0xbfb8aa3b, v176
	v_mul_f32_e32 v177, 0xbfb8aa3b, v177
	v_exp_f32_e32 v176, v176
	v_add_f32_e32 v180, 1.0, v180
	v_exp_f32_e32 v177, v177
	v_add_f32_e32 v181, 1.0, v209
	v_rcp_f32_e32 v180, v180
	v_rcp_f32_e32 v181, v181
	v_pk_fma_f32 v[176:177], v[210:211], v[176:177], 1.0 op_sel_hi:[0,1,0]
	v_mul_f32_e32 v221, 0xbfb8aa3b, v221
	v_exp_f32_e32 v222, v221
	v_pk_mul_f32 v[176:177], v[180:181], v[176:177]
	v_pk_fma_f32 v[222:223], v[210:211], v[222:223], 1.0 op_sel_hi:[0,1,0]
	v_pk_mul_f32 v[126:127], v[126:127], v[176:177]
	v_lshlrev_b32_e32 v176, 16, v178
	v_and_b32_e32 v178, 0xffff0000, v178
	v_mul_f32_e32 v178, 0xbfb8aa3b, v178
	v_exp_f32_e32 v178, v178
	v_mul_f32_e32 v176, 0xbfb8aa3b, v176
	v_exp_f32_e32 v177, v176
	v_lshlrev_b32_e32 v176, 16, v182
	v_add_f32_e32 v178, 1.0, v178
	v_rcp_f32_e32 v181, v178
	v_lshlrev_b32_e32 v178, 16, v179
	v_and_b32_e32 v179, 0xffff0000, v179
	v_mul_f32_e32 v178, 0xbfb8aa3b, v178
; #define MG_LOAD(B, S) do { _Pragma("unroll") for (int mm = 0; mm < 2; ++mm) _Pragma("unroll") for (int bj = 0; bj < 2; ++bj) { \
;             const size_t o = (size_t)(((B) >> 1) * HALF + (((B) & 1) * 2 + mm) * 16) * IN_DIM + bj * HALF; \
;             gn[S][mm][bj] = *(const u32x4*)(zn + o); gd[S][mm][bj] = *(const u32x4*)(zd + o); } } while (0)
;     __device__ __forceinline__ void operator()(f32x4 (&acc)[2][2][4][2], const Unit& u, int wr, int wc, int fr, int fq) const {
;     ...
;         MG_LOAD(0, 0); MG_LOAD(1, 1); __builtin_amdgcn_sched_barrier(0);
;         MG_APPLY(0, 0); __builtin_amdgcn_sched_barrier(0);
	v_mul_f32_e32 v179, 0xbfb8aa3b, v179
	v_add_f32_e32 v180, 1.0, v177
	v_and_b32_e32 v177, 0xffff0000, v182
	v_exp_f32_e32 v182, v178
	v_exp_f32_e32 v209, v179
	v_mul_f32_e32 v176, 0xbfb8aa3b, v176
	v_mul_f32_e32 v177, 0xbfb8aa3b, v177
	v_exp_f32_e32 v176, v176
	v_exp_f32_e32 v177, v177
	v_lshlrev_b32_e32 v178, 16, v183
	v_and_b32_e32 v179, 0xffff0000, v183
	v_rcp_f32_e32 v180, v180
	v_mul_f32_e32 v178, 0xbfb8aa3b, v178
	v_mul_f32_e32 v179, 0xbfb8aa3b, v179
	v_exp_f32_e32 v178, v178
	v_add_f32_e32 v182, 1.0, v182
	v_exp_f32_e32 v179, v179
	v_add_f32_e32 v183, 1.0, v209
	v_rcp_f32_e32 v182, v182
	v_rcp_f32_e32 v183, v183
	v_pk_fma_f32 v[176:177], v[210:211], v[176:177], 1.0 op_sel_hi:[0,1,0]
	v_pk_mul_f32 v[176:177], v[180:181], v[176:177]
	v_pk_mul_f32 v[222:223], v[224:225], v[222:223]
	v_pk_mul_f32 v[120:121], v[120:121], v[176:177]
	v_pk_fma_f32 v[176:177], v[210:211], v[178:179], 1.0 op_sel_hi:[0,1,0]
	v_pk_mul_f32 v[176:177], v[182:183], v[176:177]
	v_pk_mul_f32 v[124:125], v[124:125], v[222:223]
	v_pk_mul_f32 v[122:123], v[122:123], v[176:177]
	v_lshlrev_b32_e32 v176, 16, v164
	v_and_b32_e32 v164, 0xffff0000, v164
	v_mul_f32_e32 v176, 0xbfb8aa3b, v176
	v_mul_f32_e32 v164, 0xbfb8aa3b, v164
	v_exp_f32_e32 v177, v176
	v_exp_f32_e32 v164, v164
	v_lshlrev_b32_e32 v176, 16, v160
	v_and_b32_e32 v160, 0xffff0000, v160
	v_mul_f32_e32 v160, 0xbfb8aa3b, v160
	v_add_f32_e32 v178, 1.0, v177
	v_exp_f32_e32 v177, v160
	v_add_f32_e32 v160, 1.0, v164
	v_rcp_f32_e32 v179, v160
	v_lshlrev_b32_e32 v160, 16, v165
	v_and_b32_e32 v165, 0xffff0000, v165
	v_mul_f32_e32 v160, 0xbfb8aa3b, v160
	v_mul_f32_e32 v165, 0xbfb8aa3b, v165
	v_exp_f32_e32 v164, v160
	v_exp_f32_e32 v165, v165
	v_lshlrev_b32_e32 v160, 16, v161
	v_and_b32_e32 v161, 0xffff0000, v161
	v_mul_f32_e32 v160, 0xbfb8aa3b, v160
	v_mul_f32_e32 v161, 0xbfb8aa3b, v161
	v_exp_f32_e32 v160, v160
	v_add_f32_e32 v164, 1.0, v164
	v_exp_f32_e32 v161, v161
	v_add_f32_e32 v165, 1.0, v165
	v_rcp_f32_e32 v164, v164
	v_rcp_f32_e32 v165, v165
	v_pk_fma_f32 v[160:161], v[210:211], v[160:161], 1.0 op_sel_hi:[0,1,0]
	v_mul_f32_e32 v176, 0xbfb8aa3b, v176
	v_exp_f32_e32 v176, v176
	v_pk_mul_f32 v[160:161], v[164:165], v[160:161]
	v_rcp_f32_e32 v178, v178
	v_pk_mul_f32 v[94:95], v[94:95], v[160:161]
	v_lshlrev_b32_e32 v160, 16, v166
	v_mul_f32_e32 v160, 0xbfb8aa3b, v160
	v_exp_f32_e32 v161, v160
	v_lshlrev_b32_e32 v160, 16, v162
	v_mul_f32_e32 v160, 0xbfb8aa3b, v160
	v_exp_f32_e32 v160, v160
	v_add_f32_e32 v164, 1.0, v161
	v_and_b32_e32 v161, 0xffff0000, v162
	v_and_b32_e32 v162, 0xffff0000, v166
	v_mul_f32_e32 v162, 0xbfb8aa3b, v162
	v_exp_f32_e32 v162, v162
	v_mul_f32_e32 v161, 0xbfb8aa3b, v161
	v_exp_f32_e32 v161, v161
	v_rcp_f32_e32 v164, v164
	v_add_f32_e32 v162, 1.0, v162
	v_rcp_f32_e32 v165, v162
	v_lshlrev_b32_e32 v162, 16, v167
	v_and_b32_e32 v167, 0xffff0000, v167
	v_mul_f32_e32 v162, 0xbfb8aa3b, v162
	v_mul_f32_e32 v167, 0xbfb8aa3b, v167
	v_exp_f32_e32 v166, v162
	v_exp_f32_e32 v167, v167
	v_lshlrev_b32_e32 v162, 16, v163
	v_and_b32_e32 v163, 0xffff0000, v163
	v_mul_f32_e32 v162, 0xbfb8aa3b, v162
	v_mul_f32_e32 v163, 0xbfb8aa3b, v163
	v_exp_f32_e32 v162, v162
	v_add_f32_e32 v166, 1.0, v166
	v_exp_f32_e32 v163, v163
	v_add_f32_e32 v167, 1.0, v167
	v_rcp_f32_e32 v166, v166
	v_rcp_f32_e32 v167, v167
	v_pk_fma_f32 v[160:161], v[210:211], v[160:161], 1.0 op_sel_hi:[0,1,0]
	v_pk_mul_f32 v[160:161], v[164:165], v[160:161]
	v_pk_fma_f32 v[176:177], v[210:211], v[176:177], 1.0 op_sel_hi:[0,1,0]
	v_pk_mul_f32 v[88:89], v[88:89], v[160:161]
	v_pk_fma_f32 v[160:161], v[210:211], v[162:163], 1.0 op_sel_hi:[0,1,0]
	v_pk_mul_f32 v[160:161], v[166:167], v[160:161]
	v_pk_mul_f32 v[176:177], v[178:179], v[176:177]
	v_pk_mul_f32 v[90:91], v[90:91], v[160:161]
	v_lshlrev_b32_e32 v160, 16, v156
	v_and_b32_e32 v156, 0xffff0000, v156
	v_mul_f32_e32 v160, 0xbfb8aa3b, v160
	v_mul_f32_e32 v156, 0xbfb8aa3b, v156
	v_exp_f32_e32 v161, v160
	v_exp_f32_e32 v156, v156
	v_lshlrev_b32_e32 v160, 16, v148
	v_and_b32_e32 v148, 0xffff0000, v148
	v_mul_f32_e32 v148, 0xbfb8aa3b, v148
	v_add_f32_e32 v162, 1.0, v161
	v_exp_f32_e32 v161, v148
	v_add_f32_e32 v148, 1.0, v156
	v_rcp_f32_e32 v163, v148
	v_lshlrev_b32_e32 v148, 16, v157
	v_and_b32_e32 v157, 0xffff0000, v157
	v_mul_f32_e32 v148, 0xbfb8aa3b, v148
	v_mul_f32_e32 v157, 0xbfb8aa3b, v157
	v_exp_f32_e32 v156, v148
	v_exp_f32_e32 v157, v157
	v_lshlrev_b32_e32 v148, 16, v149
	v_and_b32_e32 v149, 0xffff0000, v149
	v_mul_f32_e32 v148, 0xbfb8aa3b, v148
	v_mul_f32_e32 v149, 0xbfb8aa3b, v149
	v_exp_f32_e32 v148, v148
	v_add_f32_e32 v156, 1.0, v156
	v_exp_f32_e32 v149, v149
	v_add_f32_e32 v157, 1.0, v157
	v_rcp_f32_e32 v156, v156
	v_rcp_f32_e32 v157, v157
	v_pk_fma_f32 v[148:149], v[210:211], v[148:149], 1.0 op_sel_hi:[0,1,0]
	v_mul_f32_e32 v160, 0xbfb8aa3b, v160
	v_exp_f32_e32 v160, v160
	v_pk_mul_f32 v[148:149], v[156:157], v[148:149]
	v_rcp_f32_e32 v162, v162
	v_pk_mul_f32 v[118:119], v[118:119], v[148:149]
	v_lshlrev_b32_e32 v148, 16, v158
	v_mul_f32_e32 v148, 0xbfb8aa3b, v148
	v_exp_f32_e32 v149, v148
	v_lshlrev_b32_e32 v148, 16, v150
	v_mul_f32_e32 v148, 0xbfb8aa3b, v148
	v_exp_f32_e32 v148, v148
	v_add_f32_e32 v156, 1.0, v149
	v_and_b32_e32 v149, 0xffff0000, v150
	v_and_b32_e32 v150, 0xffff0000, v158
	v_mul_f32_e32 v150, 0xbfb8aa3b, v150
	v_exp_f32_e32 v150, v150
	v_mul_f32_e32 v149, 0xbfb8aa3b, v149
	v_exp_f32_e32 v149, v149
	v_rcp_f32_e32 v156, v156
	v_add_f32_e32 v150, 1.0, v150
	v_rcp_f32_e32 v157, v150
	v_lshlrev_b32_e32 v150, 16, v159
	v_and_b32_e32 v159, 0xffff0000, v159
	v_mul_f32_e32 v150, 0xbfb8aa3b, v150
	v_mul_f32_e32 v159, 0xbfb8aa3b, v159
	v_exp_f32_e32 v158, v150
	v_exp_f32_e32 v159, v159
; #define MG_LOAD(B, S) do { _Pragma("unroll") for (int mm = 0; mm < 2; ++mm) _Pragma("unroll") for (int bj = 0; bj < 2; ++bj) { \
;             const size_t o = (size_t)(((B) >> 1) * HALF + (((B) & 1) * 2 + mm) * 16) * IN_DIM + bj * HALF; \
;             gn[S][mm][bj] = *(const u32x4*)(zn + o); gd[S][mm][bj] = *(const u32x4*)(zd + o); } } while (0)
;     __device__ __forceinline__ void operator()(f32x4 (&acc)[2][2][4][2], const Unit& u, int wr, int wc, int fr, int fq) const {
;     ...
;         MG_LOAD(0, 0); MG_LOAD(1, 1); __builtin_amdgcn_sched_barrier(0);
;         MG_APPLY(0, 0); __builtin_amdgcn_sched_barrier(0);
;         MG_LOAD(2, 0); __builtin_amdgcn_sched_barrier(0);
;         MG_APPLY(1, 1); __builtin_amdgcn_sched_barrier(0);
	v_lshlrev_b32_e32 v150, 16, v151
	v_and_b32_e32 v151, 0xffff0000, v151
	v_mul_f32_e32 v150, 0xbfb8aa3b, v150
	v_mul_f32_e32 v151, 0xbfb8aa3b, v151
	v_exp_f32_e32 v150, v150
	v_add_f32_e32 v158, 1.0, v158
	v_exp_f32_e32 v151, v151
	v_add_f32_e32 v159, 1.0, v159
	v_rcp_f32_e32 v158, v158
	v_rcp_f32_e32 v159, v159
	v_pk_fma_f32 v[148:149], v[210:211], v[148:149], 1.0 op_sel_hi:[0,1,0]
	v_pk_mul_f32 v[148:149], v[156:157], v[148:149]
	v_pk_fma_f32 v[160:161], v[210:211], v[160:161], 1.0 op_sel_hi:[0,1,0]
	v_pk_mul_f32 v[112:113], v[112:113], v[148:149]
	v_pk_fma_f32 v[148:149], v[210:211], v[150:151], 1.0 op_sel_hi:[0,1,0]
	v_pk_mul_f32 v[148:149], v[158:159], v[148:149]
	v_pk_mul_f32 v[160:161], v[162:163], v[160:161]
	v_pk_mul_f32 v[114:115], v[114:115], v[148:149]
	v_lshlrev_b32_e32 v148, 16, v140
	v_and_b32_e32 v140, 0xffff0000, v140
	v_mul_f32_e32 v148, 0xbfb8aa3b, v148
	v_mul_f32_e32 v140, 0xbfb8aa3b, v140
	v_exp_f32_e32 v149, v148
	v_exp_f32_e32 v140, v140
	v_lshlrev_b32_e32 v148, 16, v136
	v_and_b32_e32 v136, 0xffff0000, v136
	v_mul_f32_e32 v136, 0xbfb8aa3b, v136
	v_add_f32_e32 v150, 1.0, v149
	v_exp_f32_e32 v149, v136
	v_add_f32_e32 v136, 1.0, v140
	v_rcp_f32_e32 v151, v136
	v_lshlrev_b32_e32 v136, 16, v141
	v_and_b32_e32 v141, 0xffff0000, v141
	v_mul_f32_e32 v136, 0xbfb8aa3b, v136
	v_mul_f32_e32 v141, 0xbfb8aa3b, v141
	v_exp_f32_e32 v140, v136
	v_exp_f32_e32 v141, v141
	v_lshlrev_b32_e32 v136, 16, v137
	v_and_b32_e32 v137, 0xffff0000, v137
	v_mul_f32_e32 v136, 0xbfb8aa3b, v136
	v_mul_f32_e32 v137, 0xbfb8aa3b, v137
	v_exp_f32_e32 v136, v136
	v_add_f32_e32 v140, 1.0, v140
	v_exp_f32_e32 v137, v137
	v_add_f32_e32 v141, 1.0, v141
	v_rcp_f32_e32 v140, v140
	v_rcp_f32_e32 v141, v141
	v_pk_fma_f32 v[136:137], v[210:211], v[136:137], 1.0 op_sel_hi:[0,1,0]
	v_mul_f32_e32 v148, 0xbfb8aa3b, v148
	v_exp_f32_e32 v148, v148
	v_pk_mul_f32 v[136:137], v[140:141], v[136:137]
	v_rcp_f32_e32 v150, v150
	v_pk_mul_f32 v[86:87], v[86:87], v[136:137]
	v_lshlrev_b32_e32 v136, 16, v142
	v_mul_f32_e32 v136, 0xbfb8aa3b, v136
	v_exp_f32_e32 v137, v136
	v_lshlrev_b32_e32 v136, 16, v138
	v_mul_f32_e32 v136, 0xbfb8aa3b, v136
	v_exp_f32_e32 v136, v136
	v_add_f32_e32 v140, 1.0, v137
	v_and_b32_e32 v137, 0xffff0000, v138
	v_and_b32_e32 v138, 0xffff0000, v142
	v_mul_f32_e32 v138, 0xbfb8aa3b, v138
	v_exp_f32_e32 v138, v138
	v_mul_f32_e32 v137, 0xbfb8aa3b, v137
	v_exp_f32_e32 v137, v137
	v_rcp_f32_e32 v140, v140
	v_add_f32_e32 v138, 1.0, v138
	v_rcp_f32_e32 v141, v138
	v_lshlrev_b32_e32 v138, 16, v143
	v_and_b32_e32 v143, 0xffff0000, v143
	v_mul_f32_e32 v138, 0xbfb8aa3b, v138
	v_mul_f32_e32 v143, 0xbfb8aa3b, v143
	v_exp_f32_e32 v142, v138
	v_exp_f32_e32 v143, v143
	v_lshlrev_b32_e32 v138, 16, v139
	v_and_b32_e32 v139, 0xffff0000, v139
	v_mul_f32_e32 v138, 0xbfb8aa3b, v138
	v_mul_f32_e32 v139, 0xbfb8aa3b, v139
	v_exp_f32_e32 v138, v138
	v_add_f32_e32 v142, 1.0, v142
	v_exp_f32_e32 v139, v139
	v_add_f32_e32 v143, 1.0, v143
	v_rcp_f32_e32 v142, v142
	v_rcp_f32_e32 v143, v143
	v_pk_fma_f32 v[136:137], v[210:211], v[136:137], 1.0 op_sel_hi:[0,1,0]
	v_pk_mul_f32 v[136:137], v[140:141], v[136:137]
	v_pk_fma_f32 v[148:149], v[210:211], v[148:149], 1.0 op_sel_hi:[0,1,0]
	v_pk_mul_f32 v[80:81], v[80:81], v[136:137]
	v_pk_fma_f32 v[136:137], v[210:211], v[138:139], 1.0 op_sel_hi:[0,1,0]
	v_pk_mul_f32 v[148:149], v[150:151], v[148:149]
	v_pk_mul_f32 v[136:137], v[142:143], v[136:137]
	v_pk_mul_f32 v[92:93], v[92:93], v[176:177]
	v_pk_mul_f32 v[116:117], v[116:117], v[160:161]
	v_pk_mul_f32 v[84:85], v[84:85], v[148:149]
	v_pk_mul_f32 v[82:83], v[82:83], v[136:137]
	v_add_co_u32_e32 v136, vcc, s60, v214
	s_nop 1
	v_addc_co_u32_e32 v137, vcc, 0, v215, vcc
	v_add_co_u32_e32 v138, vcc, s60, v212
	s_nop 1
	v_addc_co_u32_e32 v139, vcc, 0, v213, vcc
	global_load_dwordx4 v[176:179], v[136:137], off
	global_load_dwordx4 v[164:167], v[136:137], off offset:256
	global_load_dwordx4 v[180:183], v[138:139], off
	global_load_dwordx4 v[160:163], v[138:139], off offset:256
	v_add_co_u32_e32 v136, vcc, s61, v214
	s_nop 1
	v_addc_co_u32_e32 v137, vcc, 0, v215, vcc
	v_add_co_u32_e32 v138, vcc, s61, v212
	s_nop 1
	v_addc_co_u32_e32 v139, vcc, 0, v213, vcc
	global_load_dwordx4 v[148:151], v[136:137], off
	global_load_dwordx4 v[140:143], v[136:137], off offset:256
	global_load_dwordx4 v[156:159], v[138:139], off
	s_nop 0
	global_load_dwordx4 v[136:139], v[138:139], off offset:256
	v_lshlrev_b32_e32 v209, 16, v188
	v_and_b32_e32 v188, 0xffff0000, v188
	v_mul_f32_e32 v188, 0xbfb8aa3b, v188
	v_exp_f32_e32 v188, v188
	v_lshlrev_b32_e32 v221, 16, v184
	v_and_b32_e32 v184, 0xffff0000, v184
	v_mul_f32_e32 v184, 0xbfb8aa3b, v184
	v_exp_f32_e32 v223, v184
	v_add_f32_e32 v184, 1.0, v188
	v_rcp_f32_e32 v225, v184
	v_lshlrev_b32_e32 v184, 16, v189
	v_and_b32_e32 v189, 0xffff0000, v189
	v_mul_f32_e32 v184, 0xbfb8aa3b, v184
	v_mul_f32_e32 v189, 0xbfb8aa3b, v189
	v_exp_f32_e32 v188, v184
	v_exp_f32_e32 v189, v189
	v_lshlrev_b32_e32 v184, 16, v185
	v_and_b32_e32 v185, 0xffff0000, v185
	v_mul_f32_e32 v184, 0xbfb8aa3b, v184
	v_mul_f32_e32 v185, 0xbfb8aa3b, v185
	v_exp_f32_e32 v184, v184
	v_add_f32_e32 v188, 1.0, v188
	v_exp_f32_e32 v185, v185
	v_add_f32_e32 v189, 1.0, v189
	v_rcp_f32_e32 v188, v188
	v_rcp_f32_e32 v189, v189
	v_pk_fma_f32 v[184:185], v[210:211], v[184:185], 1.0 op_sel_hi:[0,1,0]
	v_mul_f32_e32 v209, 0xbfb8aa3b, v209
	v_exp_f32_e32 v209, v209
	v_pk_mul_f32 v[184:185], v[188:189], v[184:185]
	v_mul_f32_e32 v221, 0xbfb8aa3b, v221
	v_pk_mul_f32 v[110:111], v[110:111], v[184:185]
	v_lshlrev_b32_e32 v184, 16, v190
	v_mul_f32_e32 v184, 0xbfb8aa3b, v184
	v_exp_f32_e32 v185, v184
	v_lshlrev_b32_e32 v184, 16, v186
; #define MG_LOAD(B, S) do { _Pragma("unroll") for (int mm = 0; mm < 2; ++mm) _Pragma("unroll") for (int bj = 0; bj < 2; ++bj) { \
;             const size_t o = (size_t)(((B) >> 1) * HALF + (((B) & 1) * 2 + mm) * 16) * IN_DIM + bj * HALF; \
;             gn[S][mm][bj] = *(const u32x4*)(zn + o); gd[S][mm][bj] = *(const u32x4*)(zd + o); } } while (0)
;     __device__ __forceinline__ void operator()(f32x4 (&acc)[2][2][4][2], const Unit& u, int wr, int wc, int fr, int fq) const {
;     ...
;         MG_LOAD(0, 0); MG_LOAD(1, 1); __builtin_amdgcn_sched_barrier(0);
;         MG_APPLY(0, 0); __builtin_amdgcn_sched_barrier(0);
;         MG_LOAD(2, 0); __builtin_amdgcn_sched_barrier(0);
;         MG_APPLY(1, 1); __builtin_amdgcn_sched_barrier(0);
	v_mul_f32_e32 v184, 0xbfb8aa3b, v184
	v_exp_f32_e32 v184, v184
	v_add_f32_e32 v188, 1.0, v185
	v_and_b32_e32 v185, 0xffff0000, v186
	v_and_b32_e32 v186, 0xffff0000, v190
	v_mul_f32_e32 v186, 0xbfb8aa3b, v186
	v_exp_f32_e32 v186, v186
	v_mul_f32_e32 v185, 0xbfb8aa3b, v185
	v_exp_f32_e32 v185, v185
	v_rcp_f32_e32 v188, v188
	v_add_f32_e32 v186, 1.0, v186
	v_rcp_f32_e32 v189, v186
	v_lshlrev_b32_e32 v186, 16, v191
	v_and_b32_e32 v191, 0xffff0000, v191
	v_mul_f32_e32 v186, 0xbfb8aa3b, v186
	v_mul_f32_e32 v191, 0xbfb8aa3b, v191
	v_exp_f32_e32 v190, v186
	v_exp_f32_e32 v191, v191
	v_lshlrev_b32_e32 v186, 16, v187
	v_and_b32_e32 v187, 0xffff0000, v187
	v_mul_f32_e32 v186, 0xbfb8aa3b, v186
	v_mul_f32_e32 v187, 0xbfb8aa3b, v187
	v_exp_f32_e32 v186, v186
	v_add_f32_e32 v190, 1.0, v190
	v_exp_f32_e32 v187, v187
	v_add_f32_e32 v191, 1.0, v191
	v_rcp_f32_e32 v190, v190
	v_rcp_f32_e32 v191, v191
	v_pk_fma_f32 v[184:185], v[210:211], v[184:185], 1.0 op_sel_hi:[0,1,0]
	v_pk_mul_f32 v[184:185], v[188:189], v[184:185]
	v_exp_f32_e32 v222, v221
	v_pk_mul_f32 v[104:105], v[104:105], v[184:185]
	v_pk_fma_f32 v[184:185], v[210:211], v[186:187], 1.0 op_sel_hi:[0,1,0]
	v_pk_mul_f32 v[184:185], v[190:191], v[184:185]
	v_add_f32_e32 v209, 1.0, v209
	v_pk_mul_f32 v[106:107], v[106:107], v[184:185]
	v_lshlrev_b32_e32 v184, 16, v172
	v_and_b32_e32 v172, 0xffff0000, v172
	v_mul_f32_e32 v184, 0xbfb8aa3b, v184
	v_mul_f32_e32 v172, 0xbfb8aa3b, v172
	v_exp_f32_e32 v185, v184
	v_exp_f32_e32 v172, v172
	v_lshlrev_b32_e32 v184, 16, v168
	v_and_b32_e32 v168, 0xffff0000, v168
	v_mul_f32_e32 v168, 0xbfb8aa3b, v168
	v_add_f32_e32 v186, 1.0, v185
	v_exp_f32_e32 v185, v168
	v_add_f32_e32 v168, 1.0, v172
	v_rcp_f32_e32 v187, v168
	v_lshlrev_b32_e32 v168, 16, v173
	v_and_b32_e32 v173, 0xffff0000, v173
	v_mul_f32_e32 v168, 0xbfb8aa3b, v168
	v_mul_f32_e32 v173, 0xbfb8aa3b, v173
	v_exp_f32_e32 v172, v168
	v_exp_f32_e32 v173, v173
	v_lshlrev_b32_e32 v168, 16, v169
	v_and_b32_e32 v169, 0xffff0000, v169
	v_mul_f32_e32 v168, 0xbfb8aa3b, v168
	v_mul_f32_e32 v169, 0xbfb8aa3b, v169
	v_exp_f32_e32 v168, v168
	v_add_f32_e32 v172, 1.0, v172
	v_exp_f32_e32 v169, v169
	v_add_f32_e32 v173, 1.0, v173
	v_rcp_f32_e32 v172, v172
	v_rcp_f32_e32 v173, v173
	v_pk_fma_f32 v[168:169], v[210:211], v[168:169], 1.0 op_sel_hi:[0,1,0]
	v_mul_f32_e32 v184, 0xbfb8aa3b, v184
	v_exp_f32_e32 v184, v184
	v_pk_mul_f32 v[168:169], v[172:173], v[168:169]
	v_rcp_f32_e32 v224, v209
	v_pk_mul_f32 v[78:79], v[78:79], v[168:169]
	v_lshlrev_b32_e32 v168, 16, v174
	v_mul_f32_e32 v168, 0xbfb8aa3b, v168
	v_exp_f32_e32 v169, v168
	v_lshlrev_b32_e32 v168, 16, v170
	v_mul_f32_e32 v168, 0xbfb8aa3b, v168
	v_exp_f32_e32 v168, v168
	v_add_f32_e32 v172, 1.0, v169
	v_and_b32_e32 v169, 0xffff0000, v170
	v_and_b32_e32 v170, 0xffff0000, v174
	v_mul_f32_e32 v170, 0xbfb8aa3b, v170
	v_exp_f32_e32 v170, v170
	v_mul_f32_e32 v169, 0xbfb8aa3b, v169
	v_exp_f32_e32 v169, v169
	v_rcp_f32_e32 v172, v172
	v_add_f32_e32 v170, 1.0, v170
	v_rcp_f32_e32 v173, v170
	v_lshlrev_b32_e32 v170, 16, v175
	v_and_b32_e32 v175, 0xffff0000, v175
	v_mul_f32_e32 v170, 0xbfb8aa3b, v170
	v_mul_f32_e32 v175, 0xbfb8aa3b, v175
	v_exp_f32_e32 v174, v170
	v_exp_f32_e32 v175, v175
	v_lshlrev_b32_e32 v170, 16, v171
	v_and_b32_e32 v171, 0xffff0000, v171
	v_mul_f32_e32 v170, 0xbfb8aa3b, v170
	v_mul_f32_e32 v171, 0xbfb8aa3b, v171
	v_exp_f32_e32 v170, v170
	v_add_f32_e32 v174, 1.0, v174
	v_exp_f32_e32 v171, v171
	v_add_f32_e32 v175, 1.0, v175
	v_rcp_f32_e32 v174, v174
	v_rcp_f32_e32 v175, v175
	v_pk_fma_f32 v[168:169], v[210:211], v[168:169], 1.0 op_sel_hi:[0,1,0]
	v_pk_mul_f32 v[168:169], v[172:173], v[168:169]
	v_rcp_f32_e32 v186, v186
	v_pk_mul_f32 v[72:73], v[72:73], v[168:169]
	v_pk_fma_f32 v[168:169], v[210:211], v[170:171], 1.0 op_sel_hi:[0,1,0]
	v_pk_mul_f32 v[168:169], v[174:175], v[168:169]
	v_pk_fma_f32 v[222:223], v[210:211], v[222:223], 1.0 op_sel_hi:[0,1,0]
	v_pk_mul_f32 v[74:75], v[74:75], v[168:169]
	v_lshlrev_b32_e32 v168, 16, v152
	v_and_b32_e32 v152, 0xffff0000, v152
	v_mul_f32_e32 v168, 0xbfb8aa3b, v168
	v_mul_f32_e32 v152, 0xbfb8aa3b, v152
	v_exp_f32_e32 v169, v168
	v_exp_f32_e32 v152, v152
	v_lshlrev_b32_e32 v168, 16, v144
	v_and_b32_e32 v144, 0xffff0000, v144
	v_mul_f32_e32 v144, 0xbfb8aa3b, v144
	v_add_f32_e32 v170, 1.0, v169
	v_exp_f32_e32 v169, v144
	v_add_f32_e32 v144, 1.0, v152
	v_rcp_f32_e32 v171, v144
	v_lshlrev_b32_e32 v144, 16, v153
	v_and_b32_e32 v153, 0xffff0000, v153
	v_mul_f32_e32 v144, 0xbfb8aa3b, v144
	v_mul_f32_e32 v153, 0xbfb8aa3b, v153
	v_exp_f32_e32 v152, v144
	v_exp_f32_e32 v153, v153
	v_lshlrev_b32_e32 v144, 16, v145
	v_and_b32_e32 v145, 0xffff0000, v145
	v_mul_f32_e32 v144, 0xbfb8aa3b, v144
	v_mul_f32_e32 v145, 0xbfb8aa3b, v145
	v_exp_f32_e32 v144, v144
	v_add_f32_e32 v152, 1.0, v152
	v_exp_f32_e32 v145, v145
	v_add_f32_e32 v153, 1.0, v153
	v_rcp_f32_e32 v152, v152
	v_rcp_f32_e32 v153, v153
	v_pk_fma_f32 v[144:145], v[210:211], v[144:145], 1.0 op_sel_hi:[0,1,0]
	v_mul_f32_e32 v168, 0xbfb8aa3b, v168
	v_exp_f32_e32 v168, v168
	v_pk_mul_f32 v[144:145], v[152:153], v[144:145]
	v_rcp_f32_e32 v170, v170
	v_pk_mul_f32 v[102:103], v[102:103], v[144:145]
	v_lshlrev_b32_e32 v144, 16, v154
	v_mul_f32_e32 v144, 0xbfb8aa3b, v144
	v_exp_f32_e32 v145, v144
	v_lshlrev_b32_e32 v144, 16, v146
	v_mul_f32_e32 v144, 0xbfb8aa3b, v144
	v_exp_f32_e32 v144, v144
	v_add_f32_e32 v152, 1.0, v145
	v_and_b32_e32 v145, 0xffff0000, v146
	v_and_b32_e32 v146, 0xffff0000, v154
	v_mul_f32_e32 v146, 0xbfb8aa3b, v146
	v_exp_f32_e32 v146, v146
	v_mul_f32_e32 v145, 0xbfb8aa3b, v145
	v_exp_f32_e32 v145, v145
	v_rcp_f32_e32 v152, v152
	v_add_f32_e32 v146, 1.0, v146
; #define MG_LOAD(B, S) do { _Pragma("unroll") for (int mm = 0; mm < 2; ++mm) _Pragma("unroll") for (int bj = 0; bj < 2; ++bj) { \
;             const size_t o = (size_t)(((B) >> 1) * HALF + (((B) & 1) * 2 + mm) * 16) * IN_DIM + bj * HALF; \
;             gn[S][mm][bj] = *(const u32x4*)(zn + o); gd[S][mm][bj] = *(const u32x4*)(zd + o); } } while (0)
;     __device__ __forceinline__ void operator()(f32x4 (&acc)[2][2][4][2], const Unit& u, int wr, int wc, int fr, int fq) const {
;     ...
;         MG_LOAD(0, 0); MG_LOAD(1, 1); __builtin_amdgcn_sched_barrier(0);
;         MG_APPLY(0, 0); __builtin_amdgcn_sched_barrier(0);
;         MG_LOAD(2, 0); __builtin_amdgcn_sched_barrier(0);
;         MG_APPLY(1, 1); __builtin_amdgcn_sched_barrier(0);
;         MG_LOAD(3, 1); __builtin_amdgcn_sched_barrier(0);
;         MG_APPLY(2, 0); __builtin_amdgcn_sched_barrier(0);
	v_rcp_f32_e32 v153, v146
	v_lshlrev_b32_e32 v146, 16, v155
	v_and_b32_e32 v155, 0xffff0000, v155
	v_mul_f32_e32 v146, 0xbfb8aa3b, v146
	v_mul_f32_e32 v155, 0xbfb8aa3b, v155
	v_exp_f32_e32 v154, v146
	v_exp_f32_e32 v155, v155
	v_lshlrev_b32_e32 v146, 16, v147
	v_and_b32_e32 v147, 0xffff0000, v147
	v_mul_f32_e32 v146, 0xbfb8aa3b, v146
	v_mul_f32_e32 v147, 0xbfb8aa3b, v147
	v_exp_f32_e32 v146, v146
	v_add_f32_e32 v154, 1.0, v154
	v_exp_f32_e32 v147, v147
	v_add_f32_e32 v155, 1.0, v155
	v_rcp_f32_e32 v154, v154
	v_rcp_f32_e32 v155, v155
	v_pk_fma_f32 v[144:145], v[210:211], v[144:145], 1.0 op_sel_hi:[0,1,0]
	v_pk_mul_f32 v[144:145], v[152:153], v[144:145]
	v_pk_fma_f32 v[184:185], v[210:211], v[184:185], 1.0 op_sel_hi:[0,1,0]
	v_pk_mul_f32 v[96:97], v[96:97], v[144:145]
	v_pk_fma_f32 v[144:145], v[210:211], v[146:147], 1.0 op_sel_hi:[0,1,0]
	v_pk_mul_f32 v[144:145], v[154:155], v[144:145]
	v_pk_fma_f32 v[168:169], v[210:211], v[168:169], 1.0 op_sel_hi:[0,1,0]
	v_pk_mul_f32 v[98:99], v[98:99], v[144:145]
	v_lshlrev_b32_e32 v144, 16, v132
	v_and_b32_e32 v132, 0xffff0000, v132
	v_mul_f32_e32 v144, 0xbfb8aa3b, v144
	v_mul_f32_e32 v132, 0xbfb8aa3b, v132
	v_exp_f32_e32 v145, v144
	v_exp_f32_e32 v132, v132
	v_lshlrev_b32_e32 v144, 16, v128
	v_and_b32_e32 v128, 0xffff0000, v128
	v_mul_f32_e32 v128, 0xbfb8aa3b, v128
	v_add_f32_e32 v146, 1.0, v145
	v_exp_f32_e32 v145, v128
	v_add_f32_e32 v128, 1.0, v132
	v_rcp_f32_e32 v147, v128
	v_lshlrev_b32_e32 v128, 16, v133
	v_and_b32_e32 v133, 0xffff0000, v133
	v_mul_f32_e32 v128, 0xbfb8aa3b, v128
	v_mul_f32_e32 v133, 0xbfb8aa3b, v133
	v_exp_f32_e32 v132, v128
	v_exp_f32_e32 v133, v133
	v_lshlrev_b32_e32 v128, 16, v129
	v_and_b32_e32 v129, 0xffff0000, v129
	v_mul_f32_e32 v128, 0xbfb8aa3b, v128
	v_mul_f32_e32 v129, 0xbfb8aa3b, v129
	v_exp_f32_e32 v128, v128
	v_add_f32_e32 v132, 1.0, v132
	v_exp_f32_e32 v129, v129
	v_add_f32_e32 v133, 1.0, v133
	v_rcp_f32_e32 v132, v132
	v_rcp_f32_e32 v133, v133
	v_pk_fma_f32 v[128:129], v[210:211], v[128:129], 1.0 op_sel_hi:[0,1,0]
	v_mul_f32_e32 v144, 0xbfb8aa3b, v144
	v_exp_f32_e32 v144, v144
	v_pk_mul_f32 v[128:129], v[132:133], v[128:129]
	v_rcp_f32_e32 v146, v146
	v_pk_mul_f32 v[70:71], v[70:71], v[128:129]
	v_lshlrev_b32_e32 v128, 16, v134
	v_mul_f32_e32 v128, 0xbfb8aa3b, v128
	v_exp_f32_e32 v129, v128
	v_lshlrev_b32_e32 v128, 16, v130
	v_mul_f32_e32 v128, 0xbfb8aa3b, v128
	v_exp_f32_e32 v128, v128
	v_add_f32_e32 v132, 1.0, v129
	v_and_b32_e32 v129, 0xffff0000, v130
	v_and_b32_e32 v130, 0xffff0000, v134
	v_mul_f32_e32 v130, 0xbfb8aa3b, v130
	v_exp_f32_e32 v130, v130
	v_mul_f32_e32 v129, 0xbfb8aa3b, v129
	v_exp_f32_e32 v129, v129
	v_rcp_f32_e32 v132, v132
	v_add_f32_e32 v130, 1.0, v130
	v_rcp_f32_e32 v133, v130
	v_lshlrev_b32_e32 v130, 16, v135
	v_and_b32_e32 v135, 0xffff0000, v135
	v_mul_f32_e32 v130, 0xbfb8aa3b, v130
	v_mul_f32_e32 v135, 0xbfb8aa3b, v135
	v_exp_f32_e32 v134, v130
	v_exp_f32_e32 v135, v135
	v_lshlrev_b32_e32 v130, 16, v131
	v_and_b32_e32 v131, 0xffff0000, v131
	v_mul_f32_e32 v130, 0xbfb8aa3b, v130
	v_mul_f32_e32 v131, 0xbfb8aa3b, v131
	v_exp_f32_e32 v130, v130
	v_add_f32_e32 v134, 1.0, v134
	v_exp_f32_e32 v131, v131
	v_add_f32_e32 v135, 1.0, v135
	v_rcp_f32_e32 v134, v134
	v_rcp_f32_e32 v135, v135
	v_pk_fma_f32 v[128:129], v[210:211], v[128:129], 1.0 op_sel_hi:[0,1,0]
	v_pk_mul_f32 v[128:129], v[132:133], v[128:129]
	v_pk_fma_f32 v[144:145], v[210:211], v[144:145], 1.0 op_sel_hi:[0,1,0]
	v_pk_mul_f32 v[64:65], v[64:65], v[128:129]
	v_pk_fma_f32 v[128:129], v[210:211], v[130:131], 1.0 op_sel_hi:[0,1,0]
	v_pk_mul_f32 v[222:223], v[224:225], v[222:223]
	v_pk_mul_f32 v[184:185], v[186:187], v[184:185]
	v_pk_mul_f32 v[168:169], v[170:171], v[168:169]
	v_pk_mul_f32 v[144:145], v[146:147], v[144:145]
	v_pk_mul_f32 v[128:129], v[134:135], v[128:129]
	v_pk_mul_f32 v[108:109], v[108:109], v[222:223]
	v_pk_mul_f32 v[76:77], v[76:77], v[184:185]
	v_pk_mul_f32 v[100:101], v[100:101], v[168:169]
	v_pk_mul_f32 v[68:69], v[68:69], v[144:145]
	v_pk_mul_f32 v[66:67], v[66:67], v[128:129]
	v_add_co_u32_e32 v128, vcc, s62, v214
	s_nop 1
	v_addc_co_u32_e32 v129, vcc, 0, v215, vcc
	v_add_co_u32_e32 v130, vcc, s62, v212
	s_nop 1
	v_addc_co_u32_e32 v131, vcc, 0, v213, vcc
	global_load_dwordx4 v[184:187], v[128:129], off
	global_load_dwordx4 v[172:175], v[128:129], off offset:256
	global_load_dwordx4 v[188:191], v[130:131], off
	global_load_dwordx4 v[168:171], v[130:131], off offset:256
	v_add_co_u32_e32 v128, vcc, s63, v214
	s_nop 1
	v_addc_co_u32_e32 v129, vcc, 0, v215, vcc
	v_add_co_u32_e32 v130, vcc, s63, v212
	s_nop 1
	v_addc_co_u32_e32 v131, vcc, 0, v213, vcc
	global_load_dwordx4 v[144:147], v[128:129], off
	global_load_dwordx4 v[132:135], v[128:129], off offset:256
	global_load_dwordx4 v[152:155], v[130:131], off
	s_nop 0
	global_load_dwordx4 v[128:131], v[130:131], off offset:256
	s_waitcnt vmcnt(15)
	v_lshlrev_b32_e32 v209, 16, v176
	v_and_b32_e32 v176, 0xffff0000, v176
	v_mul_f32_e32 v176, 0xbfb8aa3b, v176
	v_exp_f32_e32 v176, v176
	v_mul_f32_e32 v209, 0xbfb8aa3b, v209
	v_exp_f32_e32 v209, v209
	s_waitcnt vmcnt(13)
; #define MG_LOAD(B, S) do { _Pragma("unroll") for (int mm = 0; mm < 2; ++mm) _Pragma("unroll") for (int bj = 0; bj < 2; ++bj) { \
;             const size_t o = (size_t)(((B) >> 1) * HALF + (((B) & 1) * 2 + mm) * 16) * IN_DIM + bj * HALF; \
;             gn[S][mm][bj] = *(const u32x4*)(zn + o); gd[S][mm][bj] = *(const u32x4*)(zd + o); } } while (0)
;     __device__ __forceinline__ void operator()(f32x4 (&acc)[2][2][4][2], const Unit& u, int wr, int wc, int fr, int fq) const {
;     ...
;         MG_LOAD(0, 0); MG_LOAD(1, 1); __builtin_amdgcn_sched_barrier(0);
;         MG_APPLY(0, 0); __builtin_amdgcn_sched_barrier(0);
;         MG_LOAD(2, 0); __builtin_amdgcn_sched_barrier(0);
;         MG_APPLY(1, 1); __builtin_amdgcn_sched_barrier(0);
;         MG_LOAD(3, 1); __builtin_amdgcn_sched_barrier(0);
;         MG_APPLY(2, 0); __builtin_amdgcn_sched_barrier(0);
	v_lshlrev_b32_e32 v212, 16, v180
	v_add_f32_e32 v176, 1.0, v176
	v_and_b32_e32 v180, 0xffff0000, v180
	v_rcp_f32_e32 v215, v176
	v_lshlrev_b32_e32 v176, 16, v177
	v_and_b32_e32 v177, 0xffff0000, v177
	v_add_f32_e32 v209, 1.0, v209
	v_mul_f32_e32 v180, 0xbfb8aa3b, v180
	v_mul_f32_e32 v176, 0xbfb8aa3b, v176
	v_mul_f32_e32 v177, 0xbfb8aa3b, v177
	v_exp_f32_e32 v213, v180
	v_rcp_f32_e32 v214, v209
	v_exp_f32_e32 v180, v176
	v_exp_f32_e32 v209, v177
	v_lshlrev_b32_e32 v176, 16, v181
	v_and_b32_e32 v177, 0xffff0000, v181
	v_mul_f32_e32 v176, 0xbfb8aa3b, v176
	v_mul_f32_e32 v177, 0xbfb8aa3b, v177
	v_exp_f32_e32 v176, v176
	v_add_f32_e32 v180, 1.0, v180
	v_exp_f32_e32 v177, v177
	v_add_f32_e32 v181, 1.0, v209
	v_rcp_f32_e32 v180, v180
	v_rcp_f32_e32 v181, v181
	v_pk_fma_f32 v[176:177], v[210:211], v[176:177], 1.0 op_sel_hi:[0,1,0]
	v_mul_f32_e32 v212, 0xbfb8aa3b, v212
	v_exp_f32_e32 v212, v212
	v_pk_mul_f32 v[176:177], v[180:181], v[176:177]
	v_pk_fma_f32 v[212:213], v[210:211], v[212:213], 1.0 op_sel_hi:[0,1,0]
	v_pk_mul_f32 v[62:63], v[62:63], v[176:177]
	v_lshlrev_b32_e32 v176, 16, v178
	v_and_b32_e32 v178, 0xffff0000, v178
	v_mul_f32_e32 v178, 0xbfb8aa3b, v178
	v_exp_f32_e32 v178, v178
	v_mul_f32_e32 v176, 0xbfb8aa3b, v176
	v_exp_f32_e32 v177, v176
	v_lshlrev_b32_e32 v176, 16, v182
	v_add_f32_e32 v178, 1.0, v178
	v_rcp_f32_e32 v181, v178
	v_lshlrev_b32_e32 v178, 16, v179
	v_and_b32_e32 v179, 0xffff0000, v179
	v_mul_f32_e32 v178, 0xbfb8aa3b, v178
	v_mul_f32_e32 v179, 0xbfb8aa3b, v179
	v_add_f32_e32 v180, 1.0, v177
	v_and_b32_e32 v177, 0xffff0000, v182
	v_exp_f32_e32 v182, v178
	v_exp_f32_e32 v209, v179
	v_mul_f32_e32 v176, 0xbfb8aa3b, v176
	v_mul_f32_e32 v177, 0xbfb8aa3b, v177
	v_exp_f32_e32 v176, v176
	v_exp_f32_e32 v177, v177
	v_lshlrev_b32_e32 v178, 16, v183
	v_and_b32_e32 v179, 0xffff0000, v183
	v_rcp_f32_e32 v180, v180
	v_mul_f32_e32 v178, 0xbfb8aa3b, v178
	v_mul_f32_e32 v179, 0xbfb8aa3b, v179
	v_exp_f32_e32 v178, v178
	v_add_f32_e32 v182, 1.0, v182
	v_exp_f32_e32 v179, v179
	v_add_f32_e32 v183, 1.0, v209
	v_rcp_f32_e32 v182, v182
	v_rcp_f32_e32 v183, v183
	v_pk_fma_f32 v[176:177], v[210:211], v[176:177], 1.0 op_sel_hi:[0,1,0]
	v_pk_mul_f32 v[176:177], v[180:181], v[176:177]
	v_pk_mul_f32 v[212:213], v[214:215], v[212:213]
	v_pk_mul_f32 v[56:57], v[56:57], v[176:177]
	v_pk_fma_f32 v[176:177], v[210:211], v[178:179], 1.0 op_sel_hi:[0,1,0]
	v_pk_mul_f32 v[176:177], v[182:183], v[176:177]
	v_pk_mul_f32 v[60:61], v[60:61], v[212:213]
	v_pk_mul_f32 v[58:59], v[58:59], v[176:177]
	v_lshlrev_b32_e32 v176, 16, v164
	v_and_b32_e32 v164, 0xffff0000, v164
	v_mul_f32_e32 v176, 0xbfb8aa3b, v176
	v_mul_f32_e32 v164, 0xbfb8aa3b, v164
	v_exp_f32_e32 v177, v176
	v_exp_f32_e32 v164, v164
	s_waitcnt vmcnt(12)
	v_lshlrev_b32_e32 v176, 16, v160
	v_and_b32_e32 v160, 0xffff0000, v160
	v_mul_f32_e32 v160, 0xbfb8aa3b, v160
	v_add_f32_e32 v178, 1.0, v177
	v_exp_f32_e32 v177, v160
	v_add_f32_e32 v160, 1.0, v164
	v_rcp_f32_e32 v179, v160
	v_lshlrev_b32_e32 v160, 16, v165
	v_and_b32_e32 v165, 0xffff0000, v165
	v_mul_f32_e32 v160, 0xbfb8aa3b, v160
	v_mul_f32_e32 v165, 0xbfb8aa3b, v165
	v_exp_f32_e32 v164, v160
	v_exp_f32_e32 v165, v165
	v_lshlrev_b32_e32 v160, 16, v161
	v_and_b32_e32 v161, 0xffff0000, v161
	v_mul_f32_e32 v160, 0xbfb8aa3b, v160
	v_mul_f32_e32 v161, 0xbfb8aa3b, v161
	v_exp_f32_e32 v160, v160
	v_add_f32_e32 v164, 1.0, v164
	v_exp_f32_e32 v161, v161
	v_add_f32_e32 v165, 1.0, v165
	v_rcp_f32_e32 v164, v164
	v_rcp_f32_e32 v165, v165
	v_pk_fma_f32 v[160:161], v[210:211], v[160:161], 1.0 op_sel_hi:[0,1,0]
	v_mul_f32_e32 v176, 0xbfb8aa3b, v176
	v_exp_f32_e32 v176, v176
	v_pk_mul_f32 v[160:161], v[164:165], v[160:161]
	v_rcp_f32_e32 v178, v178
	v_pk_mul_f32 v[30:31], v[30:31], v[160:161]
	v_lshlrev_b32_e32 v160, 16, v166
	v_mul_f32_e32 v160, 0xbfb8aa3b, v160
	v_exp_f32_e32 v161, v160
	v_lshlrev_b32_e32 v160, 16, v162
	v_mul_f32_e32 v160, 0xbfb8aa3b, v160
	v_exp_f32_e32 v160, v160
	v_add_f32_e32 v164, 1.0, v161
	v_and_b32_e32 v161, 0xffff0000, v162
	v_and_b32_e32 v162, 0xffff0000, v166
	v_mul_f32_e32 v162, 0xbfb8aa3b, v162
	v_exp_f32_e32 v162, v162
	v_mul_f32_e32 v161, 0xbfb8aa3b, v161
	v_exp_f32_e32 v161, v161
	v_rcp_f32_e32 v164, v164
	v_add_f32_e32 v162, 1.0, v162
	v_rcp_f32_e32 v165, v162
	v_lshlrev_b32_e32 v162, 16, v167
	v_and_b32_e32 v167, 0xffff0000, v167
	v_mul_f32_e32 v162, 0xbfb8aa3b, v162
	v_mul_f32_e32 v167, 0xbfb8aa3b, v167
	v_exp_f32_e32 v166, v162
	v_exp_f32_e32 v167, v167
	v_lshlrev_b32_e32 v162, 16, v163
	v_and_b32_e32 v163, 0xffff0000, v163
	v_mul_f32_e32 v162, 0xbfb8aa3b, v162
	v_mul_f32_e32 v163, 0xbfb8aa3b, v163
	v_exp_f32_e32 v162, v162
	v_add_f32_e32 v166, 1.0, v166
	v_exp_f32_e32 v163, v163
	v_add_f32_e32 v167, 1.0, v167
	v_rcp_f32_e32 v166, v166
	v_rcp_f32_e32 v167, v167
	v_pk_fma_f32 v[160:161], v[210:211], v[160:161], 1.0 op_sel_hi:[0,1,0]
	v_pk_mul_f32 v[160:161], v[164:165], v[160:161]
	v_pk_fma_f32 v[176:177], v[210:211], v[176:177], 1.0 op_sel_hi:[0,1,0]
	v_pk_mul_f32 v[24:25], v[24:25], v[160:161]
	v_pk_fma_f32 v[160:161], v[210:211], v[162:163], 1.0 op_sel_hi:[0,1,0]
	v_pk_mul_f32 v[160:161], v[166:167], v[160:161]
	v_pk_mul_f32 v[176:177], v[178:179], v[176:177]
	v_pk_mul_f32 v[26:27], v[26:27], v[160:161]
	s_waitcnt vmcnt(11)
	v_lshlrev_b32_e32 v160, 16, v148
	v_and_b32_e32 v148, 0xffff0000, v148
	v_mul_f32_e32 v148, 0xbfb8aa3b, v148
	v_exp_f32_e32 v148, v148
	v_mul_f32_e32 v160, 0xbfb8aa3b, v160
	v_exp_f32_e32 v161, v160
	s_waitcnt vmcnt(9)
; #define MG_LOAD(B, S) do { _Pragma("unroll") for (int mm = 0; mm < 2; ++mm) _Pragma("unroll") for (int bj = 0; bj < 2; ++bj) { \
;             const size_t o = (size_t)(((B) >> 1) * HALF + (((B) & 1) * 2 + mm) * 16) * IN_DIM + bj * HALF; \
;             gn[S][mm][bj] = *(const u32x4*)(zn + o); gd[S][mm][bj] = *(const u32x4*)(zd + o); } } while (0)
;     __device__ __forceinline__ void operator()(f32x4 (&acc)[2][2][4][2], const Unit& u, int wr, int wc, int fr, int fq) const {
;     ...
;         MG_LOAD(0, 0); MG_LOAD(1, 1); __builtin_amdgcn_sched_barrier(0);
;         MG_APPLY(0, 0); __builtin_amdgcn_sched_barrier(0);
;         MG_LOAD(2, 0); __builtin_amdgcn_sched_barrier(0);
;         MG_APPLY(1, 1); __builtin_amdgcn_sched_barrier(0);
;         MG_LOAD(3, 1); __builtin_amdgcn_sched_barrier(0);
;         MG_APPLY(2, 0); __builtin_amdgcn_sched_barrier(0);
;         MG_APPLY(3, 1); __builtin_amdgcn_sched_barrier(0);
	v_lshlrev_b32_e32 v160, 16, v156
	v_add_f32_e32 v148, 1.0, v148
	v_and_b32_e32 v156, 0xffff0000, v156
	v_rcp_f32_e32 v163, v148
	v_lshlrev_b32_e32 v148, 16, v149
	v_and_b32_e32 v149, 0xffff0000, v149
	v_mul_f32_e32 v156, 0xbfb8aa3b, v156
	v_mul_f32_e32 v148, 0xbfb8aa3b, v148
	v_mul_f32_e32 v149, 0xbfb8aa3b, v149
	v_add_f32_e32 v162, 1.0, v161
	v_exp_f32_e32 v161, v156
	v_exp_f32_e32 v156, v148
	v_exp_f32_e32 v164, v149
	v_lshlrev_b32_e32 v148, 16, v157
	v_and_b32_e32 v149, 0xffff0000, v157
	v_mul_f32_e32 v148, 0xbfb8aa3b, v148
	v_mul_f32_e32 v149, 0xbfb8aa3b, v149
	v_exp_f32_e32 v148, v148
	v_add_f32_e32 v156, 1.0, v156
	v_exp_f32_e32 v149, v149
	v_add_f32_e32 v157, 1.0, v164
	v_rcp_f32_e32 v156, v156
	v_rcp_f32_e32 v157, v157
	v_pk_fma_f32 v[148:149], v[210:211], v[148:149], 1.0 op_sel_hi:[0,1,0]
	v_mul_f32_e32 v160, 0xbfb8aa3b, v160
	v_exp_f32_e32 v160, v160
	v_pk_mul_f32 v[148:149], v[156:157], v[148:149]
	v_rcp_f32_e32 v162, v162
	v_pk_mul_f32 v[54:55], v[54:55], v[148:149]
	v_lshlrev_b32_e32 v148, 16, v150
	v_and_b32_e32 v150, 0xffff0000, v150
	v_mul_f32_e32 v150, 0xbfb8aa3b, v150
	v_exp_f32_e32 v150, v150
	v_mul_f32_e32 v148, 0xbfb8aa3b, v148
	v_exp_f32_e32 v149, v148
	v_pk_fma_f32 v[160:161], v[210:211], v[160:161], 1.0 op_sel_hi:[0,1,0]
	v_add_f32_e32 v150, 1.0, v150
	v_rcp_f32_e32 v157, v150
	v_lshlrev_b32_e32 v150, 16, v151
	v_and_b32_e32 v151, 0xffff0000, v151
	v_pk_mul_f32 v[160:161], v[162:163], v[160:161]
	v_mul_f32_e32 v150, 0xbfb8aa3b, v150
	v_mul_f32_e32 v151, 0xbfb8aa3b, v151
	v_pk_mul_f32 v[52:53], v[52:53], v[160:161]
	v_lshlrev_b32_e32 v148, 16, v158
	v_add_f32_e32 v156, 1.0, v149
	v_and_b32_e32 v149, 0xffff0000, v158
	v_exp_f32_e32 v158, v150
	v_exp_f32_e32 v160, v151
	v_mul_f32_e32 v148, 0xbfb8aa3b, v148
	v_mul_f32_e32 v149, 0xbfb8aa3b, v149
	v_exp_f32_e32 v148, v148
	v_exp_f32_e32 v149, v149
	v_lshlrev_b32_e32 v150, 16, v159
	v_and_b32_e32 v151, 0xffff0000, v159
	v_rcp_f32_e32 v156, v156
	v_mul_f32_e32 v150, 0xbfb8aa3b, v150
	v_mul_f32_e32 v151, 0xbfb8aa3b, v151
	v_exp_f32_e32 v150, v150
	v_add_f32_e32 v158, 1.0, v158
	v_exp_f32_e32 v151, v151
	v_add_f32_e32 v159, 1.0, v160
	v_rcp_f32_e32 v158, v158
	v_rcp_f32_e32 v159, v159
	v_pk_fma_f32 v[148:149], v[210:211], v[148:149], 1.0 op_sel_hi:[0,1,0]
	v_pk_mul_f32 v[148:149], v[156:157], v[148:149]
	v_pk_mul_f32 v[28:29], v[28:29], v[176:177]
	v_pk_mul_f32 v[48:49], v[48:49], v[148:149]
	v_pk_fma_f32 v[148:149], v[210:211], v[150:151], 1.0 op_sel_hi:[0,1,0]
	v_pk_mul_f32 v[148:149], v[158:159], v[148:149]
	s_nop 0
	v_pk_mul_f32 v[50:51], v[50:51], v[148:149]
	v_lshlrev_b32_e32 v148, 16, v140
	v_and_b32_e32 v140, 0xffff0000, v140
	v_mul_f32_e32 v148, 0xbfb8aa3b, v148
	v_mul_f32_e32 v140, 0xbfb8aa3b, v140
	v_exp_f32_e32 v149, v148
	v_exp_f32_e32 v140, v140
	s_waitcnt vmcnt(8)
	v_lshlrev_b32_e32 v148, 16, v136
	v_and_b32_e32 v136, 0xffff0000, v136
	v_mul_f32_e32 v136, 0xbfb8aa3b, v136
	v_add_f32_e32 v150, 1.0, v149
	v_exp_f32_e32 v149, v136
	v_add_f32_e32 v136, 1.0, v140
	v_rcp_f32_e32 v151, v136
	v_lshlrev_b32_e32 v136, 16, v141
	v_and_b32_e32 v141, 0xffff0000, v141
	v_mul_f32_e32 v136, 0xbfb8aa3b, v136
	v_mul_f32_e32 v141, 0xbfb8aa3b, v141
	v_exp_f32_e32 v140, v136
	v_exp_f32_e32 v141, v141
	v_lshlrev_b32_e32 v136, 16, v137
	v_and_b32_e32 v137, 0xffff0000, v137
	v_mul_f32_e32 v136, 0xbfb8aa3b, v136
	v_mul_f32_e32 v137, 0xbfb8aa3b, v137
	v_exp_f32_e32 v136, v136
	v_add_f32_e32 v140, 1.0, v140
	v_exp_f32_e32 v137, v137
	v_add_f32_e32 v141, 1.0, v141
	v_rcp_f32_e32 v140, v140
	v_rcp_f32_e32 v141, v141
	v_pk_fma_f32 v[136:137], v[210:211], v[136:137], 1.0 op_sel_hi:[0,1,0]
	v_mul_f32_e32 v148, 0xbfb8aa3b, v148
	v_exp_f32_e32 v148, v148
	v_pk_mul_f32 v[136:137], v[140:141], v[136:137]
	v_rcp_f32_e32 v150, v150
	v_pk_mul_f32 v[22:23], v[22:23], v[136:137]
	v_lshlrev_b32_e32 v136, 16, v142
	v_mul_f32_e32 v136, 0xbfb8aa3b, v136
	v_exp_f32_e32 v137, v136
	v_lshlrev_b32_e32 v136, 16, v138
	v_mul_f32_e32 v136, 0xbfb8aa3b, v136
	v_exp_f32_e32 v136, v136
	v_add_f32_e32 v140, 1.0, v137
	v_and_b32_e32 v137, 0xffff0000, v138
	v_and_b32_e32 v138, 0xffff0000, v142
	v_mul_f32_e32 v138, 0xbfb8aa3b, v138
	v_exp_f32_e32 v138, v138
	v_mul_f32_e32 v137, 0xbfb8aa3b, v137
	v_exp_f32_e32 v137, v137
	v_rcp_f32_e32 v140, v140
	v_add_f32_e32 v138, 1.0, v138
	v_rcp_f32_e32 v141, v138
	v_lshlrev_b32_e32 v138, 16, v143
	v_and_b32_e32 v143, 0xffff0000, v143
	v_mul_f32_e32 v138, 0xbfb8aa3b, v138
	v_mul_f32_e32 v143, 0xbfb8aa3b, v143
	v_exp_f32_e32 v142, v138
	v_exp_f32_e32 v143, v143
	v_lshlrev_b32_e32 v138, 16, v139
	v_and_b32_e32 v139, 0xffff0000, v139
	v_mul_f32_e32 v138, 0xbfb8aa3b, v138
	v_mul_f32_e32 v139, 0xbfb8aa3b, v139
	v_exp_f32_e32 v138, v138
	v_add_f32_e32 v142, 1.0, v142
	v_exp_f32_e32 v139, v139
	v_add_f32_e32 v143, 1.0, v143
	v_rcp_f32_e32 v142, v142
	v_rcp_f32_e32 v143, v143
	v_pk_fma_f32 v[136:137], v[210:211], v[136:137], 1.0 op_sel_hi:[0,1,0]
	v_pk_mul_f32 v[136:137], v[140:141], v[136:137]
	v_pk_fma_f32 v[148:149], v[210:211], v[148:149], 1.0 op_sel_hi:[0,1,0]
	v_pk_mul_f32 v[16:17], v[16:17], v[136:137]
	v_pk_fma_f32 v[136:137], v[210:211], v[138:139], 1.0 op_sel_hi:[0,1,0]
	v_pk_mul_f32 v[148:149], v[150:151], v[148:149]
	v_pk_mul_f32 v[136:137], v[142:143], v[136:137]
	v_pk_mul_f32 v[20:21], v[20:21], v[148:149]
	v_pk_mul_f32 v[18:19], v[18:19], v[136:137]
	s_waitcnt vmcnt(7)
	v_lshlrev_b32_e32 v140, 16, v185
	v_mul_f32_e32 v140, 0xbfb8aa3b, v140
	v_lshlrev_b32_e32 v136, 16, v184
	v_exp_f32_e32 v141, v140
	v_mul_f32_e32 v136, 0xbfb8aa3b, v136
	v_exp_f32_e32 v137, v136
	v_and_b32_e32 v139, 0xffff0000, v184
	v_mul_f32_e32 v139, 0xbfb8aa3b, v139
	v_exp_f32_e32 v139, v139
	v_add_f32_e32 v141, 1.0, v141
	v_rcp_f32_e32 v142, v141
	v_and_b32_e32 v141, 0xffff0000, v185
	s_waitcnt vmcnt(5)
; #define MG_LOAD(B, S) do { _Pragma("unroll") for (int mm = 0; mm < 2; ++mm) _Pragma("unroll") for (int bj = 0; bj < 2; ++bj) { \
;             const size_t o = (size_t)(((B) >> 1) * HALF + (((B) & 1) * 2 + mm) * 16) * IN_DIM + bj * HALF; \
;             gn[S][mm][bj] = *(const u32x4*)(zn + o); gd[S][mm][bj] = *(const u32x4*)(zd + o); } } while (0)
;     __device__ __forceinline__ void operator()(f32x4 (&acc)[2][2][4][2], const Unit& u, int wr, int wc, int fr, int fq) const {
;     ...
;         MG_LOAD(0, 0); MG_LOAD(1, 1); __builtin_amdgcn_sched_barrier(0);
;         MG_APPLY(0, 0); __builtin_amdgcn_sched_barrier(0);
;         MG_LOAD(2, 0); __builtin_amdgcn_sched_barrier(0);
;         MG_APPLY(1, 1); __builtin_amdgcn_sched_barrier(0);
;         MG_LOAD(3, 1); __builtin_amdgcn_sched_barrier(0);
;         MG_APPLY(2, 0); __builtin_amdgcn_sched_barrier(0);
;         MG_APPLY(3, 1); __builtin_amdgcn_sched_barrier(0);
	v_lshlrev_b32_e32 v136, 16, v188
	v_add_f32_e32 v138, 1.0, v137
	v_and_b32_e32 v137, 0xffff0000, v188
	v_mul_f32_e32 v141, 0xbfb8aa3b, v141
	v_mul_f32_e32 v136, 0xbfb8aa3b, v136
	v_mul_f32_e32 v137, 0xbfb8aa3b, v137
	v_exp_f32_e32 v143, v141
	v_exp_f32_e32 v136, v136
	v_exp_f32_e32 v137, v137
	v_add_f32_e32 v139, 1.0, v139
	v_lshlrev_b32_e32 v140, 16, v189
	v_and_b32_e32 v141, 0xffff0000, v189
	v_rcp_f32_e32 v138, v138
	v_rcp_f32_e32 v139, v139
	v_mul_f32_e32 v140, 0xbfb8aa3b, v140
	v_mul_f32_e32 v141, 0xbfb8aa3b, v141
	v_exp_f32_e32 v140, v140
	v_exp_f32_e32 v141, v141
	v_add_f32_e32 v143, 1.0, v143
	v_pk_fma_f32 v[136:137], v[210:211], v[136:137], 1.0 op_sel_hi:[0,1,0]
	v_rcp_f32_e32 v143, v143
	v_pk_mul_f32 v[136:137], v[138:139], v[136:137]
	v_and_b32_e32 v139, 0xffff0000, v186
	v_pk_mul_f32 v[44:45], v[44:45], v[136:137]
	v_pk_fma_f32 v[136:137], v[210:211], v[140:141], 1.0 op_sel_hi:[0,1,0]
	v_lshlrev_b32_e32 v140, 16, v187
	v_mul_f32_e32 v140, 0xbfb8aa3b, v140
	v_pk_mul_f32 v[136:137], v[142:143], v[136:137]
	v_exp_f32_e32 v141, v140
	v_pk_mul_f32 v[46:47], v[46:47], v[136:137]
	v_lshlrev_b32_e32 v136, 16, v186
	v_mul_f32_e32 v136, 0xbfb8aa3b, v136
	v_exp_f32_e32 v137, v136
	v_mul_f32_e32 v139, 0xbfb8aa3b, v139
	v_add_f32_e32 v141, 1.0, v141
	v_exp_f32_e32 v139, v139
	v_rcp_f32_e32 v142, v141
	v_and_b32_e32 v141, 0xffff0000, v187
	v_mul_f32_e32 v141, 0xbfb8aa3b, v141
	v_lshlrev_b32_e32 v136, 16, v190
	v_add_f32_e32 v138, 1.0, v137
	v_and_b32_e32 v137, 0xffff0000, v190
	v_exp_f32_e32 v143, v141
	v_mul_f32_e32 v136, 0xbfb8aa3b, v136
	v_mul_f32_e32 v137, 0xbfb8aa3b, v137
	v_exp_f32_e32 v136, v136
	v_exp_f32_e32 v137, v137
	v_add_f32_e32 v139, 1.0, v139
	v_lshlrev_b32_e32 v140, 16, v191
	v_and_b32_e32 v141, 0xffff0000, v191
	v_rcp_f32_e32 v138, v138
	v_rcp_f32_e32 v139, v139
	v_mul_f32_e32 v140, 0xbfb8aa3b, v140
	v_mul_f32_e32 v141, 0xbfb8aa3b, v141
	v_exp_f32_e32 v140, v140
	v_exp_f32_e32 v141, v141
	v_add_f32_e32 v143, 1.0, v143
	v_rcp_f32_e32 v143, v143
	v_pk_fma_f32 v[136:137], v[210:211], v[136:137], 1.0 op_sel_hi:[0,1,0]
	v_pk_mul_f32 v[136:137], v[138:139], v[136:137]
	v_and_b32_e32 v139, 0xffff0000, v172
	v_pk_mul_f32 v[40:41], v[40:41], v[136:137]
	v_pk_fma_f32 v[136:137], v[210:211], v[140:141], 1.0 op_sel_hi:[0,1,0]
	v_lshlrev_b32_e32 v140, 16, v173
	v_pk_mul_f32 v[136:137], v[142:143], v[136:137]
	v_mul_f32_e32 v140, 0xbfb8aa3b, v140
	v_pk_mul_f32 v[42:43], v[42:43], v[136:137]
	v_lshlrev_b32_e32 v136, 16, v172
	v_exp_f32_e32 v141, v140
	v_mul_f32_e32 v136, 0xbfb8aa3b, v136
	v_exp_f32_e32 v137, v136
	v_mul_f32_e32 v139, 0xbfb8aa3b, v139
	v_exp_f32_e32 v139, v139
	v_add_f32_e32 v141, 1.0, v141
	v_rcp_f32_e32 v142, v141
	v_and_b32_e32 v141, 0xffff0000, v173
	s_waitcnt vmcnt(4)
	v_lshlrev_b32_e32 v136, 16, v168
	v_add_f32_e32 v138, 1.0, v137
	v_and_b32_e32 v137, 0xffff0000, v168
	v_mul_f32_e32 v141, 0xbfb8aa3b, v141
	v_mul_f32_e32 v136, 0xbfb8aa3b, v136
	v_mul_f32_e32 v137, 0xbfb8aa3b, v137
	v_exp_f32_e32 v143, v141
	v_exp_f32_e32 v136, v136
	v_exp_f32_e32 v137, v137
	v_add_f32_e32 v139, 1.0, v139
	v_lshlrev_b32_e32 v140, 16, v169
	v_and_b32_e32 v141, 0xffff0000, v169
	v_rcp_f32_e32 v138, v138
	v_rcp_f32_e32 v139, v139
	v_mul_f32_e32 v140, 0xbfb8aa3b, v140
	v_mul_f32_e32 v141, 0xbfb8aa3b, v141
	v_exp_f32_e32 v140, v140
	v_exp_f32_e32 v141, v141
	v_add_f32_e32 v143, 1.0, v143
	v_pk_fma_f32 v[136:137], v[210:211], v[136:137], 1.0 op_sel_hi:[0,1,0]
	v_rcp_f32_e32 v143, v143
	v_pk_mul_f32 v[136:137], v[138:139], v[136:137]
	v_and_b32_e32 v139, 0xffff0000, v174
	v_pk_mul_f32 v[12:13], v[12:13], v[136:137]
	v_pk_fma_f32 v[136:137], v[210:211], v[140:141], 1.0 op_sel_hi:[0,1,0]
	v_lshlrev_b32_e32 v140, 16, v175
	v_mul_f32_e32 v140, 0xbfb8aa3b, v140
	v_pk_mul_f32 v[136:137], v[142:143], v[136:137]
	v_exp_f32_e32 v141, v140
	v_pk_mul_f32 v[14:15], v[14:15], v[136:137]
	v_lshlrev_b32_e32 v136, 16, v174
	v_mul_f32_e32 v136, 0xbfb8aa3b, v136
	v_exp_f32_e32 v137, v136
	v_mul_f32_e32 v139, 0xbfb8aa3b, v139
	v_add_f32_e32 v141, 1.0, v141
	v_exp_f32_e32 v139, v139
	v_rcp_f32_e32 v142, v141
	v_and_b32_e32 v141, 0xffff0000, v175
	v_mul_f32_e32 v141, 0xbfb8aa3b, v141
	v_lshlrev_b32_e32 v136, 16, v170
	v_add_f32_e32 v138, 1.0, v137
	v_and_b32_e32 v137, 0xffff0000, v170
	v_exp_f32_e32 v143, v141
	v_mul_f32_e32 v136, 0xbfb8aa3b, v136
	v_mul_f32_e32 v137, 0xbfb8aa3b, v137
	v_exp_f32_e32 v136, v136
	v_exp_f32_e32 v137, v137
	v_add_f32_e32 v139, 1.0, v139
	v_lshlrev_b32_e32 v140, 16, v171
	v_and_b32_e32 v141, 0xffff0000, v171
	v_rcp_f32_e32 v138, v138
	v_rcp_f32_e32 v139, v139
	v_mul_f32_e32 v140, 0xbfb8aa3b, v140
	v_mul_f32_e32 v141, 0xbfb8aa3b, v141
	v_exp_f32_e32 v140, v140
	v_exp_f32_e32 v141, v141
	v_add_f32_e32 v143, 1.0, v143
	v_rcp_f32_e32 v143, v143
	v_pk_fma_f32 v[136:137], v[210:211], v[136:137], 1.0 op_sel_hi:[0,1,0]
	v_pk_mul_f32 v[136:137], v[138:139], v[136:137]
	s_waitcnt vmcnt(3)
	v_and_b32_e32 v139, 0xffff0000, v144
	v_pk_mul_f32 v[8:9], v[8:9], v[136:137]
	v_pk_fma_f32 v[136:137], v[210:211], v[140:141], 1.0 op_sel_hi:[0,1,0]
	v_lshlrev_b32_e32 v140, 16, v145
	v_pk_mul_f32 v[136:137], v[142:143], v[136:137]
	v_mul_f32_e32 v140, 0xbfb8aa3b, v140
	v_pk_mul_f32 v[10:11], v[10:11], v[136:137]
	v_lshlrev_b32_e32 v136, 16, v144
	v_exp_f32_e32 v141, v140
	v_mul_f32_e32 v136, 0xbfb8aa3b, v136
	v_exp_f32_e32 v137, v136
	v_mul_f32_e32 v139, 0xbfb8aa3b, v139
	v_exp_f32_e32 v139, v139
	v_add_f32_e32 v141, 1.0, v141
	v_rcp_f32_e32 v142, v141
	v_and_b32_e32 v141, 0xffff0000, v145
	s_waitcnt vmcnt(1)
; #define MG_LOAD(B, S) do { _Pragma("unroll") for (int mm = 0; mm < 2; ++mm) _Pragma("unroll") for (int bj = 0; bj < 2; ++bj) { \
;             const size_t o = (size_t)(((B) >> 1) * HALF + (((B) & 1) * 2 + mm) * 16) * IN_DIM + bj * HALF; \
;             gn[S][mm][bj] = *(const u32x4*)(zn + o); gd[S][mm][bj] = *(const u32x4*)(zd + o); } } while (0)
;     __device__ __forceinline__ void operator()(f32x4 (&acc)[2][2][4][2], const Unit& u, int wr, int wc, int fr, int fq) const {
;     ...
;         MG_LOAD(0, 0); MG_LOAD(1, 1); __builtin_amdgcn_sched_barrier(0);
;         MG_APPLY(0, 0); __builtin_amdgcn_sched_barrier(0);
;         MG_LOAD(2, 0); __builtin_amdgcn_sched_barrier(0);
;         MG_APPLY(1, 1); __builtin_amdgcn_sched_barrier(0);
;         MG_LOAD(3, 1); __builtin_amdgcn_sched_barrier(0);
;         MG_APPLY(2, 0); __builtin_amdgcn_sched_barrier(0);
;         MG_APPLY(3, 1); __builtin_amdgcn_sched_barrier(0);
;     ...
;         if (indep) {
;             float* pb = PARTM + ((size_t)u.seg * TC + (size_t)(row0 - TL)) * DM + col0;
; #pragma unroll
;             for (int ai = 0; ai < 2; ++ai)
; #pragma unroll
;                 for (int m = 0; m < 4; ++m)
; #pragma unroll
;                     for (int bj = 0; bj < 2; ++bj) { float* q = pb + (size_t)(ai * HALF + m * 16) * DM + bj * HALF; *(f32x4*)q = acc[ai][bj][m][0]; *(f32x4*)(q + 4) = acc[ai][bj][m][1]; }
;         } else if (u.seg == 3) {
	v_lshlrev_b32_e32 v136, 16, v152
	v_add_f32_e32 v138, 1.0, v137
	v_and_b32_e32 v137, 0xffff0000, v152
	v_mul_f32_e32 v141, 0xbfb8aa3b, v141
	v_mul_f32_e32 v136, 0xbfb8aa3b, v136
	v_mul_f32_e32 v137, 0xbfb8aa3b, v137
	v_exp_f32_e32 v143, v141
	v_exp_f32_e32 v136, v136
	v_exp_f32_e32 v137, v137
	v_add_f32_e32 v139, 1.0, v139
	v_lshlrev_b32_e32 v140, 16, v153
	v_and_b32_e32 v141, 0xffff0000, v153
	v_rcp_f32_e32 v138, v138
	v_rcp_f32_e32 v139, v139
	v_mul_f32_e32 v140, 0xbfb8aa3b, v140
	v_mul_f32_e32 v141, 0xbfb8aa3b, v141
	v_exp_f32_e32 v140, v140
	v_exp_f32_e32 v141, v141
	v_add_f32_e32 v143, 1.0, v143
	v_pk_fma_f32 v[136:137], v[210:211], v[136:137], 1.0 op_sel_hi:[0,1,0]
	v_rcp_f32_e32 v143, v143
	v_pk_mul_f32 v[136:137], v[138:139], v[136:137]
	v_and_b32_e32 v139, 0xffff0000, v146
	v_pk_mul_f32 v[36:37], v[36:37], v[136:137]
	v_pk_fma_f32 v[136:137], v[210:211], v[140:141], 1.0 op_sel_hi:[0,1,0]
	v_lshlrev_b32_e32 v140, 16, v147
	v_mul_f32_e32 v140, 0xbfb8aa3b, v140
	v_pk_mul_f32 v[136:137], v[142:143], v[136:137]
	v_exp_f32_e32 v141, v140
	v_pk_mul_f32 v[38:39], v[38:39], v[136:137]
	v_lshlrev_b32_e32 v136, 16, v146
	v_mul_f32_e32 v136, 0xbfb8aa3b, v136
	v_exp_f32_e32 v137, v136
	v_mul_f32_e32 v139, 0xbfb8aa3b, v139
	v_add_f32_e32 v141, 1.0, v141
	v_exp_f32_e32 v139, v139
	v_rcp_f32_e32 v142, v141
	v_and_b32_e32 v141, 0xffff0000, v147
	v_mul_f32_e32 v141, 0xbfb8aa3b, v141
	v_lshlrev_b32_e32 v136, 16, v154
	v_add_f32_e32 v138, 1.0, v137
	v_and_b32_e32 v137, 0xffff0000, v154
	v_exp_f32_e32 v143, v141
	v_mul_f32_e32 v136, 0xbfb8aa3b, v136
	v_mul_f32_e32 v137, 0xbfb8aa3b, v137
	v_exp_f32_e32 v136, v136
	v_exp_f32_e32 v137, v137
	v_add_f32_e32 v139, 1.0, v139
	v_lshlrev_b32_e32 v140, 16, v155
	v_and_b32_e32 v141, 0xffff0000, v155
	v_rcp_f32_e32 v138, v138
	v_rcp_f32_e32 v139, v139
	v_mul_f32_e32 v140, 0xbfb8aa3b, v140
	v_mul_f32_e32 v141, 0xbfb8aa3b, v141
	v_exp_f32_e32 v140, v140
	v_exp_f32_e32 v141, v141
	v_add_f32_e32 v143, 1.0, v143
	v_rcp_f32_e32 v143, v143
	v_pk_fma_f32 v[136:137], v[210:211], v[136:137], 1.0 op_sel_hi:[0,1,0]
	v_pk_mul_f32 v[136:137], v[138:139], v[136:137]
	s_nop 0
	v_pk_mul_f32 v[32:33], v[32:33], v[136:137]
	v_pk_fma_f32 v[136:137], v[210:211], v[140:141], 1.0 op_sel_hi:[0,1,0]
	v_pk_mul_f32 v[136:137], v[142:143], v[136:137]
	s_nop 0
	v_pk_mul_f32 v[34:35], v[34:35], v[136:137]
	v_lshlrev_b32_e32 v136, 16, v132
	v_and_b32_e32 v132, 0xffff0000, v132
	v_mul_f32_e32 v136, 0xbfb8aa3b, v136
	v_mul_f32_e32 v132, 0xbfb8aa3b, v132
	v_exp_f32_e32 v137, v136
	v_exp_f32_e32 v132, v132
	s_waitcnt vmcnt(0)
	v_lshlrev_b32_e32 v136, 16, v128
	v_and_b32_e32 v128, 0xffff0000, v128
	v_mul_f32_e32 v128, 0xbfb8aa3b, v128
	v_add_f32_e32 v138, 1.0, v137
	v_exp_f32_e32 v137, v128
	v_add_f32_e32 v128, 1.0, v132
	v_rcp_f32_e32 v139, v128
	v_lshlrev_b32_e32 v128, 16, v133
	v_and_b32_e32 v133, 0xffff0000, v133
	v_mul_f32_e32 v128, 0xbfb8aa3b, v128
	v_mul_f32_e32 v133, 0xbfb8aa3b, v133
	v_exp_f32_e32 v132, v128
	v_exp_f32_e32 v133, v133
	v_lshlrev_b32_e32 v128, 16, v129
	v_and_b32_e32 v129, 0xffff0000, v129
	v_mul_f32_e32 v128, 0xbfb8aa3b, v128
	v_mul_f32_e32 v129, 0xbfb8aa3b, v129
	v_exp_f32_e32 v128, v128
	v_add_f32_e32 v132, 1.0, v132
	v_exp_f32_e32 v129, v129
	v_add_f32_e32 v133, 1.0, v133
	v_rcp_f32_e32 v132, v132
	v_rcp_f32_e32 v133, v133
	v_pk_fma_f32 v[128:129], v[210:211], v[128:129], 1.0 op_sel_hi:[0,1,0]
	v_mul_f32_e32 v136, 0xbfb8aa3b, v136
	v_exp_f32_e32 v136, v136
	v_pk_mul_f32 v[128:129], v[132:133], v[128:129]
	v_rcp_f32_e32 v138, v138
	v_pk_mul_f32 v[6:7], v[6:7], v[128:129]
	v_lshlrev_b32_e32 v128, 16, v134
	v_mul_f32_e32 v128, 0xbfb8aa3b, v128
	v_exp_f32_e32 v129, v128
	v_lshlrev_b32_e32 v128, 16, v130
	v_mul_f32_e32 v128, 0xbfb8aa3b, v128
	v_exp_f32_e32 v128, v128
	v_add_f32_e32 v132, 1.0, v129
	v_and_b32_e32 v129, 0xffff0000, v130
	v_and_b32_e32 v130, 0xffff0000, v134
	v_mul_f32_e32 v130, 0xbfb8aa3b, v130
	v_exp_f32_e32 v130, v130
	v_mul_f32_e32 v129, 0xbfb8aa3b, v129
	v_exp_f32_e32 v129, v129
	v_rcp_f32_e32 v132, v132
	v_add_f32_e32 v130, 1.0, v130
	v_rcp_f32_e32 v133, v130
	v_lshlrev_b32_e32 v130, 16, v135
	v_and_b32_e32 v135, 0xffff0000, v135
	v_mul_f32_e32 v130, 0xbfb8aa3b, v130
	v_mul_f32_e32 v135, 0xbfb8aa3b, v135
	v_exp_f32_e32 v134, v130
	v_exp_f32_e32 v135, v135
	v_lshlrev_b32_e32 v130, 16, v131
	v_and_b32_e32 v131, 0xffff0000, v131
	v_mul_f32_e32 v130, 0xbfb8aa3b, v130
	v_mul_f32_e32 v131, 0xbfb8aa3b, v131
	v_exp_f32_e32 v130, v130
	v_add_f32_e32 v134, 1.0, v134
	v_exp_f32_e32 v131, v131
	v_add_f32_e32 v135, 1.0, v135
	v_rcp_f32_e32 v134, v134
	v_rcp_f32_e32 v135, v135
	v_pk_fma_f32 v[128:129], v[210:211], v[128:129], 1.0 op_sel_hi:[0,1,0]
	v_pk_mul_f32 v[128:129], v[132:133], v[128:129]
	v_pk_fma_f32 v[136:137], v[210:211], v[136:137], 1.0 op_sel_hi:[0,1,0]
	v_pk_mul_f32 v[0:1], v[0:1], v[128:129]
	v_pk_fma_f32 v[128:129], v[210:211], v[130:131], 1.0 op_sel_hi:[0,1,0]
	v_pk_mul_f32 v[136:137], v[138:139], v[136:137]
	v_pk_mul_f32 v[128:129], v[134:135], v[128:129]
	v_pk_mul_f32 v[4:5], v[4:5], v[136:137]
	v_pk_mul_f32 v[2:3], v[2:3], v[128:129]
	s_cbranch_scc1 .LBB0_1618
; __device__ __forceinline__ unsigned cvt_pk_bf16(float lo, float hi) { unsigned r; asm volatile("v_cvt_pk_bf16_f32 %0, %1, %2" : "=v"(r) : "v"(lo), "v"(hi)); return r; }
;     __device__ __forceinline__ void operator()(f32x4 (&acc)[2][2][4][2], const Unit& u, int wr, int wc, int fr, int fq) const {
;     ...
;         } else if (u.seg == 3) {
;             bf16_t* ob = O + (size_t)row0 * DM + col0;
; #pragma unroll
;             for (int ai = 0; ai < 2; ++ai)
; #pragma unroll
;                 for (int m = 0; m < 4; ++m)
; #pragma unroll
;                     for (int bj = 0; bj < 2; ++bj) { const f32x4 v0 = acc[ai][bj][m][0], v1 = acc[ai][bj][m][1];
;                         u32x4 w; w.x = cvt_pk_bf16(v0[0], v0[1]); w.y = cvt_pk_bf16(v0[2], v0[3]); w.z = cvt_pk_bf16(v1[0], v1[1]); w.w = cvt_pk_bf16(v1[2], v1[3]);
;                         *(u32x4*)(ob + (size_t)(ai * HALF + m * 16) * DM + bj * HALF) = w; }
	v_ashrrev_i32_e32 v209, 31, v208
	v_lshlrev_b64 v[128:129], 12, v[208:209]
	v_lshl_add_u64 v[128:129], s[10:11], 0, v[128:129]
	v_lshl_add_u64 v[128:129], v[206:207], 1, v[128:129]
	v_cvt_pk_bf16_f32 v130, v124, v125
	v_cvt_pk_bf16_f32 v131, v126, v127
	v_cvt_pk_bf16_f32 v132, v120, v121
	v_cvt_pk_bf16_f32 v133, v122, v123
	global_store_dwordx4 v[128:129], v[130:133], off
	v_add_co_u32_e32 v134, vcc, s51, v128
	s_nop 0
	v_cvt_pk_bf16_f32 v130, v92, v93
	v_cvt_pk_bf16_f32 v131, v94, v95
	v_cvt_pk_bf16_f32 v132, v88, v89
	v_cvt_pk_bf16_f32 v133, v90, v91
	global_store_dwordx4 v[128:129], v[130:133], off offset:256
	v_addc_co_u32_e32 v135, vcc, 0, v129, vcc
	s_nop 0
	v_cvt_pk_bf16_f32 v130, v116, v117
	v_cvt_pk_bf16_f32 v131, v118, v119
	v_cvt_pk_bf16_f32 v132, v112, v113
	v_cvt_pk_bf16_f32 v133, v114, v115
	global_store_dwordx4 v[134:135], v[130:133], off
	s_nop 1
	v_cvt_pk_bf16_f32 v130, v84, v85
	v_cvt_pk_bf16_f32 v131, v86, v87
	v_cvt_pk_bf16_f32 v132, v80, v81
	v_cvt_pk_bf16_f32 v133, v82, v83
	global_store_dwordx4 v[134:135], v[130:133], off offset:256
	v_add_co_u32_e32 v134, vcc, s64, v128
	s_nop 0
	v_cvt_pk_bf16_f32 v130, v108, v109
	v_cvt_pk_bf16_f32 v131, v110, v111
	v_cvt_pk_bf16_f32 v132, v104, v105
	v_cvt_pk_bf16_f32 v133, v106, v107
	s_nop 0
	v_addc_co_u32_e32 v135, vcc, 0, v129, vcc
	global_store_dwordx4 v[134:135], v[130:133], off
	s_nop 1
	v_cvt_pk_bf16_f32 v130, v76, v77
	v_cvt_pk_bf16_f32 v131, v78, v79
	v_cvt_pk_bf16_f32 v132, v72, v73
	v_cvt_pk_bf16_f32 v133, v74, v75
	global_store_dwordx4 v[134:135], v[130:133], off offset:256
	v_add_co_u32_e32 v134, vcc, s65, v128
	s_nop 0
	v_cvt_pk_bf16_f32 v130, v100, v101
	v_cvt_pk_bf16_f32 v131, v102, v103
	v_cvt_pk_bf16_f32 v132, v96, v97
	v_cvt_pk_bf16_f32 v133, v98, v99
	s_nop 0
	v_addc_co_u32_e32 v135, vcc, 0, v129, vcc
	global_store_dwordx4 v[134:135], v[130:133], off
	s_nop 1
	v_cvt_pk_bf16_f32 v130, v68, v69
	v_cvt_pk_bf16_f32 v131, v70, v71
	v_cvt_pk_bf16_f32 v132, v64, v65
	v_cvt_pk_bf16_f32 v133, v66, v67
	global_store_dwordx4 v[134:135], v[130:133], off offset:256
	v_add_co_u32_e32 v134, vcc, s66, v128
	s_nop 0
	v_cvt_pk_bf16_f32 v130, v60, v61
	v_cvt_pk_bf16_f32 v131, v62, v63
	v_cvt_pk_bf16_f32 v132, v56, v57
	v_cvt_pk_bf16_f32 v133, v58, v59
	s_nop 0
	v_addc_co_u32_e32 v135, vcc, 0, v129, vcc
	global_store_dwordx4 v[134:135], v[130:133], off
	s_nop 1
	v_cvt_pk_bf16_f32 v130, v28, v29
	v_cvt_pk_bf16_f32 v131, v30, v31
	v_cvt_pk_bf16_f32 v132, v24, v25
	v_cvt_pk_bf16_f32 v133, v26, v27
	global_store_dwordx4 v[134:135], v[130:133], off offset:256
	v_add_co_u32_e32 v134, vcc, s67, v128
	s_nop 0
	v_cvt_pk_bf16_f32 v130, v52, v53
	v_cvt_pk_bf16_f32 v131, v54, v55
	v_cvt_pk_bf16_f32 v132, v48, v49
	v_cvt_pk_bf16_f32 v133, v50, v51
	s_nop 0
	v_addc_co_u32_e32 v135, vcc, 0, v129, vcc
	global_store_dwordx4 v[134:135], v[130:133], off
	s_nop 1
	v_cvt_pk_bf16_f32 v130, v20, v21
	v_cvt_pk_bf16_f32 v131, v22, v23
	v_cvt_pk_bf16_f32 v132, v16, v17
	v_cvt_pk_bf16_f32 v133, v18, v19
	global_store_dwordx4 v[134:135], v[130:133], off offset:256
	v_add_co_u32_e32 v134, vcc, s68, v128
	s_nop 0
	v_cvt_pk_bf16_f32 v130, v44, v45
	v_cvt_pk_bf16_f32 v131, v46, v47
	v_cvt_pk_bf16_f32 v132, v40, v41
	v_cvt_pk_bf16_f32 v133, v42, v43
	s_nop 0
	v_addc_co_u32_e32 v135, vcc, 0, v129, vcc
	global_store_dwordx4 v[134:135], v[130:133], off
	s_nop 1
	v_cvt_pk_bf16_f32 v130, v12, v13
	v_cvt_pk_bf16_f32 v131, v14, v15
	v_cvt_pk_bf16_f32 v132, v8, v9
	v_cvt_pk_bf16_f32 v133, v10, v11
	global_store_dwordx4 v[134:135], v[130:133], off offset:256
	v_add_co_u32_e32 v134, vcc, s69, v128
	s_nop 0
	v_cvt_pk_bf16_f32 v130, v36, v37
	v_cvt_pk_bf16_f32 v131, v38, v39
	v_cvt_pk_bf16_f32 v132, v32, v33
	v_cvt_pk_bf16_f32 v133, v34, v35
	s_nop 0
	v_addc_co_u32_e32 v135, vcc, 0, v129, vcc
	global_store_dwordx4 v[134:135], v[130:133], off
	v_cvt_pk_bf16_f32 v128, v4, v5
	v_cvt_pk_bf16_f32 v129, v6, v7
	s_nop 1
	v_cvt_pk_bf16_f32 v130, v0, v1
	v_cvt_pk_bf16_f32 v131, v2, v3
	global_store_dwordx4 v[134:135], v[128:131], off offset:256
